# v45 + defer the work-queue atomic's vmcnt wait to the tile end in P8/P6/P5 (next-item fetch latency overlapped with the tile)
# baseline (speedup 1.0000x reference)
.LBB0_94:
	v_mov_b32_e32 v128, 0
	s_and_saveexec_b64 s[4:5], s[36:37]
	s_cbranch_execz .LBB0_98
	s_mov_b64 s[8:9], exec
	v_mbcnt_lo_u32_b32 v0, s8, 0
	v_mbcnt_hi_u32_b32 v0, s9, v0
	v_cmp_eq_u32_e32 vcc, 0, v0
	s_and_saveexec_b64 s[6:7], vcc
	s_cbranch_execz .LBB0_97
	s_bcnt1_i32_b64 s8, s[8:9]
	v_mov_b32_e32 v1, s8
	global_atomic_add v128, v209, v1, s[0:1] sc0

.LBB0_98:
	s_or_b64 exec, exec, s[4:5]
	s_ashr_i32 s4, s11, 4
	s_ashr_i32 s5, s4, 31
	v_mov_b32_e32 v129, v211
	s_and_b32 s6, s11, 15
	s_lshl_b64 s[8:9], s[4:5], 18
	s_add_u32 s8, s30, s8
	v_ashrrev_i32_e32 v0, 3, v129
	v_ashrrev_i32_e32 v1, 31, v0
	s_addc_u32 s9, s31, s9
	v_lshlrev_b64 v[2:3], 11, v[0:1]
	v_lshlrev_b32_e32 v1, 4, v129
	v_lshl_add_u64 v[4:5], s[8:9], 0, v[2:3]
	v_and_b32_e32 v208, 0x70, v1
	s_lshl_b32 s7, s6, 18
	v_readlane_b32 s11, v252, 9
	v_lshl_add_u64 v[114:115], v[4:5], 0, v[208:209]
	s_mov_b32 s8, 0x10000
	s_add_u32 s12, s11, s7
	v_readlane_b32 s7, v252, 10
	v_add_co_u32_e32 v116, vcc, s8, v114
	s_addc_u32 s13, s7, 0
	s_nop 0
	v_addc_co_u32_e32 v117, vcc, 0, v115, vcc
	s_mov_b32 s7, 0x20000
	v_add_co_u32_e32 v118, vcc, s7, v114
	s_mov_b32 s9, 0x30000
	s_nop 0
	v_addc_co_u32_e32 v119, vcc, 0, v115, vcc
	v_add_co_u32_e32 v124, vcc, s9, v114
	v_lshl_add_u64 v[2:3], s[12:13], 0, v[2:3]
	s_nop 0
	v_addc_co_u32_e32 v125, vcc, 0, v115, vcc
	v_lshl_add_u64 v[112:113], v[2:3], 0, v[208:209]
	global_load_dwordx4 v[96:99], v[114:115], off
	global_load_dwordx4 v[100:103], v[116:117], off
	global_load_dwordx4 v[104:107], v[118:119], off
	global_load_dwordx4 v[108:111], v[124:125], off
	global_load_dwordx4 v[132:135], v[112:113], off
	v_add_co_u32_e32 v120, vcc, s8, v112
	v_mul_u32_u24_e32 v0, 0xa0, v0
	s_nop 0
	v_addc_co_u32_e32 v121, vcc, 0, v113, vcc
	v_add_co_u32_e32 v122, vcc, s7, v112
	global_load_dwordx4 v[136:139], v[120:121], off
	s_nop 0
	v_addc_co_u32_e32 v123, vcc, 0, v113, vcc
	v_add_co_u32_e32 v126, vcc, s9, v112
	global_load_dwordx4 v[140:143], v[122:123], off
	s_nop 0
	v_addc_co_u32_e32 v127, vcc, 0, v113, vcc
	global_load_dwordx4 v[144:147], v[126:127], off
	global_load_dwordx4 v[32:35], v[114:115], off offset:128
	global_load_dwordx4 v[36:39], v[114:115], off offset:256
	global_load_dwordx4 v[40:43], v[116:117], off offset:128
	global_load_dwordx4 v[44:47], v[118:119], off offset:128
	global_load_dwordx4 v[48:51], v[124:125], off offset:128
	global_load_dwordx4 v[64:67], v[112:113], off offset:128
	global_load_dwordx4 v[52:55], v[116:117], off offset:256
	global_load_dwordx4 v[56:59], v[118:119], off offset:256
	global_load_dwordx4 v[60:63], v[124:125], off offset:256
	global_load_dwordx4 v[68:71], v[112:113], off offset:256
	global_load_dwordx4 v[76:79], v[120:121], off offset:128
	global_load_dwordx4 v[80:83], v[122:123], off offset:128
	global_load_dwordx4 v[84:87], v[126:127], off offset:128
	global_load_dwordx4 v[72:75], v[120:121], off offset:256
	global_load_dwordx4 v[88:91], v[122:123], off offset:256
	global_load_dwordx4 v[92:95], v[126:127], off offset:256
	v_add3_u32 v130, 0, v0, v208
	s_barrier
	global_load_dwordx4 v[0:3], v[126:127], off offset:384
	global_load_dwordx4 v[4:7], v[122:123], off offset:384
	global_load_dwordx4 v[8:11], v[120:121], off offset:384
	global_load_dwordx4 v[12:15], v[112:113], off offset:384
	global_load_dwordx4 v[16:19], v[124:125], off offset:384
	global_load_dwordx4 v[20:23], v[118:119], off offset:384
	global_load_dwordx4 v[24:27], v[116:117], off offset:384
	global_load_dwordx4 v[28:31], v[114:115], off offset:384
	s_lshl_b64 s[4:5], s[4:5], 19
	s_add_u32 s4, s20, s4
	s_addc_u32 s5, s21, s5
	s_lshl_b32 s6, s6, 8
	s_add_u32 s4, s4, s6
	s_addc_u32 s5, s5, 0
	s_waitcnt vmcnt(31)
	ds_write_b128 v130, v[96:99]
	s_waitcnt vmcnt(30)
	ds_write_b128 v130, v[100:103] offset:5120
	s_waitcnt vmcnt(29)
	ds_write_b128 v130, v[104:107] offset:10240
	s_waitcnt vmcnt(28)
	ds_write_b128 v130, v[108:111] offset:15360
	s_waitcnt vmcnt(27)
	ds_write_b128 v130, v[132:135] offset:20480
	s_waitcnt vmcnt(26)
	ds_write_b128 v130, v[136:139] offset:25600
	s_waitcnt vmcnt(25)
	ds_write_b128 v130, v[140:143] offset:30720
	s_waitcnt vmcnt(24)
	ds_write_b128 v130, v[144:147] offset:35840
	v_and_b32_e32 v96, 15, v129
	v_lshrrev_b32_e32 v97, 1, v129
	v_and_or_b32 v96, v97, s43, v96
	v_mul_u32_u24_e32 v96, 0xa0, v96
	v_and_b32_e32 v100, 48, v129
	v_add3_u32 v131, 0, v96, v100
	s_waitcnt lgkmcnt(0)
	s_barrier
	v_and_b32_e32 v101, 0x4f, v129
	ds_read_b128 v[96:99], v131
	ds_read_b128 v[184:187], v131 offset:64
	ds_read_b128 v[148:151], v131 offset:2560
	ds_read_b128 v[164:167], v131 offset:5120
	ds_read_b128 v[180:183], v131 offset:7680
	v_mul_u32_u24_e32 v101, 0x50, v101
	v_lshlrev_b32_e32 v101, 1, v101
	v_add3_u32 v129, 0, v101, v100
	v_add_u32_e32 v129, 0x5000, v129
	ds_read_b128 v[100:103], v129
	ds_read_b128 v[108:111], v129 offset:2560
	ds_read_b128 v[136:139], v129 offset:5120
	ds_read_b128 v[196:199], v129 offset:5184
	ds_read_b128 v[144:147], v129 offset:7680
	ds_read_b128 v[200:203], v129 offset:7744
	s_waitcnt lgkmcnt(5)
	v_mfma_f32_16x16x32_bf16 v[104:107], v[96:99], v[100:103], 0
	ds_read_b128 v[188:191], v129 offset:2624
	s_waitcnt lgkmcnt(5)
	v_mfma_f32_16x16x32_bf16 v[132:135], v[96:99], v[108:111], 0
	s_waitcnt lgkmcnt(4)
	v_mfma_f32_16x16x32_bf16 v[140:143], v[96:99], v[136:139], 0
	s_waitcnt lgkmcnt(2)
	v_mfma_f32_16x16x32_bf16 v[96:99], v[96:99], v[144:147], 0
	v_mfma_f32_16x16x32_bf16 v[152:155], v[148:151], v[100:103], 0
	v_mfma_f32_16x16x32_bf16 v[156:159], v[148:151], v[108:111], 0
	v_mfma_f32_16x16x32_bf16 v[160:163], v[148:151], v[136:139], 0
	v_mfma_f32_16x16x32_bf16 v[148:151], v[148:151], v[144:147], 0
	v_mfma_f32_16x16x32_bf16 v[168:171], v[164:167], v[100:103], 0
	v_mfma_f32_16x16x32_bf16 v[172:175], v[164:167], v[108:111], 0
	v_mfma_f32_16x16x32_bf16 v[176:179], v[164:167], v[136:139], 0
	v_mfma_f32_16x16x32_bf16 v[164:167], v[164:167], v[144:147], 0
	v_mfma_f32_16x16x32_bf16 v[100:103], v[180:183], v[100:103], 0
	v_mfma_f32_16x16x32_bf16 v[108:111], v[180:183], v[108:111], 0
	v_mfma_f32_16x16x32_bf16 v[136:139], v[180:183], v[136:139], 0
	v_mfma_f32_16x16x32_bf16 v[144:147], v[180:183], v[144:147], 0
	ds_read_b128 v[180:183], v129 offset:64
	s_waitcnt lgkmcnt(1)
	v_mfma_f32_16x16x32_bf16 v[192:195], v[184:187], v[188:191], v[132:135]
	s_nop 2
	ds_read_b128 v[132:135], v131 offset:2624
	s_waitcnt lgkmcnt(1)
	v_mfma_f32_16x16x32_bf16 v[104:107], v[184:187], v[180:183], v[104:107]
	v_mfma_f32_16x16x32_bf16 v[140:143], v[184:187], v[196:199], v[140:143]
	v_mfma_f32_16x16x32_bf16 v[96:99], v[184:187], v[200:203], v[96:99]
	ds_read_b128 v[184:187], v131 offset:7744
	s_waitcnt lgkmcnt(1)
	v_mfma_f32_16x16x32_bf16 v[152:155], v[132:135], v[180:183], v[152:155]
	v_mfma_f32_16x16x32_bf16 v[156:159], v[132:135], v[188:191], v[156:159]
	v_mfma_f32_16x16x32_bf16 v[160:163], v[132:135], v[196:199], v[160:163]
	v_mfma_f32_16x16x32_bf16 v[148:151], v[132:135], v[200:203], v[148:151]
	ds_read_b128 v[132:135], v131 offset:5184
	s_waitcnt lgkmcnt(0)
	v_mfma_f32_16x16x32_bf16 v[168:171], v[132:135], v[180:183], v[168:171]
	v_mfma_f32_16x16x32_bf16 v[172:175], v[132:135], v[188:191], v[172:175]
	v_mfma_f32_16x16x32_bf16 v[176:179], v[132:135], v[196:199], v[176:179]
	v_mfma_f32_16x16x32_bf16 v[164:167], v[132:135], v[200:203], v[164:167]
	v_add_u32_e32 v132, 0xf000, v130
	s_waitcnt vmcnt(23)
	ds_write_b128 v130, v[32:35] offset:40960
	s_waitcnt vmcnt(21)
	ds_write_b128 v130, v[40:43] offset:46080
	s_waitcnt vmcnt(20)
	ds_write_b128 v130, v[44:47] offset:51200
	s_waitcnt vmcnt(19)
	ds_write_b128 v130, v[48:51] offset:56320
	s_waitcnt vmcnt(18)
	ds_write_b128 v130, v[64:67] offset:61440
	s_waitcnt vmcnt(13)
	ds_write_b128 v132, v[76:79] offset:5120
	s_waitcnt vmcnt(12)
	ds_write_b128 v132, v[80:83] offset:10240
	s_waitcnt vmcnt(11)
	ds_write_b128 v132, v[84:87] offset:15360
	global_load_dwordx4 v[32:35], v[114:115], off offset:512
	global_load_dwordx4 v[40:43], v[116:117], off offset:512
	global_load_dwordx4 v[44:47], v[118:119], off offset:512
	global_load_dwordx4 v[48:51], v[124:125], off offset:512
	global_load_dwordx4 v[64:67], v[112:113], off offset:512
	global_load_dwordx4 v[76:79], v[120:121], off offset:512
	global_load_dwordx4 v[80:83], v[122:123], off offset:512
	global_load_dwordx4 v[84:87], v[126:127], off offset:512
	v_mfma_f32_16x16x32_bf16 v[100:103], v[184:187], v[180:183], v[100:103]
	s_waitcnt lgkmcnt(0)
	s_barrier
	ds_read_b128 v[180:183], v131 offset:40960
	ds_read_b128 v[204:207], v131 offset:48704
	v_mfma_f32_16x16x32_bf16 v[108:111], v[184:187], v[188:191], v[108:111]
	ds_read_b128 v[188:191], v129 offset:43520
	v_mfma_f32_16x16x32_bf16 v[134:137], v[184:187], v[196:199], v[136:139]
	ds_read_b128 v[196:199], v129 offset:46080
	v_mfma_f32_16x16x32_bf16 v[144:147], v[184:187], v[200:203], v[144:147]
	ds_read_b128 v[184:187], v129 offset:40960
	ds_read_b128 v[200:203], v129 offset:48640
	s_waitcnt lgkmcnt(1)
	v_mfma_f32_16x16x32_bf16 v[104:107], v[180:183], v[184:187], v[104:107]
	v_mfma_f32_16x16x32_bf16 v[192:195], v[180:183], v[188:191], v[192:195]
	v_mfma_f32_16x16x32_bf16 v[138:141], v[180:183], v[196:199], v[140:143]
	s_waitcnt lgkmcnt(0)
	v_mfma_f32_16x16x32_bf16 v[96:99], v[180:183], v[200:203], v[96:99]
	ds_read_b128 v[180:183], v131 offset:43520
	s_waitcnt lgkmcnt(0)
	v_mfma_f32_16x16x32_bf16 v[152:155], v[180:183], v[184:187], v[152:155]
	v_mfma_f32_16x16x32_bf16 v[156:159], v[180:183], v[188:191], v[156:159]
	v_mfma_f32_16x16x32_bf16 v[160:163], v[180:183], v[196:199], v[160:163]
	v_mfma_f32_16x16x32_bf16 v[148:151], v[180:183], v[200:203], v[148:151]
	ds_read_b128 v[180:183], v131 offset:46080
	s_waitcnt lgkmcnt(0)
	v_mfma_f32_16x16x32_bf16 v[168:171], v[180:183], v[184:187], v[168:171]
	v_mfma_f32_16x16x32_bf16 v[172:175], v[180:183], v[188:191], v[172:175]
	v_mfma_f32_16x16x32_bf16 v[176:179], v[180:183], v[196:199], v[176:179]
	v_mfma_f32_16x16x32_bf16 v[164:167], v[180:183], v[200:203], v[164:167]
	ds_read_b128 v[180:183], v131 offset:48640
	s_waitcnt lgkmcnt(0)
	v_mfma_f32_16x16x32_bf16 v[100:103], v[180:183], v[184:187], v[100:103]
	ds_read_b128 v[184:187], v131 offset:41024
	v_mfma_f32_16x16x32_bf16 v[108:111], v[180:183], v[188:191], v[108:111]
	ds_read_b128 v[188:191], v129 offset:43584
	v_mfma_f32_16x16x32_bf16 v[134:137], v[180:183], v[196:199], v[134:137]
	ds_read_b128 v[196:199], v129 offset:46144
	v_mfma_f32_16x16x32_bf16 v[142:145], v[180:183], v[200:203], v[144:147]
	ds_read_b128 v[180:183], v129 offset:41024
	ds_read_b128 v[200:203], v129 offset:48704
	s_waitcnt lgkmcnt(1)
	v_mfma_f32_16x16x32_bf16 v[104:107], v[184:187], v[180:183], v[104:107]
	v_mfma_f32_16x16x32_bf16 v[192:195], v[184:187], v[188:191], v[192:195]
	v_mfma_f32_16x16x32_bf16 v[138:141], v[184:187], v[196:199], v[138:141]
	s_waitcnt lgkmcnt(0)
	v_mfma_f32_16x16x32_bf16 v[184:187], v[184:187], v[200:203], v[96:99]
	s_nop 2
	ds_read_b128 v[96:99], v131 offset:43584
	s_waitcnt lgkmcnt(0)
	v_mfma_f32_16x16x32_bf16 v[152:155], v[96:99], v[180:183], v[152:155]
	v_mfma_f32_16x16x32_bf16 v[156:159], v[96:99], v[188:191], v[156:159]
	v_mfma_f32_16x16x32_bf16 v[160:163], v[96:99], v[196:199], v[160:163]
	v_mfma_f32_16x16x32_bf16 v[146:149], v[96:99], v[200:203], v[148:151]
	ds_read_b128 v[96:99], v131 offset:46144
	ds_write_b128 v130, v[36:39]
	ds_write_b128 v130, v[52:55] offset:5120
	ds_write_b128 v130, v[56:59] offset:10240
	ds_write_b128 v130, v[60:63] offset:15360
	ds_write_b128 v130, v[68:71] offset:20480
	s_waitcnt vmcnt(18)
	ds_write_b128 v130, v[72:75] offset:25600
	s_waitcnt vmcnt(17)
	ds_write_b128 v130, v[88:91] offset:30720
	s_waitcnt vmcnt(16)
	ds_write_b128 v130, v[92:95] offset:35840
	s_waitcnt lgkmcnt(8)
	v_mfma_f32_16x16x32_bf16 v[168:171], v[96:99], v[180:183], v[168:171]
	v_mfma_f32_16x16x32_bf16 v[172:175], v[96:99], v[188:191], v[172:175]
	v_mfma_f32_16x16x32_bf16 v[176:179], v[96:99], v[196:199], v[176:179]
	v_mfma_f32_16x16x32_bf16 v[164:167], v[96:99], v[200:203], v[164:167]
	global_load_dwordx4 v[36:39], v[114:115], off offset:640
	global_load_dwordx4 v[52:55], v[116:117], off offset:640
	global_load_dwordx4 v[56:59], v[118:119], off offset:640
	global_load_dwordx4 v[60:63], v[124:125], off offset:640
	global_load_dwordx4 v[68:71], v[112:113], off offset:640
	global_load_dwordx4 v[88:91], v[120:121], off offset:640
	global_load_dwordx4 v[92:95], v[122:123], off offset:640
	global_load_dwordx4 v[96:99], v[126:127], off offset:640
	s_waitcnt lgkmcnt(0)
	s_barrier
	ds_read_b128 v[72:75], v131
	v_mfma_f32_16x16x32_bf16 v[100:103], v[204:207], v[180:183], v[100:103]
	ds_read_b128 v[180:183], v129
	v_mfma_f32_16x16x32_bf16 v[108:111], v[204:207], v[188:191], v[108:111]
	ds_read_b128 v[188:191], v129 offset:2560
	v_mfma_f32_16x16x32_bf16 v[134:137], v[204:207], v[196:199], v[134:137]
	ds_read_b128 v[196:199], v129 offset:5120
	v_mfma_f32_16x16x32_bf16 v[142:145], v[204:207], v[200:203], v[142:145]
	ds_read_b128 v[200:203], v129 offset:7680
	ds_read_b128 v[204:207], v131 offset:7744
	s_waitcnt lgkmcnt(4)
	v_mfma_f32_16x16x32_bf16 v[104:107], v[72:75], v[180:183], v[104:107]
	s_waitcnt lgkmcnt(3)
	v_mfma_f32_16x16x32_bf16 v[192:195], v[72:75], v[188:191], v[192:195]
	s_waitcnt lgkmcnt(2)
	v_mfma_f32_16x16x32_bf16 v[138:141], v[72:75], v[196:199], v[138:141]
	s_waitcnt lgkmcnt(1)
	v_mfma_f32_16x16x32_bf16 v[72:75], v[72:75], v[200:203], v[184:187]
	s_nop 2
	ds_read_b128 v[184:187], v131 offset:2560
	s_waitcnt lgkmcnt(0)
	v_mfma_f32_16x16x32_bf16 v[150:153], v[184:187], v[180:183], v[152:155]
	v_mfma_f32_16x16x32_bf16 v[154:157], v[184:187], v[188:191], v[156:159]
	v_mfma_f32_16x16x32_bf16 v[158:161], v[184:187], v[196:199], v[160:163]
	v_mfma_f32_16x16x32_bf16 v[146:149], v[184:187], v[200:203], v[146:149]
	ds_read_b128 v[184:187], v131 offset:5120
	s_waitcnt lgkmcnt(0)
	v_mfma_f32_16x16x32_bf16 v[168:171], v[184:187], v[180:183], v[168:171]
	v_mfma_f32_16x16x32_bf16 v[172:175], v[184:187], v[188:191], v[172:175]
	v_mfma_f32_16x16x32_bf16 v[176:179], v[184:187], v[196:199], v[176:179]
	v_mfma_f32_16x16x32_bf16 v[162:165], v[184:187], v[200:203], v[164:167]
	ds_read_b128 v[184:187], v131 offset:7680
	s_waitcnt lgkmcnt(0)
	v_mfma_f32_16x16x32_bf16 v[100:103], v[184:187], v[180:183], v[100:103]
	ds_read_b128 v[180:183], v131 offset:64
	v_mfma_f32_16x16x32_bf16 v[108:111], v[184:187], v[188:191], v[108:111]
	v_mfma_f32_16x16x32_bf16 v[134:137], v[184:187], v[196:199], v[134:137]
	ds_read_b128 v[196:199], v129 offset:5184
	v_mfma_f32_16x16x32_bf16 v[142:145], v[184:187], v[200:203], v[142:145]
	ds_read_b128 v[184:187], v129 offset:64
	ds_read_b128 v[200:203], v129 offset:7744
	s_waitcnt lgkmcnt(1)
	v_mfma_f32_16x16x32_bf16 v[188:191], v[180:183], v[184:187], v[104:107]
	s_nop 2
	ds_read_b128 v[104:107], v129 offset:2624
	s_waitcnt lgkmcnt(0)
	v_mfma_f32_16x16x32_bf16 v[192:195], v[180:183], v[104:107], v[192:195]
	v_mfma_f32_16x16x32_bf16 v[138:141], v[180:183], v[196:199], v[138:141]
	v_mfma_f32_16x16x32_bf16 v[180:183], v[180:183], v[200:203], v[72:75]
	s_nop 2
	ds_read_b128 v[72:75], v131 offset:2624
	s_waitcnt lgkmcnt(0)
	v_mfma_f32_16x16x32_bf16 v[150:153], v[72:75], v[184:187], v[150:153]
	v_mfma_f32_16x16x32_bf16 v[154:157], v[72:75], v[104:107], v[154:157]
	v_mfma_f32_16x16x32_bf16 v[158:161], v[72:75], v[196:199], v[158:161]
	v_mfma_f32_16x16x32_bf16 v[146:149], v[72:75], v[200:203], v[146:149]
	ds_read_b128 v[72:75], v131 offset:5184
	s_waitcnt vmcnt(16)
	ds_write_b128 v130, v[28:31] offset:40960
	ds_write_b128 v130, v[24:27] offset:46080
	ds_write_b128 v130, v[20:23] offset:51200
	ds_write_b128 v130, v[16:19] offset:56320
	ds_write_b128 v130, v[12:15] offset:61440
	ds_write_b128 v132, v[8:11] offset:5120
	ds_write_b128 v132, v[4:7] offset:10240
	ds_write_b128 v132, v[0:3] offset:15360
	s_waitcnt lgkmcnt(8)
	v_mfma_f32_16x16x32_bf16 v[166:169], v[72:75], v[184:187], v[168:171]
	v_mfma_f32_16x16x32_bf16 v[170:173], v[72:75], v[104:107], v[172:175]
	v_mfma_f32_16x16x32_bf16 v[174:177], v[72:75], v[196:199], v[176:179]
	v_mfma_f32_16x16x32_bf16 v[162:165], v[72:75], v[200:203], v[162:165]
	v_mfma_f32_16x16x32_bf16 v[184:187], v[204:207], v[184:187], v[100:103]
	v_mfma_f32_16x16x32_bf16 v[212:215], v[204:207], v[104:107], v[108:111]
	global_load_dwordx4 v[0:3], v[114:115], off offset:768
	global_load_dwordx4 v[12:15], v[116:117], off offset:768
	global_load_dwordx4 v[16:19], v[118:119], off offset:768
	global_load_dwordx4 v[20:23], v[124:125], off offset:768
	global_load_dwordx4 v[72:75], v[112:113], off offset:768
	global_load_dwordx4 v[100:103], v[120:121], off offset:768
	global_load_dwordx4 v[104:107], v[122:123], off offset:768
	global_load_dwordx4 v[108:111], v[126:127], off offset:768
	s_waitcnt lgkmcnt(0)
	s_barrier
	ds_read_b128 v[4:7], v131 offset:40960
	v_mfma_f32_16x16x32_bf16 v[8:11], v[204:207], v[200:203], v[142:145]
	ds_read_b128 v[24:27], v129 offset:40960
	ds_read_b128 v[200:203], v129 offset:48704
	s_nop 0
	ds_read_b128 v[142:145], v129 offset:43520
	v_mfma_f32_16x16x32_bf16 v[134:137], v[204:207], v[196:199], v[134:137]
	ds_read_b128 v[196:199], v129 offset:48640
	ds_read_b128 v[204:207], v131 offset:48704
	s_waitcnt lgkmcnt(4)
	v_mfma_f32_16x16x32_bf16 v[28:31], v[4:7], v[24:27], v[188:191]
	s_waitcnt lgkmcnt(2)
	v_mfma_f32_16x16x32_bf16 v[188:191], v[4:7], v[142:145], v[192:195]
	s_nop 2
	ds_read_b128 v[192:195], v129 offset:46080
	s_waitcnt lgkmcnt(0)
	v_mfma_f32_16x16x32_bf16 v[138:141], v[4:7], v[192:195], v[138:141]
	v_mfma_f32_16x16x32_bf16 v[4:7], v[4:7], v[196:199], v[180:183]
	s_nop 2
	ds_read_b128 v[178:181], v131 offset:43520
	s_waitcnt lgkmcnt(0)
	v_mfma_f32_16x16x32_bf16 v[150:153], v[178:181], v[24:27], v[150:153]
	v_mfma_f32_16x16x32_bf16 v[154:157], v[178:181], v[142:145], v[154:157]
	v_mfma_f32_16x16x32_bf16 v[158:161], v[178:181], v[192:195], v[158:161]
	v_mfma_f32_16x16x32_bf16 v[146:149], v[178:181], v[196:199], v[146:149]
	ds_read_b128 v[178:181], v131 offset:46080
	s_waitcnt lgkmcnt(0)
	v_mfma_f32_16x16x32_bf16 v[166:169], v[178:181], v[24:27], v[166:169]
	v_mfma_f32_16x16x32_bf16 v[170:173], v[178:181], v[142:145], v[170:173]
	v_mfma_f32_16x16x32_bf16 v[174:177], v[178:181], v[192:195], v[174:177]
	v_mfma_f32_16x16x32_bf16 v[162:165], v[178:181], v[196:199], v[162:165]
	ds_read_b128 v[178:181], v131 offset:48640
	s_waitcnt lgkmcnt(0)
	v_mfma_f32_16x16x32_bf16 v[24:27], v[178:181], v[24:27], v[184:187]
	s_nop 2
	ds_read_b128 v[182:185], v131 offset:41024
	v_mfma_f32_16x16x32_bf16 v[142:145], v[178:181], v[142:145], v[212:215]
	v_mfma_f32_16x16x32_bf16 v[134:137], v[178:181], v[192:195], v[134:137]
	v_mfma_f32_16x16x32_bf16 v[8:11], v[178:181], v[196:199], v[8:11]
	ds_read_b128 v[178:181], v129 offset:41024
	ds_read_b128 v[196:199], v129 offset:46144
	s_waitcnt lgkmcnt(1)
	v_mfma_f32_16x16x32_bf16 v[192:195], v[182:185], v[178:181], v[28:31]
	s_nop 2
	ds_read_b128 v[28:31], v129 offset:43584
	s_waitcnt lgkmcnt(0)
	v_mfma_f32_16x16x32_bf16 v[186:189], v[182:185], v[28:31], v[188:191]
	v_mfma_f32_16x16x32_bf16 v[138:141], v[182:185], v[196:199], v[138:141]
	v_mfma_f32_16x16x32_bf16 v[182:185], v[182:185], v[200:203], v[4:7]
	s_nop 2
	ds_read_b128 v[4:7], v131 offset:43584
	s_waitcnt lgkmcnt(0)
	v_mfma_f32_16x16x32_bf16 v[150:153], v[4:7], v[178:181], v[150:153]
	v_mfma_f32_16x16x32_bf16 v[154:157], v[4:7], v[28:31], v[154:157]
	v_mfma_f32_16x16x32_bf16 v[158:161], v[4:7], v[196:199], v[158:161]
	v_mfma_f32_16x16x32_bf16 v[146:149], v[4:7], v[200:203], v[146:149]
	ds_read_b128 v[4:7], v131 offset:46144
	s_waitcnt vmcnt(23)
	ds_write_b128 v130, v[32:35]
	s_waitcnt vmcnt(22)
	ds_write_b128 v130, v[40:43] offset:5120
	s_waitcnt vmcnt(21)
	ds_write_b128 v130, v[44:47] offset:10240
	s_waitcnt vmcnt(20)
	ds_write_b128 v130, v[48:51] offset:15360
	s_waitcnt vmcnt(19)
	ds_write_b128 v130, v[64:67] offset:20480
	s_waitcnt vmcnt(18)
	ds_write_b128 v130, v[76:79] offset:25600
	s_waitcnt vmcnt(17)
	ds_write_b128 v130, v[80:83] offset:30720
	s_waitcnt vmcnt(16)
	ds_write_b128 v130, v[84:87] offset:35840
	s_waitcnt lgkmcnt(8)
	v_mfma_f32_16x16x32_bf16 v[166:169], v[4:7], v[178:181], v[166:169]
	v_mfma_f32_16x16x32_bf16 v[170:173], v[4:7], v[28:31], v[170:173]
	v_mfma_f32_16x16x32_bf16 v[174:177], v[4:7], v[196:199], v[174:177]
	v_mfma_f32_16x16x32_bf16 v[162:165], v[4:7], v[200:203], v[162:165]
	v_mfma_f32_16x16x32_bf16 v[178:181], v[204:207], v[178:181], v[24:27]
	v_mfma_f32_16x16x32_bf16 v[142:145], v[204:207], v[28:31], v[142:145]
	global_load_dwordx4 v[4:7], v[114:115], off offset:896
	s_nop 0
	global_load_dwordx4 v[24:27], v[116:117], off offset:896
	global_load_dwordx4 v[28:31], v[118:119], off offset:896
	global_load_dwordx4 v[32:35], v[124:125], off offset:896
	global_load_dwordx4 v[48:51], v[112:113], off offset:896
	global_load_dwordx4 v[64:67], v[120:121], off offset:896
	global_load_dwordx4 v[76:79], v[122:123], off offset:896
	global_load_dwordx4 v[80:83], v[126:127], off offset:896
	s_waitcnt lgkmcnt(0)
	s_barrier
	ds_read_b128 v[40:43], v131
	ds_read_b128 v[44:47], v129
	v_mfma_f32_16x16x32_bf16 v[134:137], v[204:207], v[196:199], v[134:137]
	v_mfma_f32_16x16x32_bf16 v[8:11], v[204:207], v[200:203], v[8:11]
	ds_read_b128 v[198:201], v129 offset:7680
	ds_read_b128 v[202:205], v131 offset:7744
	s_waitcnt lgkmcnt(2)
	v_mfma_f32_16x16x32_bf16 v[84:87], v[40:43], v[44:47], v[192:195]
	s_nop 2
	ds_read_b128 v[190:193], v129 offset:2560
	ds_read_b128 v[194:197], v129 offset:5120
	s_waitcnt lgkmcnt(1)
	v_mfma_f32_16x16x32_bf16 v[186:189], v[40:43], v[190:193], v[186:189]
	s_waitcnt lgkmcnt(0)
	v_mfma_f32_16x16x32_bf16 v[138:141], v[40:43], v[194:197], v[138:141]
	v_mfma_f32_16x16x32_bf16 v[40:43], v[40:43], v[198:201], v[182:185]
	s_nop 2
	ds_read_b128 v[182:185], v131 offset:2560
	s_waitcnt lgkmcnt(0)
	v_mfma_f32_16x16x32_bf16 v[150:153], v[182:185], v[44:47], v[150:153]
	v_mfma_f32_16x16x32_bf16 v[154:157], v[182:185], v[190:193], v[154:157]
	v_mfma_f32_16x16x32_bf16 v[158:161], v[182:185], v[194:197], v[158:161]
	v_mfma_f32_16x16x32_bf16 v[146:149], v[182:185], v[198:201], v[146:149]
	ds_read_b128 v[182:185], v131 offset:5120
	s_waitcnt lgkmcnt(0)
	v_mfma_f32_16x16x32_bf16 v[166:169], v[182:185], v[44:47], v[166:169]
	v_mfma_f32_16x16x32_bf16 v[170:173], v[182:185], v[190:193], v[170:173]
	v_mfma_f32_16x16x32_bf16 v[174:177], v[182:185], v[194:197], v[174:177]
	v_mfma_f32_16x16x32_bf16 v[162:165], v[182:185], v[198:201], v[162:165]
	ds_read_b128 v[182:185], v131 offset:7680
	s_waitcnt lgkmcnt(0)
	v_mfma_f32_16x16x32_bf16 v[44:47], v[182:185], v[44:47], v[178:181]
	s_nop 2
	ds_read_b128 v[178:181], v131 offset:64
	v_mfma_f32_16x16x32_bf16 v[142:145], v[182:185], v[190:193], v[142:145]
	v_mfma_f32_16x16x32_bf16 v[134:137], v[182:185], v[194:197], v[134:137]
	ds_read_b128 v[194:197], v129 offset:5184
	v_mfma_f32_16x16x32_bf16 v[182:185], v[182:185], v[198:201], v[8:11]
	ds_read_b128 v[198:201], v129 offset:7744
	s_nop 1
	ds_read_b128 v[8:11], v129 offset:64
	s_waitcnt lgkmcnt(0)
	v_mfma_f32_16x16x32_bf16 v[190:193], v[178:181], v[8:11], v[84:87]
	s_nop 2
	ds_read_b128 v[84:87], v129 offset:2624
	s_waitcnt lgkmcnt(0)
	v_mfma_f32_16x16x32_bf16 v[186:189], v[178:181], v[84:87], v[186:189]
	v_mfma_f32_16x16x32_bf16 v[138:141], v[178:181], v[194:197], v[138:141]
	v_mfma_f32_16x16x32_bf16 v[178:181], v[178:181], v[198:201], v[40:43]
	s_nop 2
	ds_read_b128 v[40:43], v131 offset:2624
	s_waitcnt lgkmcnt(0)
	v_mfma_f32_16x16x32_bf16 v[150:153], v[40:43], v[8:11], v[150:153]
	v_mfma_f32_16x16x32_bf16 v[154:157], v[40:43], v[84:87], v[154:157]
	v_mfma_f32_16x16x32_bf16 v[158:161], v[40:43], v[194:197], v[158:161]
	v_mfma_f32_16x16x32_bf16 v[146:149], v[40:43], v[198:201], v[146:149]
	ds_read_b128 v[40:43], v131 offset:5184
	s_waitcnt vmcnt(23)
	ds_write_b128 v130, v[36:39] offset:40960
	s_waitcnt vmcnt(22)
	ds_write_b128 v130, v[52:55] offset:46080
	s_waitcnt vmcnt(21)
	ds_write_b128 v130, v[56:59] offset:51200
	s_waitcnt vmcnt(20)
	ds_write_b128 v130, v[60:63] offset:56320
	s_waitcnt vmcnt(19)
	ds_write_b128 v130, v[68:71] offset:61440
	s_waitcnt vmcnt(18)
	ds_write_b128 v132, v[88:91] offset:5120
	s_waitcnt vmcnt(17)
	ds_write_b128 v132, v[92:95] offset:10240
	s_waitcnt vmcnt(16)
	ds_write_b128 v132, v[96:99] offset:15360
	s_waitcnt lgkmcnt(8)
	v_mfma_f32_16x16x32_bf16 v[166:169], v[40:43], v[8:11], v[166:169]
	v_mfma_f32_16x16x32_bf16 v[170:173], v[40:43], v[84:87], v[170:173]
	v_mfma_f32_16x16x32_bf16 v[174:177], v[40:43], v[194:197], v[174:177]
	v_mfma_f32_16x16x32_bf16 v[162:165], v[40:43], v[198:201], v[162:165]
	v_mfma_f32_16x16x32_bf16 v[212:215], v[202:205], v[8:11], v[44:47]
	v_mfma_f32_16x16x32_bf16 v[142:145], v[202:205], v[84:87], v[142:145]
	global_load_dwordx4 v[8:11], v[114:115], off offset:1024
	global_load_dwordx4 v[36:39], v[116:117], off offset:1024
	global_load_dwordx4 v[40:43], v[118:119], off offset:1024
	global_load_dwordx4 v[44:47], v[124:125], off offset:1024
	global_load_dwordx4 v[52:55], v[112:113], off offset:1024
	global_load_dwordx4 v[60:63], v[120:121], off offset:1024
	global_load_dwordx4 v[68:71], v[122:123], off offset:1024
	global_load_dwordx4 v[84:87], v[126:127], off offset:1024
	s_waitcnt lgkmcnt(0)
	s_barrier
	ds_read_b128 v[56:59], v131 offset:40960
	ds_read_b128 v[92:95], v129 offset:40960
	v_mfma_f32_16x16x32_bf16 v[134:137], v[202:205], v[194:197], v[134:137]
	ds_read_b128 v[194:197], v129 offset:48640
	v_mfma_f32_16x16x32_bf16 v[88:91], v[202:205], v[198:201], v[182:185]
	ds_read_b128 v[202:205], v131 offset:48704
	ds_read_b128 v[198:201], v129 offset:48704
	s_nop 0
	ds_read_b128 v[182:185], v129 offset:43520
	s_waitcnt lgkmcnt(4)
	v_mfma_f32_16x16x32_bf16 v[96:99], v[56:59], v[92:95], v[190:193]
	s_nop 2
	ds_read_b128 v[190:193], v129 offset:46080
	s_waitcnt lgkmcnt(1)
	v_mfma_f32_16x16x32_bf16 v[186:189], v[56:59], v[182:185], v[186:189]
	s_waitcnt lgkmcnt(0)
	v_mfma_f32_16x16x32_bf16 v[138:141], v[56:59], v[190:193], v[138:141]
	v_mfma_f32_16x16x32_bf16 v[56:59], v[56:59], v[194:197], v[178:181]
	s_nop 2
	ds_read_b128 v[178:181], v131 offset:43520
	s_waitcnt lgkmcnt(0)
	v_mfma_f32_16x16x32_bf16 v[150:153], v[178:181], v[92:95], v[150:153]
	v_mfma_f32_16x16x32_bf16 v[154:157], v[178:181], v[182:185], v[154:157]
	v_mfma_f32_16x16x32_bf16 v[158:161], v[178:181], v[190:193], v[158:161]
	v_mfma_f32_16x16x32_bf16 v[146:149], v[178:181], v[194:197], v[146:149]
	ds_read_b128 v[178:181], v131 offset:46080
	s_waitcnt lgkmcnt(0)
	v_mfma_f32_16x16x32_bf16 v[166:169], v[178:181], v[92:95], v[166:169]
	v_mfma_f32_16x16x32_bf16 v[170:173], v[178:181], v[182:185], v[170:173]
	v_mfma_f32_16x16x32_bf16 v[174:177], v[178:181], v[190:193], v[174:177]
	v_mfma_f32_16x16x32_bf16 v[162:165], v[178:181], v[194:197], v[162:165]
	ds_read_b128 v[178:181], v131 offset:48640
	s_waitcnt lgkmcnt(0)
	v_mfma_f32_16x16x32_bf16 v[142:145], v[178:181], v[182:185], v[142:145]
	ds_read_b128 v[182:185], v131 offset:41024
	v_mfma_f32_16x16x32_bf16 v[92:95], v[178:181], v[92:95], v[212:215]
	v_mfma_f32_16x16x32_bf16 v[134:137], v[178:181], v[190:193], v[134:137]
	ds_read_b128 v[190:193], v129 offset:43584
	v_mfma_f32_16x16x32_bf16 v[178:181], v[178:181], v[194:197], v[88:91]
	ds_read_b128 v[194:197], v129 offset:46144
	s_nop 1
	ds_read_b128 v[88:91], v129 offset:41024
	s_waitcnt lgkmcnt(0)
	v_mfma_f32_16x16x32_bf16 v[96:99], v[182:185], v[88:91], v[96:99]
	v_mfma_f32_16x16x32_bf16 v[186:189], v[182:185], v[190:193], v[186:189]
	v_mfma_f32_16x16x32_bf16 v[138:141], v[182:185], v[194:197], v[138:141]
	v_mfma_f32_16x16x32_bf16 v[182:185], v[182:185], v[198:201], v[56:59]
	s_nop 2
	ds_read_b128 v[56:59], v131 offset:43584
	s_waitcnt lgkmcnt(0)
	v_mfma_f32_16x16x32_bf16 v[150:153], v[56:59], v[88:91], v[150:153]
	v_mfma_f32_16x16x32_bf16 v[154:157], v[56:59], v[190:193], v[154:157]
	v_mfma_f32_16x16x32_bf16 v[158:161], v[56:59], v[194:197], v[158:161]
	v_mfma_f32_16x16x32_bf16 v[146:149], v[56:59], v[198:201], v[146:149]
	ds_read_b128 v[56:59], v131 offset:46144
	s_waitcnt vmcnt(23)
	ds_write_b128 v130, v[0:3]
	s_waitcnt vmcnt(22)
	ds_write_b128 v130, v[12:15] offset:5120
	s_waitcnt vmcnt(21)
	ds_write_b128 v130, v[16:19] offset:10240
	s_waitcnt vmcnt(20)
	ds_write_b128 v130, v[20:23] offset:15360
	s_waitcnt vmcnt(19)
	ds_write_b128 v130, v[72:75] offset:20480
	s_waitcnt vmcnt(18)
	ds_write_b128 v130, v[100:103] offset:25600
	s_waitcnt vmcnt(17)
	ds_write_b128 v130, v[104:107] offset:30720
	s_waitcnt vmcnt(16)
	ds_write_b128 v130, v[108:111] offset:35840
	s_waitcnt lgkmcnt(8)
	v_mfma_f32_16x16x32_bf16 v[166:169], v[56:59], v[88:91], v[166:169]
	v_mfma_f32_16x16x32_bf16 v[170:173], v[56:59], v[190:193], v[170:173]
	v_mfma_f32_16x16x32_bf16 v[174:177], v[56:59], v[194:197], v[174:177]
	v_mfma_f32_16x16x32_bf16 v[162:165], v[56:59], v[198:201], v[162:165]
	v_mfma_f32_16x16x32_bf16 v[212:215], v[202:205], v[88:91], v[92:95]
	global_load_dwordx4 v[0:3], v[114:115], off offset:1152
	global_load_dwordx4 v[12:15], v[116:117], off offset:1152
	global_load_dwordx4 v[16:19], v[118:119], off offset:1152
	global_load_dwordx4 v[20:23], v[124:125], off offset:1152
	global_load_dwordx4 v[56:59], v[112:113], off offset:1152
	global_load_dwordx4 v[72:75], v[120:121], off offset:1152
	global_load_dwordx4 v[88:91], v[122:123], off offset:1152
	global_load_dwordx4 v[92:95], v[126:127], off offset:1152
	s_waitcnt lgkmcnt(0)
	s_barrier
	ds_read_b128 v[100:103], v131
	v_mfma_f32_16x16x32_bf16 v[142:145], v[202:205], v[190:193], v[142:145]
	ds_read_b128 v[108:111], v129
	ds_read_b128 v[190:193], v129 offset:5120
	v_mfma_f32_16x16x32_bf16 v[134:137], v[202:205], v[194:197], v[134:137]
	ds_read_b128 v[194:197], v129 offset:7680
	v_mfma_f32_16x16x32_bf16 v[104:107], v[202:205], v[198:201], v[178:181]
	ds_read_b128 v[198:201], v129 offset:7744
	s_nop 1
	ds_read_b128 v[178:181], v129 offset:2560
	s_waitcnt lgkmcnt(4)
	v_mfma_f32_16x16x32_bf16 v[96:99], v[100:103], v[108:111], v[96:99]
	s_waitcnt lgkmcnt(0)
	v_mfma_f32_16x16x32_bf16 v[186:189], v[100:103], v[178:181], v[186:189]
	v_mfma_f32_16x16x32_bf16 v[138:141], v[100:103], v[190:193], v[138:141]
	v_mfma_f32_16x16x32_bf16 v[100:103], v[100:103], v[194:197], v[182:185]
	s_nop 2
	ds_read_b128 v[182:185], v131 offset:2560
	s_waitcnt lgkmcnt(0)
	v_mfma_f32_16x16x32_bf16 v[150:153], v[182:185], v[108:111], v[150:153]
	v_mfma_f32_16x16x32_bf16 v[154:157], v[182:185], v[178:181], v[154:157]
	v_mfma_f32_16x16x32_bf16 v[158:161], v[182:185], v[190:193], v[158:161]
	v_mfma_f32_16x16x32_bf16 v[146:149], v[182:185], v[194:197], v[146:149]
	ds_read_b128 v[182:185], v131 offset:5120
	s_waitcnt lgkmcnt(0)
	v_mfma_f32_16x16x32_bf16 v[166:169], v[182:185], v[108:111], v[166:169]
	v_mfma_f32_16x16x32_bf16 v[170:173], v[182:185], v[178:181], v[170:173]
	v_mfma_f32_16x16x32_bf16 v[174:177], v[182:185], v[190:193], v[174:177]
	v_mfma_f32_16x16x32_bf16 v[162:165], v[182:185], v[194:197], v[162:165]
	ds_read_b128 v[182:185], v131 offset:7680
	s_waitcnt lgkmcnt(0)
	v_mfma_f32_16x16x32_bf16 v[142:145], v[182:185], v[178:181], v[142:145]
	ds_read_b128 v[178:181], v131 offset:64
	v_mfma_f32_16x16x32_bf16 v[108:111], v[182:185], v[108:111], v[212:215]
	v_mfma_f32_16x16x32_bf16 v[134:137], v[182:185], v[190:193], v[134:137]
	ds_read_b128 v[190:193], v129 offset:2624
	v_mfma_f32_16x16x32_bf16 v[104:107], v[182:185], v[194:197], v[104:107]
	ds_read_b128 v[182:185], v129 offset:64
	ds_read_b128 v[194:197], v129 offset:5184
	s_waitcnt lgkmcnt(1)
	v_mfma_f32_16x16x32_bf16 v[96:99], v[178:181], v[182:185], v[96:99]
	v_mfma_f32_16x16x32_bf16 v[186:189], v[178:181], v[190:193], v[186:189]
	s_waitcnt lgkmcnt(0)
	v_mfma_f32_16x16x32_bf16 v[138:141], v[178:181], v[194:197], v[138:141]
	v_mfma_f32_16x16x32_bf16 v[100:103], v[178:181], v[198:201], v[100:103]
	ds_read_b128 v[178:181], v131 offset:2624
	s_waitcnt lgkmcnt(0)
	v_mfma_f32_16x16x32_bf16 v[150:153], v[178:181], v[182:185], v[150:153]
	v_mfma_f32_16x16x32_bf16 v[154:157], v[178:181], v[190:193], v[154:157]
	v_mfma_f32_16x16x32_bf16 v[158:161], v[178:181], v[194:197], v[158:161]
	v_mfma_f32_16x16x32_bf16 v[146:149], v[178:181], v[198:201], v[146:149]
	ds_read_b128 v[178:181], v131 offset:5184
	s_waitcnt lgkmcnt(0)
	v_mfma_f32_16x16x32_bf16 v[166:169], v[178:181], v[182:185], v[166:169]
	v_mfma_f32_16x16x32_bf16 v[170:173], v[178:181], v[190:193], v[170:173]
	v_mfma_f32_16x16x32_bf16 v[174:177], v[178:181], v[194:197], v[174:177]
	v_mfma_f32_16x16x32_bf16 v[162:165], v[178:181], v[198:201], v[162:165]
	ds_read_b128 v[178:181], v131 offset:7744
	s_waitcnt vmcnt(23)
	ds_write_b128 v130, v[4:7] offset:40960
	s_waitcnt vmcnt(22)
	ds_write_b128 v130, v[24:27] offset:46080
	s_waitcnt vmcnt(21)
	ds_write_b128 v130, v[28:31] offset:51200
	s_waitcnt vmcnt(20)
	ds_write_b128 v130, v[32:35] offset:56320
	s_waitcnt vmcnt(19)
	ds_write_b128 v130, v[48:51] offset:61440
	s_waitcnt vmcnt(18)
	ds_write_b128 v132, v[64:67] offset:5120
	s_waitcnt vmcnt(17)
	ds_write_b128 v132, v[76:79] offset:10240
	s_waitcnt vmcnt(16)
	ds_write_b128 v132, v[80:83] offset:15360
	global_load_dwordx4 v[4:7], v[114:115], off offset:1280
	global_load_dwordx4 v[24:27], v[116:117], off offset:1280
	global_load_dwordx4 v[28:31], v[118:119], off offset:1280
	global_load_dwordx4 v[32:35], v[124:125], off offset:1280
	global_load_dwordx4 v[48:51], v[112:113], off offset:1280
	global_load_dwordx4 v[64:67], v[120:121], off offset:1280
	global_load_dwordx4 v[76:79], v[122:123], off offset:1280
	global_load_dwordx4 v[80:83], v[126:127], off offset:1280
	s_waitcnt lgkmcnt(8)
	v_mfma_f32_16x16x32_bf16 v[108:111], v[178:181], v[182:185], v[108:111]
	s_waitcnt lgkmcnt(0)
	s_barrier
	ds_read_b128 v[182:185], v131 offset:40960
	v_mfma_f32_16x16x32_bf16 v[142:145], v[178:181], v[190:193], v[142:145]
	ds_read_b128 v[190:193], v129 offset:43520
	v_mfma_f32_16x16x32_bf16 v[134:137], v[178:181], v[194:197], v[134:137]
	ds_read_b128 v[194:197], v129 offset:46080
	v_mfma_f32_16x16x32_bf16 v[104:107], v[178:181], v[198:201], v[104:107]
	ds_read_b128 v[178:181], v129 offset:40960
	ds_read_b128 v[198:201], v129 offset:48640
	s_waitcnt lgkmcnt(1)
	v_mfma_f32_16x16x32_bf16 v[96:99], v[182:185], v[178:181], v[96:99]
	v_mfma_f32_16x16x32_bf16 v[186:189], v[182:185], v[190:193], v[186:189]
	v_mfma_f32_16x16x32_bf16 v[138:141], v[182:185], v[194:197], v[138:141]
	s_waitcnt lgkmcnt(0)
	v_mfma_f32_16x16x32_bf16 v[100:103], v[182:185], v[198:201], v[100:103]
	ds_read_b128 v[182:185], v131 offset:43520
	s_waitcnt lgkmcnt(0)
	v_mfma_f32_16x16x32_bf16 v[150:153], v[182:185], v[178:181], v[150:153]
	v_mfma_f32_16x16x32_bf16 v[154:157], v[182:185], v[190:193], v[154:157]
	v_mfma_f32_16x16x32_bf16 v[158:161], v[182:185], v[194:197], v[158:161]
	v_mfma_f32_16x16x32_bf16 v[146:149], v[182:185], v[198:201], v[146:149]
	ds_read_b128 v[182:185], v131 offset:46080
	s_waitcnt lgkmcnt(0)
	v_mfma_f32_16x16x32_bf16 v[166:169], v[182:185], v[178:181], v[166:169]
	v_mfma_f32_16x16x32_bf16 v[170:173], v[182:185], v[190:193], v[170:173]
	v_mfma_f32_16x16x32_bf16 v[174:177], v[182:185], v[194:197], v[174:177]
	v_mfma_f32_16x16x32_bf16 v[162:165], v[182:185], v[198:201], v[162:165]
	ds_read_b128 v[182:185], v131 offset:48640
	s_waitcnt lgkmcnt(0)
	v_mfma_f32_16x16x32_bf16 v[108:111], v[182:185], v[178:181], v[108:111]
	ds_read_b128 v[178:181], v131 offset:41024
	v_mfma_f32_16x16x32_bf16 v[142:145], v[182:185], v[190:193], v[142:145]
	ds_read_b128 v[190:193], v129 offset:43584
	v_mfma_f32_16x16x32_bf16 v[134:137], v[182:185], v[194:197], v[134:137]
	ds_read_b128 v[194:197], v129 offset:46144
	v_mfma_f32_16x16x32_bf16 v[104:107], v[182:185], v[198:201], v[104:107]
	ds_read_b128 v[182:185], v129 offset:41024
	ds_read_b128 v[198:201], v129 offset:48704
	s_waitcnt lgkmcnt(1)
	v_mfma_f32_16x16x32_bf16 v[96:99], v[178:181], v[182:185], v[96:99]
	v_mfma_f32_16x16x32_bf16 v[186:189], v[178:181], v[190:193], v[186:189]
	v_mfma_f32_16x16x32_bf16 v[138:141], v[178:181], v[194:197], v[138:141]
	s_waitcnt lgkmcnt(0)
	v_mfma_f32_16x16x32_bf16 v[100:103], v[178:181], v[198:201], v[100:103]
	ds_read_b128 v[178:181], v131 offset:43584
	s_waitcnt lgkmcnt(0)
	v_mfma_f32_16x16x32_bf16 v[150:153], v[178:181], v[182:185], v[150:153]
	v_mfma_f32_16x16x32_bf16 v[154:157], v[178:181], v[190:193], v[154:157]
	v_mfma_f32_16x16x32_bf16 v[158:161], v[178:181], v[194:197], v[158:161]
	v_mfma_f32_16x16x32_bf16 v[146:149], v[178:181], v[198:201], v[146:149]
	ds_read_b128 v[178:181], v131 offset:46144
	s_waitcnt lgkmcnt(0)
	v_mfma_f32_16x16x32_bf16 v[166:169], v[178:181], v[182:185], v[166:169]
	v_mfma_f32_16x16x32_bf16 v[170:173], v[178:181], v[190:193], v[170:173]
	v_mfma_f32_16x16x32_bf16 v[174:177], v[178:181], v[194:197], v[174:177]
	v_mfma_f32_16x16x32_bf16 v[162:165], v[178:181], v[198:201], v[162:165]
	ds_read_b128 v[178:181], v131 offset:48704
	s_waitcnt vmcnt(23)
	ds_write_b128 v130, v[8:11]
	s_waitcnt vmcnt(22)
	ds_write_b128 v130, v[36:39] offset:5120
	s_waitcnt vmcnt(21)
	ds_write_b128 v130, v[40:43] offset:10240
	s_waitcnt vmcnt(20)
	ds_write_b128 v130, v[44:47] offset:15360
	s_waitcnt vmcnt(19)
	ds_write_b128 v130, v[52:55] offset:20480
	s_waitcnt vmcnt(18)
	ds_write_b128 v130, v[60:63] offset:25600
	s_waitcnt vmcnt(17)
	ds_write_b128 v130, v[68:71] offset:30720
	s_waitcnt vmcnt(16)
	ds_write_b128 v130, v[84:87] offset:35840
	global_load_dwordx4 v[8:11], v[114:115], off offset:1408
	global_load_dwordx4 v[36:39], v[116:117], off offset:1408
	global_load_dwordx4 v[40:43], v[118:119], off offset:1408
	global_load_dwordx4 v[44:47], v[124:125], off offset:1408
	global_load_dwordx4 v[52:55], v[112:113], off offset:1408
	global_load_dwordx4 v[60:63], v[120:121], off offset:1408
	global_load_dwordx4 v[68:71], v[122:123], off offset:1408
	global_load_dwordx4 v[84:87], v[126:127], off offset:1408
	s_waitcnt lgkmcnt(8)
	v_mfma_f32_16x16x32_bf16 v[108:111], v[178:181], v[182:185], v[108:111]
	s_waitcnt lgkmcnt(0)
	s_barrier
	ds_read_b128 v[182:185], v131
	v_mfma_f32_16x16x32_bf16 v[142:145], v[178:181], v[190:193], v[142:145]
	ds_read_b128 v[190:193], v129 offset:2560
	v_mfma_f32_16x16x32_bf16 v[134:137], v[178:181], v[194:197], v[134:137]
	ds_read_b128 v[194:197], v129 offset:5120
	v_mfma_f32_16x16x32_bf16 v[104:107], v[178:181], v[198:201], v[104:107]
	ds_read_b128 v[178:181], v129
	ds_read_b128 v[198:201], v129 offset:7680
	s_waitcnt lgkmcnt(1)
	v_mfma_f32_16x16x32_bf16 v[96:99], v[182:185], v[178:181], v[96:99]
	v_mfma_f32_16x16x32_bf16 v[186:189], v[182:185], v[190:193], v[186:189]
	v_mfma_f32_16x16x32_bf16 v[138:141], v[182:185], v[194:197], v[138:141]
	s_waitcnt lgkmcnt(0)
	v_mfma_f32_16x16x32_bf16 v[100:103], v[182:185], v[198:201], v[100:103]
	ds_read_b128 v[182:185], v131 offset:2560
	s_waitcnt lgkmcnt(0)
	v_mfma_f32_16x16x32_bf16 v[150:153], v[182:185], v[178:181], v[150:153]
	v_mfma_f32_16x16x32_bf16 v[154:157], v[182:185], v[190:193], v[154:157]
	v_mfma_f32_16x16x32_bf16 v[158:161], v[182:185], v[194:197], v[158:161]
	v_mfma_f32_16x16x32_bf16 v[146:149], v[182:185], v[198:201], v[146:149]
	ds_read_b128 v[182:185], v131 offset:5120
	s_waitcnt lgkmcnt(0)
	v_mfma_f32_16x16x32_bf16 v[166:169], v[182:185], v[178:181], v[166:169]
	v_mfma_f32_16x16x32_bf16 v[170:173], v[182:185], v[190:193], v[170:173]
	v_mfma_f32_16x16x32_bf16 v[174:177], v[182:185], v[194:197], v[174:177]
	v_mfma_f32_16x16x32_bf16 v[162:165], v[182:185], v[198:201], v[162:165]
	ds_read_b128 v[182:185], v131 offset:7680
	s_waitcnt lgkmcnt(0)
	v_mfma_f32_16x16x32_bf16 v[108:111], v[182:185], v[178:181], v[108:111]
	ds_read_b128 v[178:181], v131 offset:64
	v_mfma_f32_16x16x32_bf16 v[142:145], v[182:185], v[190:193], v[142:145]
	ds_read_b128 v[190:193], v129 offset:2624
	v_mfma_f32_16x16x32_bf16 v[134:137], v[182:185], v[194:197], v[134:137]
	ds_read_b128 v[194:197], v129 offset:5184
	v_mfma_f32_16x16x32_bf16 v[104:107], v[182:185], v[198:201], v[104:107]
	ds_read_b128 v[182:185], v129 offset:64
	ds_read_b128 v[198:201], v129 offset:7744
	s_waitcnt lgkmcnt(1)
	v_mfma_f32_16x16x32_bf16 v[96:99], v[178:181], v[182:185], v[96:99]
	v_mfma_f32_16x16x32_bf16 v[186:189], v[178:181], v[190:193], v[186:189]
	v_mfma_f32_16x16x32_bf16 v[138:141], v[178:181], v[194:197], v[138:141]
	s_waitcnt lgkmcnt(0)
	v_mfma_f32_16x16x32_bf16 v[100:103], v[178:181], v[198:201], v[100:103]
	ds_read_b128 v[178:181], v131 offset:2624
	s_waitcnt lgkmcnt(0)
	v_mfma_f32_16x16x32_bf16 v[150:153], v[178:181], v[182:185], v[150:153]
	v_mfma_f32_16x16x32_bf16 v[154:157], v[178:181], v[190:193], v[154:157]
	v_mfma_f32_16x16x32_bf16 v[158:161], v[178:181], v[194:197], v[158:161]
	v_mfma_f32_16x16x32_bf16 v[146:149], v[178:181], v[198:201], v[146:149]
	ds_read_b128 v[178:181], v131 offset:5184
	s_waitcnt lgkmcnt(0)
	v_mfma_f32_16x16x32_bf16 v[166:169], v[178:181], v[182:185], v[166:169]
	v_mfma_f32_16x16x32_bf16 v[170:173], v[178:181], v[190:193], v[170:173]
	v_mfma_f32_16x16x32_bf16 v[174:177], v[178:181], v[194:197], v[174:177]
	v_mfma_f32_16x16x32_bf16 v[162:165], v[178:181], v[198:201], v[162:165]
	ds_read_b128 v[178:181], v131 offset:7744
	s_waitcnt vmcnt(23)
	ds_write_b128 v130, v[0:3] offset:40960
	s_waitcnt vmcnt(22)
	ds_write_b128 v130, v[12:15] offset:46080
	s_waitcnt vmcnt(21)
	ds_write_b128 v130, v[16:19] offset:51200
	s_waitcnt vmcnt(20)
	ds_write_b128 v130, v[20:23] offset:56320
	s_waitcnt vmcnt(19)
	ds_write_b128 v130, v[56:59] offset:61440
	s_waitcnt vmcnt(18)
	ds_write_b128 v132, v[72:75] offset:5120
	s_waitcnt vmcnt(17)
	ds_write_b128 v132, v[88:91] offset:10240
	s_waitcnt vmcnt(16)
	ds_write_b128 v132, v[92:95] offset:15360
	global_load_dwordx4 v[0:3], v[114:115], off offset:1536
	global_load_dwordx4 v[12:15], v[116:117], off offset:1536
	global_load_dwordx4 v[16:19], v[118:119], off offset:1536
	global_load_dwordx4 v[20:23], v[124:125], off offset:1536
	global_load_dwordx4 v[56:59], v[112:113], off offset:1536
	global_load_dwordx4 v[72:75], v[120:121], off offset:1536
	global_load_dwordx4 v[88:91], v[122:123], off offset:1536
	global_load_dwordx4 v[92:95], v[126:127], off offset:1536
	s_waitcnt lgkmcnt(8)
	v_mfma_f32_16x16x32_bf16 v[108:111], v[178:181], v[182:185], v[108:111]
	s_waitcnt lgkmcnt(0)
	s_barrier
	ds_read_b128 v[182:185], v131 offset:40960
	v_mfma_f32_16x16x32_bf16 v[142:145], v[178:181], v[190:193], v[142:145]
	ds_read_b128 v[190:193], v129 offset:43520
	v_mfma_f32_16x16x32_bf16 v[134:137], v[178:181], v[194:197], v[134:137]
	ds_read_b128 v[194:197], v129 offset:46080
	v_mfma_f32_16x16x32_bf16 v[104:107], v[178:181], v[198:201], v[104:107]
	ds_read_b128 v[178:181], v129 offset:40960
	ds_read_b128 v[198:201], v129 offset:48640
	s_waitcnt lgkmcnt(1)
	v_mfma_f32_16x16x32_bf16 v[96:99], v[182:185], v[178:181], v[96:99]
	v_mfma_f32_16x16x32_bf16 v[186:189], v[182:185], v[190:193], v[186:189]
	v_mfma_f32_16x16x32_bf16 v[138:141], v[182:185], v[194:197], v[138:141]
	s_waitcnt lgkmcnt(0)
	v_mfma_f32_16x16x32_bf16 v[100:103], v[182:185], v[198:201], v[100:103]
	ds_read_b128 v[182:185], v131 offset:43520
	s_waitcnt lgkmcnt(0)
	v_mfma_f32_16x16x32_bf16 v[150:153], v[182:185], v[178:181], v[150:153]
	v_mfma_f32_16x16x32_bf16 v[154:157], v[182:185], v[190:193], v[154:157]
	v_mfma_f32_16x16x32_bf16 v[158:161], v[182:185], v[194:197], v[158:161]
	v_mfma_f32_16x16x32_bf16 v[146:149], v[182:185], v[198:201], v[146:149]
	ds_read_b128 v[182:185], v131 offset:46080
	s_waitcnt lgkmcnt(0)
	v_mfma_f32_16x16x32_bf16 v[166:169], v[182:185], v[178:181], v[166:169]
	v_mfma_f32_16x16x32_bf16 v[170:173], v[182:185], v[190:193], v[170:173]
	v_mfma_f32_16x16x32_bf16 v[174:177], v[182:185], v[194:197], v[174:177]
	v_mfma_f32_16x16x32_bf16 v[162:165], v[182:185], v[198:201], v[162:165]
	ds_read_b128 v[182:185], v131 offset:48640
	s_waitcnt lgkmcnt(0)
	v_mfma_f32_16x16x32_bf16 v[108:111], v[182:185], v[178:181], v[108:111]
	ds_read_b128 v[178:181], v131 offset:41024
	v_mfma_f32_16x16x32_bf16 v[142:145], v[182:185], v[190:193], v[142:145]
	ds_read_b128 v[190:193], v129 offset:43584
	v_mfma_f32_16x16x32_bf16 v[134:137], v[182:185], v[194:197], v[134:137]
	ds_read_b128 v[194:197], v129 offset:46144
	v_mfma_f32_16x16x32_bf16 v[104:107], v[182:185], v[198:201], v[104:107]
	ds_read_b128 v[182:185], v129 offset:41024
	ds_read_b128 v[198:201], v129 offset:48704
	s_waitcnt lgkmcnt(1)
	v_mfma_f32_16x16x32_bf16 v[96:99], v[178:181], v[182:185], v[96:99]
	v_mfma_f32_16x16x32_bf16 v[186:189], v[178:181], v[190:193], v[186:189]
	v_mfma_f32_16x16x32_bf16 v[138:141], v[178:181], v[194:197], v[138:141]
	s_waitcnt lgkmcnt(0)
	v_mfma_f32_16x16x32_bf16 v[100:103], v[178:181], v[198:201], v[100:103]
	ds_read_b128 v[178:181], v131 offset:43584
	s_waitcnt lgkmcnt(0)
	v_mfma_f32_16x16x32_bf16 v[150:153], v[178:181], v[182:185], v[150:153]
	v_mfma_f32_16x16x32_bf16 v[154:157], v[178:181], v[190:193], v[154:157]
	v_mfma_f32_16x16x32_bf16 v[158:161], v[178:181], v[194:197], v[158:161]
	v_mfma_f32_16x16x32_bf16 v[146:149], v[178:181], v[198:201], v[146:149]
	ds_read_b128 v[178:181], v131 offset:46144
	s_waitcnt lgkmcnt(0)
	v_mfma_f32_16x16x32_bf16 v[166:169], v[178:181], v[182:185], v[166:169]
	v_mfma_f32_16x16x32_bf16 v[170:173], v[178:181], v[190:193], v[170:173]
	v_mfma_f32_16x16x32_bf16 v[174:177], v[178:181], v[194:197], v[174:177]
	v_mfma_f32_16x16x32_bf16 v[162:165], v[178:181], v[198:201], v[162:165]
	ds_read_b128 v[178:181], v131 offset:48704
	s_waitcnt vmcnt(23)
	ds_write_b128 v130, v[4:7]
	s_waitcnt vmcnt(22)
	ds_write_b128 v130, v[24:27] offset:5120
	s_waitcnt vmcnt(21)
	ds_write_b128 v130, v[28:31] offset:10240
	s_waitcnt vmcnt(20)
	ds_write_b128 v130, v[32:35] offset:15360
	s_waitcnt vmcnt(19)
	ds_write_b128 v130, v[48:51] offset:20480
	s_waitcnt vmcnt(18)
	ds_write_b128 v130, v[64:67] offset:25600
	s_waitcnt vmcnt(17)
	ds_write_b128 v130, v[76:79] offset:30720
	s_waitcnt vmcnt(16)
	ds_write_b128 v130, v[80:83] offset:35840
	global_load_dwordx4 v[4:7], v[114:115], off offset:1664
	global_load_dwordx4 v[24:27], v[116:117], off offset:1664
	global_load_dwordx4 v[28:31], v[118:119], off offset:1664
	global_load_dwordx4 v[32:35], v[124:125], off offset:1664
	global_load_dwordx4 v[48:51], v[112:113], off offset:1664
	global_load_dwordx4 v[64:67], v[120:121], off offset:1664
	global_load_dwordx4 v[76:79], v[122:123], off offset:1664
	global_load_dwordx4 v[80:83], v[126:127], off offset:1664
	s_waitcnt lgkmcnt(8)
	v_mfma_f32_16x16x32_bf16 v[108:111], v[178:181], v[182:185], v[108:111]
	s_waitcnt lgkmcnt(0)
	s_barrier
	ds_read_b128 v[182:185], v131
	v_mfma_f32_16x16x32_bf16 v[142:145], v[178:181], v[190:193], v[142:145]
	ds_read_b128 v[190:193], v129 offset:2560
	v_mfma_f32_16x16x32_bf16 v[134:137], v[178:181], v[194:197], v[134:137]
	ds_read_b128 v[194:197], v129 offset:5120
	v_mfma_f32_16x16x32_bf16 v[104:107], v[178:181], v[198:201], v[104:107]
	ds_read_b128 v[178:181], v129
	ds_read_b128 v[198:201], v129 offset:7680
	s_waitcnt lgkmcnt(1)
	v_mfma_f32_16x16x32_bf16 v[96:99], v[182:185], v[178:181], v[96:99]
	v_mfma_f32_16x16x32_bf16 v[186:189], v[182:185], v[190:193], v[186:189]
	v_mfma_f32_16x16x32_bf16 v[138:141], v[182:185], v[194:197], v[138:141]
	s_waitcnt lgkmcnt(0)
	v_mfma_f32_16x16x32_bf16 v[100:103], v[182:185], v[198:201], v[100:103]
	ds_read_b128 v[182:185], v131 offset:2560
	s_waitcnt lgkmcnt(0)
	v_mfma_f32_16x16x32_bf16 v[150:153], v[182:185], v[178:181], v[150:153]
	v_mfma_f32_16x16x32_bf16 v[154:157], v[182:185], v[190:193], v[154:157]
	v_mfma_f32_16x16x32_bf16 v[158:161], v[182:185], v[194:197], v[158:161]
	v_mfma_f32_16x16x32_bf16 v[146:149], v[182:185], v[198:201], v[146:149]
	ds_read_b128 v[182:185], v131 offset:5120
	s_waitcnt lgkmcnt(0)
	v_mfma_f32_16x16x32_bf16 v[166:169], v[182:185], v[178:181], v[166:169]
	v_mfma_f32_16x16x32_bf16 v[170:173], v[182:185], v[190:193], v[170:173]
	v_mfma_f32_16x16x32_bf16 v[174:177], v[182:185], v[194:197], v[174:177]
	v_mfma_f32_16x16x32_bf16 v[162:165], v[182:185], v[198:201], v[162:165]
	ds_read_b128 v[182:185], v131 offset:7680
	s_waitcnt lgkmcnt(0)
	v_mfma_f32_16x16x32_bf16 v[108:111], v[182:185], v[178:181], v[108:111]
	ds_read_b128 v[178:181], v131 offset:64
	v_mfma_f32_16x16x32_bf16 v[142:145], v[182:185], v[190:193], v[142:145]
	ds_read_b128 v[190:193], v129 offset:2624
	v_mfma_f32_16x16x32_bf16 v[134:137], v[182:185], v[194:197], v[134:137]
	ds_read_b128 v[194:197], v129 offset:5184
	v_mfma_f32_16x16x32_bf16 v[104:107], v[182:185], v[198:201], v[104:107]
	ds_read_b128 v[182:185], v129 offset:64
	ds_read_b128 v[198:201], v129 offset:7744
	s_waitcnt lgkmcnt(1)
	v_mfma_f32_16x16x32_bf16 v[96:99], v[178:181], v[182:185], v[96:99]
	v_mfma_f32_16x16x32_bf16 v[186:189], v[178:181], v[190:193], v[186:189]
	v_mfma_f32_16x16x32_bf16 v[138:141], v[178:181], v[194:197], v[138:141]
	s_waitcnt lgkmcnt(0)
	v_mfma_f32_16x16x32_bf16 v[100:103], v[178:181], v[198:201], v[100:103]
	ds_read_b128 v[178:181], v131 offset:2624
	s_waitcnt lgkmcnt(0)
	v_mfma_f32_16x16x32_bf16 v[150:153], v[178:181], v[182:185], v[150:153]
	v_mfma_f32_16x16x32_bf16 v[154:157], v[178:181], v[190:193], v[154:157]
	v_mfma_f32_16x16x32_bf16 v[158:161], v[178:181], v[194:197], v[158:161]
	v_mfma_f32_16x16x32_bf16 v[146:149], v[178:181], v[198:201], v[146:149]
	ds_read_b128 v[178:181], v131 offset:5184
	s_waitcnt lgkmcnt(0)
	v_mfma_f32_16x16x32_bf16 v[166:169], v[178:181], v[182:185], v[166:169]
	v_mfma_f32_16x16x32_bf16 v[170:173], v[178:181], v[190:193], v[170:173]
	v_mfma_f32_16x16x32_bf16 v[174:177], v[178:181], v[194:197], v[174:177]
	v_mfma_f32_16x16x32_bf16 v[162:165], v[178:181], v[198:201], v[162:165]
	ds_read_b128 v[178:181], v131 offset:7744
	s_waitcnt vmcnt(23)
	ds_write_b128 v130, v[8:11] offset:40960
	s_waitcnt vmcnt(22)
	ds_write_b128 v130, v[36:39] offset:46080
	s_waitcnt vmcnt(21)
	ds_write_b128 v130, v[40:43] offset:51200
	s_waitcnt vmcnt(20)
	ds_write_b128 v130, v[44:47] offset:56320
	s_waitcnt vmcnt(19)
	ds_write_b128 v130, v[52:55] offset:61440
	s_waitcnt vmcnt(18)
	ds_write_b128 v132, v[60:63] offset:5120
	s_waitcnt vmcnt(17)
	ds_write_b128 v132, v[68:71] offset:10240
	s_waitcnt vmcnt(16)
	ds_write_b128 v132, v[84:87] offset:15360
	global_load_dwordx4 v[8:11], v[114:115], off offset:1792
	global_load_dwordx4 v[44:47], v[116:117], off offset:1792
	global_load_dwordx4 v[36:39], v[118:119], off offset:1792
	global_load_dwordx4 v[40:43], v[124:125], off offset:1792
	global_load_dwordx4 v[52:55], v[112:113], off offset:1792
	global_load_dwordx4 v[60:63], v[120:121], off offset:1792
	global_load_dwordx4 v[68:71], v[122:123], off offset:1792
	global_load_dwordx4 v[84:87], v[126:127], off offset:1792
	s_waitcnt lgkmcnt(8)
	v_mfma_f32_16x16x32_bf16 v[108:111], v[178:181], v[182:185], v[108:111]
	s_waitcnt lgkmcnt(0)
	s_barrier
	ds_read_b128 v[182:185], v131 offset:40960
	v_mfma_f32_16x16x32_bf16 v[142:145], v[178:181], v[190:193], v[142:145]
	ds_read_b128 v[190:193], v129 offset:43520
	v_mfma_f32_16x16x32_bf16 v[134:137], v[178:181], v[194:197], v[134:137]
	ds_read_b128 v[194:197], v129 offset:46080
	v_mfma_f32_16x16x32_bf16 v[104:107], v[178:181], v[198:201], v[104:107]
	ds_read_b128 v[178:181], v129 offset:40960
	ds_read_b128 v[198:201], v129 offset:48640
	s_waitcnt lgkmcnt(1)
	v_mfma_f32_16x16x32_bf16 v[96:99], v[182:185], v[178:181], v[96:99]
	v_mfma_f32_16x16x32_bf16 v[186:189], v[182:185], v[190:193], v[186:189]
	v_mfma_f32_16x16x32_bf16 v[138:141], v[182:185], v[194:197], v[138:141]
	s_waitcnt lgkmcnt(0)
	v_mfma_f32_16x16x32_bf16 v[100:103], v[182:185], v[198:201], v[100:103]
	ds_read_b128 v[182:185], v131 offset:43520
	s_waitcnt lgkmcnt(0)
	v_mfma_f32_16x16x32_bf16 v[150:153], v[182:185], v[178:181], v[150:153]
	v_mfma_f32_16x16x32_bf16 v[154:157], v[182:185], v[190:193], v[154:157]
	v_mfma_f32_16x16x32_bf16 v[158:161], v[182:185], v[194:197], v[158:161]
	v_mfma_f32_16x16x32_bf16 v[146:149], v[182:185], v[198:201], v[146:149]
	ds_read_b128 v[182:185], v131 offset:46080
	s_waitcnt lgkmcnt(0)
	v_mfma_f32_16x16x32_bf16 v[166:169], v[182:185], v[178:181], v[166:169]
	v_mfma_f32_16x16x32_bf16 v[170:173], v[182:185], v[190:193], v[170:173]
	v_mfma_f32_16x16x32_bf16 v[174:177], v[182:185], v[194:197], v[174:177]
	v_mfma_f32_16x16x32_bf16 v[162:165], v[182:185], v[198:201], v[162:165]
	ds_read_b128 v[182:185], v131 offset:48640
	s_waitcnt lgkmcnt(0)
	v_mfma_f32_16x16x32_bf16 v[108:111], v[182:185], v[178:181], v[108:111]
	ds_read_b128 v[178:181], v131 offset:41024
	v_mfma_f32_16x16x32_bf16 v[142:145], v[182:185], v[190:193], v[142:145]
	ds_read_b128 v[190:193], v129 offset:43584
	v_mfma_f32_16x16x32_bf16 v[134:137], v[182:185], v[194:197], v[134:137]
	ds_read_b128 v[194:197], v129 offset:46144
	v_mfma_f32_16x16x32_bf16 v[104:107], v[182:185], v[198:201], v[104:107]
	ds_read_b128 v[182:185], v129 offset:41024
	ds_read_b128 v[198:201], v129 offset:48704
	s_waitcnt lgkmcnt(1)
	v_mfma_f32_16x16x32_bf16 v[96:99], v[178:181], v[182:185], v[96:99]
	v_mfma_f32_16x16x32_bf16 v[186:189], v[178:181], v[190:193], v[186:189]
	v_mfma_f32_16x16x32_bf16 v[138:141], v[178:181], v[194:197], v[138:141]
	s_waitcnt lgkmcnt(0)
	v_mfma_f32_16x16x32_bf16 v[100:103], v[178:181], v[198:201], v[100:103]
	ds_read_b128 v[178:181], v131 offset:43584
	s_waitcnt lgkmcnt(0)
	v_mfma_f32_16x16x32_bf16 v[150:153], v[178:181], v[182:185], v[150:153]
	v_mfma_f32_16x16x32_bf16 v[154:157], v[178:181], v[190:193], v[154:157]
	v_mfma_f32_16x16x32_bf16 v[158:161], v[178:181], v[194:197], v[158:161]
	v_mfma_f32_16x16x32_bf16 v[146:149], v[178:181], v[198:201], v[146:149]
	ds_read_b128 v[178:181], v131 offset:46144
	s_waitcnt lgkmcnt(0)
	v_mfma_f32_16x16x32_bf16 v[166:169], v[178:181], v[182:185], v[166:169]
	v_mfma_f32_16x16x32_bf16 v[170:173], v[178:181], v[190:193], v[170:173]
	v_mfma_f32_16x16x32_bf16 v[174:177], v[178:181], v[194:197], v[174:177]
	v_mfma_f32_16x16x32_bf16 v[162:165], v[178:181], v[198:201], v[162:165]
	ds_read_b128 v[178:181], v131 offset:48704
	s_waitcnt vmcnt(23)
	ds_write_b128 v130, v[0:3]
	s_waitcnt vmcnt(22)
	ds_write_b128 v130, v[12:15] offset:5120
	s_waitcnt vmcnt(21)
	ds_write_b128 v130, v[16:19] offset:10240
	s_waitcnt vmcnt(20)
	ds_write_b128 v130, v[20:23] offset:15360
	s_waitcnt vmcnt(19)
	ds_write_b128 v130, v[56:59] offset:20480
	s_waitcnt vmcnt(18)
	ds_write_b128 v130, v[72:75] offset:25600
	s_waitcnt vmcnt(17)
	ds_write_b128 v130, v[88:91] offset:30720
	s_waitcnt vmcnt(16)
	ds_write_b128 v130, v[92:95] offset:35840
	global_load_dwordx4 v[0:3], v[114:115], off offset:1920
	global_load_dwordx4 v[20:23], v[116:117], off offset:1920
	global_load_dwordx4 v[12:15], v[118:119], off offset:1920
	global_load_dwordx4 v[16:19], v[124:125], off offset:1920
	global_load_dwordx4 v[56:59], v[112:113], off offset:1920
	global_load_dwordx4 v[72:75], v[120:121], off offset:1920
	global_load_dwordx4 v[88:91], v[122:123], off offset:1920
	global_load_dwordx4 v[92:95], v[126:127], off offset:1920
	s_waitcnt lgkmcnt(0)
	s_barrier
	ds_read_b128 v[112:115], v131
	v_mfma_f32_16x16x32_bf16 v[108:111], v[178:181], v[182:185], v[108:111]
	ds_read_b128 v[116:119], v129
	ds_read_b128 v[120:123], v129 offset:2560
	ds_read_b128 v[182:185], v129 offset:7680
	v_mfma_f32_16x16x32_bf16 v[142:145], v[178:181], v[190:193], v[142:145]
	v_mfma_f32_16x16x32_bf16 v[134:137], v[178:181], v[194:197], v[134:137]
	v_mfma_f32_16x16x32_bf16 v[104:107], v[178:181], v[198:201], v[104:107]
	ds_read_b128 v[178:181], v129 offset:5120
	s_waitcnt lgkmcnt(3)
	v_mfma_f32_16x16x32_bf16 v[96:99], v[112:115], v[116:119], v[96:99]
	s_waitcnt lgkmcnt(2)
	v_mfma_f32_16x16x32_bf16 v[124:127], v[112:115], v[120:123], v[186:189]
	s_waitcnt lgkmcnt(0)
	v_mfma_f32_16x16x32_bf16 v[138:141], v[112:115], v[178:181], v[138:141]
	v_mfma_f32_16x16x32_bf16 v[100:103], v[112:115], v[182:185], v[100:103]
	ds_read_b128 v[112:115], v131 offset:2560
	s_waitcnt lgkmcnt(0)
	v_mfma_f32_16x16x32_bf16 v[150:153], v[112:115], v[116:119], v[150:153]
	v_mfma_f32_16x16x32_bf16 v[154:157], v[112:115], v[120:123], v[154:157]
	v_mfma_f32_16x16x32_bf16 v[158:161], v[112:115], v[178:181], v[158:161]
	v_mfma_f32_16x16x32_bf16 v[112:115], v[112:115], v[182:185], v[146:149]
	s_nop 2
	ds_read_b128 v[146:149], v131 offset:5120
	s_waitcnt lgkmcnt(0)
	v_mfma_f32_16x16x32_bf16 v[166:169], v[146:149], v[116:119], v[166:169]
	v_mfma_f32_16x16x32_bf16 v[170:173], v[146:149], v[120:123], v[170:173]
	v_mfma_f32_16x16x32_bf16 v[174:177], v[146:149], v[178:181], v[174:177]
	v_mfma_f32_16x16x32_bf16 v[146:149], v[146:149], v[182:185], v[162:165]
	s_nop 2
	ds_read_b128 v[162:165], v131 offset:7680
	s_waitcnt lgkmcnt(0)
	v_mfma_f32_16x16x32_bf16 v[108:111], v[162:165], v[116:119], v[108:111]
	v_mfma_f32_16x16x32_bf16 v[116:119], v[162:165], v[120:123], v[142:145]
	v_mfma_f32_16x16x32_bf16 v[120:123], v[162:165], v[178:181], v[134:137]
	s_nop 1
	ds_read_b128 v[142:145], v129 offset:64
	ds_read_b128 v[178:181], v129 offset:5184
	ds_read_b128 v[134:137], v131 offset:64
	v_mfma_f32_16x16x32_bf16 v[104:107], v[162:165], v[182:185], v[104:107]
	ds_read_b128 v[162:165], v129 offset:2624
	ds_read_b128 v[182:185], v129 offset:7744
	s_waitcnt lgkmcnt(2)
	v_mfma_f32_16x16x32_bf16 v[96:99], v[134:137], v[142:145], v[96:99]
	s_waitcnt lgkmcnt(1)
	v_mfma_f32_16x16x32_bf16 v[124:127], v[134:137], v[162:165], v[124:127]
	v_mfma_f32_16x16x32_bf16 v[138:141], v[134:137], v[178:181], v[138:141]
	s_waitcnt lgkmcnt(0)
	v_mfma_f32_16x16x32_bf16 v[100:103], v[134:137], v[182:185], v[100:103]
	ds_read_b128 v[134:137], v131 offset:2624
	s_waitcnt lgkmcnt(0)
	v_mfma_f32_16x16x32_bf16 v[150:153], v[134:137], v[142:145], v[150:153]
	v_mfma_f32_16x16x32_bf16 v[154:157], v[134:137], v[162:165], v[154:157]
	v_mfma_f32_16x16x32_bf16 v[158:161], v[134:137], v[178:181], v[158:161]
	v_mfma_f32_16x16x32_bf16 v[112:115], v[134:137], v[182:185], v[112:115]
	ds_read_b128 v[134:137], v131 offset:5184
	s_waitcnt lgkmcnt(0)
	v_mfma_f32_16x16x32_bf16 v[166:169], v[134:137], v[142:145], v[166:169]
	v_mfma_f32_16x16x32_bf16 v[170:173], v[134:137], v[162:165], v[170:173]
	v_mfma_f32_16x16x32_bf16 v[174:177], v[134:137], v[178:181], v[174:177]
	v_mfma_f32_16x16x32_bf16 v[134:137], v[134:137], v[182:185], v[146:149]
	s_nop 2
	ds_read_b128 v[146:149], v131 offset:7744
	s_waitcnt vmcnt(23)
	ds_write_b128 v130, v[4:7] offset:40960
	s_waitcnt vmcnt(22)
	ds_write_b128 v130, v[24:27] offset:46080
	s_waitcnt vmcnt(21)
	ds_write_b128 v130, v[28:31] offset:51200
	s_waitcnt vmcnt(20)
	ds_write_b128 v130, v[32:35] offset:56320
	s_waitcnt vmcnt(19)
	ds_write_b128 v130, v[48:51] offset:61440
	s_waitcnt vmcnt(18)
	ds_write_b128 v132, v[64:67] offset:5120
	s_waitcnt vmcnt(17)
	ds_write_b128 v132, v[76:79] offset:10240
	s_waitcnt vmcnt(16)
	ds_write_b128 v132, v[80:83] offset:15360
	s_waitcnt lgkmcnt(0)
	s_barrier
	ds_read_b128 v[4:7], v131 offset:40960
	ds_read_b128 v[28:31], v129 offset:40960
	ds_read_b128 v[48:51], v129 offset:43520
	s_waitcnt lgkmcnt(1)
	v_mfma_f32_16x16x32_bf16 v[32:35], v[4:7], v[28:31], v[96:99]
	ds_read_b128 v[76:79], v129 offset:46080
	s_nop 1
	ds_read_b128 v[96:99], v129 offset:48640
	s_waitcnt lgkmcnt(2)
	v_mfma_f32_16x16x32_bf16 v[64:67], v[4:7], v[48:51], v[124:127]
	s_waitcnt lgkmcnt(1)
	v_mfma_f32_16x16x32_bf16 v[80:83], v[4:7], v[76:79], v[138:141]
	s_waitcnt lgkmcnt(0)
	v_mfma_f32_16x16x32_bf16 v[4:7], v[4:7], v[96:99], v[100:103]
	s_nop 2
	ds_read_b128 v[100:103], v131 offset:43520
	v_mfma_f32_16x16x32_bf16 v[24:27], v[146:149], v[182:185], v[104:107]
	s_waitcnt lgkmcnt(0)
	v_mfma_f32_16x16x32_bf16 v[104:107], v[100:103], v[28:31], v[150:153]
	v_mfma_f32_16x16x32_bf16 v[124:127], v[100:103], v[48:51], v[154:157]
	v_mfma_f32_16x16x32_bf16 v[138:141], v[100:103], v[76:79], v[158:161]
	s_nop 1
	ds_read_b128 v[154:157], v131 offset:48704
	v_mfma_f32_16x16x32_bf16 v[100:103], v[100:103], v[96:99], v[112:115]
	s_nop 2
	ds_read_b128 v[112:115], v131 offset:46080
	v_mfma_f32_16x16x32_bf16 v[108:111], v[146:149], v[142:145], v[108:111]
	v_mfma_f32_16x16x32_bf16 v[116:119], v[146:149], v[162:165], v[116:119]
	v_mfma_f32_16x16x32_bf16 v[120:123], v[146:149], v[178:181], v[120:123]
	s_waitcnt lgkmcnt(0)
	v_mfma_f32_16x16x32_bf16 v[142:145], v[112:115], v[28:31], v[166:169]
	v_mfma_f32_16x16x32_bf16 v[146:149], v[112:115], v[48:51], v[170:173]
	v_mfma_f32_16x16x32_bf16 v[150:153], v[112:115], v[76:79], v[174:177]
	v_mfma_f32_16x16x32_bf16 v[112:115], v[112:115], v[96:99], v[134:137]
	s_nop 2
	ds_read_b128 v[134:137], v131 offset:48640
	s_waitcnt lgkmcnt(0)
	v_mfma_f32_16x16x32_bf16 v[28:31], v[134:137], v[28:31], v[108:111]
	s_nop 2
	ds_read_b128 v[108:111], v131 offset:41024
	v_mfma_f32_16x16x32_bf16 v[48:51], v[134:137], v[48:51], v[116:119]
	v_mfma_f32_16x16x32_bf16 v[76:79], v[134:137], v[76:79], v[120:123]
	s_nop 1
	ds_read_b128 v[116:119], v129 offset:43584
	v_mfma_f32_16x16x32_bf16 v[24:27], v[134:137], v[96:99], v[24:27]
	ds_read_b128 v[96:99], v129 offset:41024
	ds_read_b128 v[120:123], v129 offset:46144
	ds_read_b128 v[134:137], v129 offset:48704
	s_waitcnt lgkmcnt(2)
	v_mfma_f32_16x16x32_bf16 v[32:35], v[108:111], v[96:99], v[32:35]
	v_mfma_f32_16x16x32_bf16 v[64:67], v[108:111], v[116:119], v[64:67]
	s_waitcnt lgkmcnt(1)
	v_mfma_f32_16x16x32_bf16 v[80:83], v[108:111], v[120:123], v[80:83]
	s_waitcnt lgkmcnt(0)
	v_mfma_f32_16x16x32_bf16 v[4:7], v[108:111], v[134:137], v[4:7]
	ds_read_b128 v[108:111], v131 offset:43584
	s_waitcnt lgkmcnt(0)
	v_mfma_f32_16x16x32_bf16 v[104:107], v[108:111], v[96:99], v[104:107]
	v_mfma_f32_16x16x32_bf16 v[124:127], v[108:111], v[116:119], v[124:127]
	v_mfma_f32_16x16x32_bf16 v[138:141], v[108:111], v[120:123], v[138:141]
	v_mfma_f32_16x16x32_bf16 v[100:103], v[108:111], v[134:137], v[100:103]
	ds_read_b128 v[108:111], v131 offset:46144
	s_waitcnt vmcnt(15)
	ds_write_b128 v130, v[8:11]
	s_waitcnt vmcnt(14)
	ds_write_b128 v130, v[44:47] offset:5120
	s_waitcnt vmcnt(13)
	ds_write_b128 v130, v[36:39] offset:10240
	s_waitcnt vmcnt(12)
	ds_write_b128 v130, v[40:43] offset:15360
	s_waitcnt vmcnt(11)
	ds_write_b128 v130, v[52:55] offset:20480
	s_waitcnt vmcnt(10)
	ds_write_b128 v130, v[60:63] offset:25600
	s_waitcnt vmcnt(9)
	ds_write_b128 v130, v[68:71] offset:30720
	s_waitcnt vmcnt(8)
	ds_write_b128 v130, v[84:87] offset:35840
	s_waitcnt lgkmcnt(0)
	s_barrier
	ds_read_b128 v[44:47], v131
	v_mfma_f32_16x16x32_bf16 v[36:39], v[154:157], v[116:119], v[48:51]
	ds_read_b128 v[52:55], v129 offset:2560
	s_nop 1
	ds_read_b128 v[48:51], v129
	v_mfma_f32_16x16x32_bf16 v[146:149], v[108:111], v[116:119], v[146:149]
	ds_read_b128 v[116:119], v131 offset:7744
	v_mfma_f32_16x16x32_bf16 v[40:43], v[154:157], v[120:123], v[76:79]
	s_waitcnt lgkmcnt(2)
	v_mfma_f32_16x16x32_bf16 v[60:63], v[44:47], v[52:55], v[64:67]
	s_nop 0
	ds_read_b128 v[76:79], v129 offset:7680
	s_nop 0
	ds_read_b128 v[64:67], v129 offset:5120
	s_waitcnt lgkmcnt(3)
	v_mfma_f32_16x16x32_bf16 v[32:35], v[44:47], v[48:51], v[32:35]
	s_waitcnt lgkmcnt(0)
	v_mfma_f32_16x16x32_bf16 v[68:71], v[44:47], v[64:67], v[80:83]
	v_mfma_f32_16x16x32_bf16 v[4:7], v[44:47], v[76:79], v[4:7]
	ds_read_b128 v[44:47], v131 offset:2560
	v_mfma_f32_16x16x32_bf16 v[142:145], v[108:111], v[96:99], v[142:145]
	v_mfma_f32_16x16x32_bf16 v[28:31], v[154:157], v[96:99], v[28:31]
	s_waitcnt lgkmcnt(0)
	v_mfma_f32_16x16x32_bf16 v[80:83], v[44:47], v[48:51], v[104:107]
	v_mfma_f32_16x16x32_bf16 v[84:87], v[44:47], v[52:55], v[124:127]
	v_mfma_f32_16x16x32_bf16 v[96:99], v[44:47], v[64:67], v[138:141]
	v_mfma_f32_16x16x32_bf16 v[44:47], v[44:47], v[76:79], v[100:103]
	s_nop 2
	ds_read_b128 v[100:103], v131 offset:5120
	v_mfma_f32_16x16x32_bf16 v[150:153], v[108:111], v[120:123], v[150:153]
	v_mfma_f32_16x16x32_bf16 v[8:11], v[108:111], v[134:137], v[112:115]
	s_waitcnt lgkmcnt(0)
	v_mfma_f32_16x16x32_bf16 v[104:107], v[100:103], v[48:51], v[142:145]
	v_mfma_f32_16x16x32_bf16 v[108:111], v[100:103], v[52:55], v[146:149]
	v_mfma_f32_16x16x32_bf16 v[112:115], v[100:103], v[64:67], v[150:153]
	v_mfma_f32_16x16x32_bf16 v[8:11], v[100:103], v[76:79], v[8:11]
	ds_read_b128 v[100:103], v131 offset:7680
	v_mfma_f32_16x16x32_bf16 v[24:27], v[154:157], v[134:137], v[24:27]
	s_waitcnt lgkmcnt(0)
	v_mfma_f32_16x16x32_bf16 v[28:31], v[100:103], v[48:51], v[28:31]
	ds_read_b128 v[48:51], v131 offset:64
	v_mfma_f32_16x16x32_bf16 v[36:39], v[100:103], v[52:55], v[36:39]
	ds_read_b128 v[52:55], v129 offset:64
	v_mfma_f32_16x16x32_bf16 v[40:43], v[100:103], v[64:67], v[40:43]
	ds_read_b128 v[64:67], v129 offset:2624
	v_mfma_f32_16x16x32_bf16 v[24:27], v[100:103], v[76:79], v[24:27]
	ds_read_b128 v[76:79], v129 offset:5184
	ds_read_b128 v[100:103], v129 offset:7744
	s_waitcnt lgkmcnt(3)
	v_mfma_f32_16x16x32_bf16 v[32:35], v[48:51], v[52:55], v[32:35]
	s_waitcnt lgkmcnt(2)
	v_mfma_f32_16x16x32_bf16 v[60:63], v[48:51], v[64:67], v[60:63]
	s_waitcnt lgkmcnt(1)
	v_mfma_f32_16x16x32_bf16 v[68:71], v[48:51], v[76:79], v[68:71]
	s_waitcnt lgkmcnt(0)
	v_mfma_f32_16x16x32_bf16 v[4:7], v[48:51], v[100:103], v[4:7]
	ds_read_b128 v[48:51], v131 offset:2624
	s_waitcnt lgkmcnt(0)
	v_mfma_f32_16x16x32_bf16 v[80:83], v[48:51], v[52:55], v[80:83]
	v_mfma_f32_16x16x32_bf16 v[84:87], v[48:51], v[64:67], v[84:87]
	v_mfma_f32_16x16x32_bf16 v[96:99], v[48:51], v[76:79], v[96:99]
	v_mfma_f32_16x16x32_bf16 v[44:47], v[48:51], v[100:103], v[44:47]
	ds_read_b128 v[48:51], v131 offset:5184
	s_waitcnt vmcnt(7)
	ds_write_b128 v130, v[0:3] offset:40960
	s_waitcnt vmcnt(6)
	ds_write_b128 v130, v[20:23] offset:46080
	s_waitcnt vmcnt(5)
	ds_write_b128 v130, v[12:15] offset:51200
	s_waitcnt vmcnt(4)
	ds_write_b128 v130, v[16:19] offset:56320
	s_waitcnt vmcnt(3)
	ds_write_b128 v130, v[56:59] offset:61440
	s_waitcnt vmcnt(2)
	ds_write_b128 v132, v[72:75] offset:5120
	s_waitcnt vmcnt(1)
	ds_write_b128 v132, v[88:91] offset:10240
	s_waitcnt vmcnt(0)
	ds_write_b128 v132, v[92:95] offset:15360
	s_waitcnt lgkmcnt(0)
	s_barrier
	ds_read_b128 v[20:23], v131 offset:40960
	v_mfma_f32_16x16x32_bf16 v[104:107], v[48:51], v[52:55], v[104:107]
	ds_read_b128 v[56:59], v129 offset:48640
	v_mfma_f32_16x16x32_bf16 v[108:111], v[48:51], v[64:67], v[108:111]
	v_mfma_f32_16x16x32_bf16 v[112:115], v[48:51], v[76:79], v[112:115]
	v_mfma_f32_16x16x32_bf16 v[0:3], v[48:51], v[100:103], v[8:11]
	ds_read_b128 v[48:51], v129 offset:46080
	v_mfma_f32_16x16x32_bf16 v[8:11], v[116:119], v[52:55], v[28:31]
	v_mfma_f32_16x16x32_bf16 v[12:15], v[116:119], v[64:67], v[36:39]
	s_nop 1
	ds_read_b128 v[28:31], v129 offset:40960
	ds_read_b128 v[36:39], v129 offset:43520
	v_mfma_f32_16x16x32_bf16 v[16:19], v[116:119], v[76:79], v[40:43]
	s_waitcnt lgkmcnt(1)
	v_mfma_f32_16x16x32_bf16 v[32:35], v[20:23], v[28:31], v[32:35]
	s_waitcnt lgkmcnt(0)
	v_mfma_f32_16x16x32_bf16 v[40:43], v[20:23], v[36:39], v[60:63]
	v_mfma_f32_16x16x32_bf16 v[52:55], v[20:23], v[48:51], v[68:71]
	v_mfma_f32_16x16x32_bf16 v[4:7], v[20:23], v[56:59], v[4:7]
	ds_read_b128 v[20:23], v131 offset:43520
	s_waitcnt lgkmcnt(0)
	v_mfma_f32_16x16x32_bf16 v[60:63], v[20:23], v[28:31], v[80:83]
	v_mfma_f32_16x16x32_bf16 v[64:67], v[20:23], v[36:39], v[84:87]
	v_mfma_f32_16x16x32_bf16 v[68:71], v[20:23], v[48:51], v[96:99]
	v_mfma_f32_16x16x32_bf16 v[20:23], v[20:23], v[56:59], v[44:47]
	s_nop 2
	ds_read_b128 v[44:47], v131 offset:46080
	s_waitcnt lgkmcnt(0)
	v_mfma_f32_16x16x32_bf16 v[72:75], v[44:47], v[28:31], v[104:107]
	v_mfma_f32_16x16x32_bf16 v[76:79], v[44:47], v[36:39], v[108:111]
	v_mfma_f32_16x16x32_bf16 v[80:83], v[44:47], v[48:51], v[112:115]
	v_mfma_f32_16x16x32_bf16 v[0:3], v[44:47], v[56:59], v[0:3]
	ds_read_b128 v[44:47], v131 offset:48640
	ds_read_b128 v[84:87], v131 offset:41024
	ds_read_b128 v[88:91], v131 offset:43584
	v_mfma_f32_16x16x32_bf16 v[24:27], v[116:119], v[100:103], v[24:27]
	s_waitcnt lgkmcnt(2)
	v_mfma_f32_16x16x32_bf16 v[8:11], v[44:47], v[28:31], v[8:11]
	ds_read_b128 v[28:31], v131 offset:46144
	ds_read_b128 v[92:95], v131 offset:48704
	ds_read_b128 v[96:99], v129 offset:41024
	v_mfma_f32_16x16x32_bf16 v[12:15], v[44:47], v[36:39], v[12:15]
	ds_read_b128 v[36:39], v129 offset:43584
	ds_read_b128 v[100:103], v129 offset:46144
	ds_read_b128 v[104:107], v129 offset:48704
	s_waitcnt lgkmcnt(0)
	s_barrier
	v_mfma_f32_16x16x32_bf16 v[16:19], v[44:47], v[48:51], v[16:19]
	v_mfma_f32_16x16x32_bf16 v[24:27], v[44:47], v[56:59], v[24:27]
	v_mov_b32_e32 v44, v211
	s_nop 0
	v_lshrrev_b32_e32 v46, 2, v44
	v_mfma_f32_16x16x32_bf16 v[32:35], v[84:87], v[96:99], v[32:35]
	v_lshrrev_b32_e32 v45, 1, v44
	v_and_b32_e32 v46, 12, v46
	v_and_b32_e32 v44, 0x4f, v44
	v_mfma_f32_16x16x32_bf16 v[40:43], v[84:87], v[36:39], v[40:43]
	v_and_or_b32 v48, v45, s43, v46
	v_lshlrev_b32_e32 v49, 2, v44
	v_mul_lo_u32 v48, v48, s22
	v_mfma_f32_16x16x32_bf16 v[44:47], v[84:87], v[100:103], v[52:55]
	v_mfma_f32_16x16x32_bf16 v[4:7], v[84:87], v[104:107], v[4:7]
	s_nop 1
	v_add3_u32 v52, 0, v49, v48
	ds_write2_b32 v52, v32, v40 offset1:16
	v_add_u32_e32 v40, 0x400, v52
	ds_write2_b32 v52, v33, v41 offset0:132 offset1:148
	ds_write2_b32 v40, v34, v42 offset0:8 offset1:24
	v_mfma_f32_16x16x32_bf16 v[48:51], v[88:91], v[96:99], v[60:63]
	ds_write2_b32 v40, v35, v43 offset0:140 offset1:156
	ds_write2_b32 v52, v44, v4 offset0:32 offset1:48
	ds_write2_b32 v52, v45, v5 offset0:164 offset1:180
	ds_write2_b32 v40, v46, v6 offset0:40 offset1:56
	ds_write2_b32 v40, v47, v7 offset0:172 offset1:188
	v_add_u32_e32 v40, 0x2000, v52
	v_mfma_f32_16x16x32_bf16 v[32:35], v[88:91], v[36:39], v[64:67]
	v_add_u32_e32 v41, 0x2400, v52
	s_nop 6
	ds_write2_b32 v40, v48, v32 offset0:64 offset1:80
	ds_write2_b32 v40, v49, v33 offset0:196 offset1:212
	v_mfma_f32_16x16x32_bf16 v[4:7], v[88:91], v[100:103], v[68:71]
	v_mfma_f32_16x16x32_bf16 v[20:23], v[88:91], v[104:107], v[20:23]
	ds_write2_b32 v41, v50, v34 offset0:72 offset1:88
	ds_write2_b32 v41, v51, v35 offset0:204 offset1:220
	s_nop 5
	ds_write2_b32 v40, v4, v20 offset0:96 offset1:112
	ds_write2_b32 v40, v5, v21 offset0:228 offset1:244
	ds_write2_b32 v41, v6, v22 offset0:104 offset1:120
	ds_write2_b32 v41, v7, v23 offset0:236 offset1:252
	v_mfma_f32_16x16x32_bf16 v[32:35], v[28:31], v[96:99], v[72:75]
	v_add_u32_e32 v40, 0x4000, v52
	v_mfma_f32_16x16x32_bf16 v[4:7], v[28:31], v[36:39], v[76:79]
	v_mfma_f32_16x16x32_bf16 v[20:23], v[28:31], v[100:103], v[80:83]
	v_mfma_f32_16x16x32_bf16 v[0:3], v[28:31], v[104:107], v[0:3]
	s_nop 5
	ds_write2_b32 v40, v32, v4 offset0:128 offset1:144
	v_add_u32_e32 v32, 0x4400, v52
	ds_write2_b32 v32, v33, v5 offset0:4 offset1:20
	ds_write2_b32 v32, v34, v6 offset0:136 offset1:152
	v_add_u32_e32 v33, 0x4800, v52
	ds_write2_b32 v33, v35, v7 offset0:12 offset1:28
	ds_write2_b32 v40, v20, v0 offset0:160 offset1:176
	ds_write2_b32 v32, v21, v1 offset0:36 offset1:52
	v_mfma_f32_16x16x32_bf16 v[4:7], v[92:95], v[96:99], v[8:11]
	ds_write2_b32 v32, v22, v2 offset0:168 offset1:184
	ds_write2_b32 v33, v23, v3 offset0:44 offset1:60
	v_add_u32_e32 v20, 0x6000, v52
	v_mfma_f32_16x16x32_bf16 v[0:3], v[92:95], v[36:39], v[12:15]
	v_mfma_f32_16x16x32_bf16 v[8:11], v[92:95], v[100:103], v[16:19]
	s_nop 6
	ds_write2_b32 v20, v4, v0 offset0:192 offset1:208
	v_add_u32_e32 v4, 0x6400, v52
	ds_write2_b32 v4, v5, v1 offset0:68 offset1:84
	v_add_u32_e32 v5, 0x6800, v52
	ds_write2_b32 v4, v6, v2 offset0:200 offset1:216
	ds_write2_b32 v5, v7, v3 offset0:76 offset1:92
	v_mfma_f32_16x16x32_bf16 v[0:3], v[92:95], v[104:107], v[24:27]
	s_nop 7
	ds_write2_b32 v20, v8, v0 offset0:224 offset1:240
	ds_write2_b32 v4, v9, v1 offset0:100 offset1:116
	ds_write2_b32 v4, v10, v2 offset0:232 offset1:248
	ds_write2_b32 v5, v11, v3 offset0:108 offset1:124
	v_mov_b32_e32 v0, v211
	s_waitcnt lgkmcnt(0)
	s_barrier
	s_nop 0
	v_lshlrev_b32_e32 v1, 3, v0
	v_and_b32_e32 v9, 0x78, v1
	v_ashrrev_i32_e32 v8, 4, v0
	v_lshlrev_b32_e32 v0, 2, v9
	v_mul_lo_u32 v1, v8, s22
	v_add3_u32 v16, 0, v0, v1
	ds_read_b128 v[0:3], v16
	ds_read_b128 v[4:7], v16 offset:16
	v_lshlrev_b32_e32 v208, 1, v9
	v_ashrrev_i32_e32 v9, 31, v8
	v_lshlrev_b64 v[14:15], 12, v[8:9]
	s_waitcnt lgkmcnt(1)
	v_cvt_pk_bf16_f32 v0, v0, v1
	v_cvt_pk_bf16_f32 v1, v2, v3
	s_waitcnt lgkmcnt(0)
	v_cvt_pk_bf16_f32 v2, v4, v5
	v_cvt_pk_bf16_f32 v3, v6, v7
	ds_read_b128 v[4:7], v16 offset:8448
	ds_read_b128 v[8:11], v16 offset:8464
	v_lshl_add_u64 v[12:13], s[4:5], 0, v[208:209]
	v_lshl_add_u64 v[12:13], v[12:13], 0, v[14:15]
	global_store_dwordx4 v[12:13], v[0:3], off nt
	v_add_co_u32_e32 v14, vcc, s8, v12
	s_waitcnt lgkmcnt(1)
	v_cvt_pk_bf16_f32 v0, v4, v5
	v_cvt_pk_bf16_f32 v1, v6, v7
	s_waitcnt lgkmcnt(0)
	v_cvt_pk_bf16_f32 v2, v8, v9
	v_cvt_pk_bf16_f32 v3, v10, v11
	ds_read_b128 v[4:7], v16 offset:16896
	ds_read_b128 v[8:11], v16 offset:16912
	v_addc_co_u32_e32 v15, vcc, 0, v13, vcc
	global_store_dwordx4 v[14:15], v[0:3], off nt
	v_add_co_u32_e32 v14, vcc, s7, v12
	s_waitcnt lgkmcnt(1)
	v_cvt_pk_bf16_f32 v0, v4, v5
	v_cvt_pk_bf16_f32 v1, v6, v7
	s_waitcnt lgkmcnt(0)
	v_cvt_pk_bf16_f32 v2, v8, v9
	v_cvt_pk_bf16_f32 v3, v10, v11
	ds_read_b128 v[4:7], v16 offset:25344
	ds_read_b128 v[8:11], v16 offset:25360
	v_addc_co_u32_e32 v15, vcc, 0, v13, vcc
	global_store_dwordx4 v[14:15], v[0:3], off nt
	v_add_co_u32_e32 v14, vcc, s9, v12
	s_waitcnt lgkmcnt(1)
	v_cvt_pk_bf16_f32 v0, v4, v5
	v_cvt_pk_bf16_f32 v1, v6, v7
	s_waitcnt lgkmcnt(0)
	v_cvt_pk_bf16_f32 v2, v8, v9
	v_cvt_pk_bf16_f32 v3, v10, v11
	ds_read_b128 v[4:7], v16 offset:33792
	ds_read_b128 v[8:11], v16 offset:33808
	v_addc_co_u32_e32 v15, vcc, 0, v13, vcc
	global_store_dwordx4 v[14:15], v[0:3], off nt
	s_mov_b32 s4, 0x40000
	v_add_co_u32_e32 v14, vcc, s4, v12
	s_waitcnt lgkmcnt(1)
	v_cvt_pk_bf16_f32 v0, v4, v5
	v_cvt_pk_bf16_f32 v1, v6, v7
	s_waitcnt lgkmcnt(0)
	v_cvt_pk_bf16_f32 v2, v8, v9
	v_cvt_pk_bf16_f32 v3, v10, v11
	ds_read_b128 v[4:7], v16 offset:42240
	ds_read_b128 v[8:11], v16 offset:42256
	v_addc_co_u32_e32 v15, vcc, 0, v13, vcc
	global_store_dwordx4 v[14:15], v[0:3], off nt
	s_mov_b32 s4, 0x50000
	v_add_co_u32_e32 v14, vcc, s4, v12
	s_waitcnt lgkmcnt(1)
	v_cvt_pk_bf16_f32 v0, v4, v5
	v_cvt_pk_bf16_f32 v1, v6, v7
	s_waitcnt lgkmcnt(0)
	v_cvt_pk_bf16_f32 v2, v8, v9
	v_cvt_pk_bf16_f32 v3, v10, v11
	ds_read_b128 v[4:7], v16 offset:50688
	ds_read_b128 v[8:11], v16 offset:50704
	v_addc_co_u32_e32 v15, vcc, 0, v13, vcc
	global_store_dwordx4 v[14:15], v[0:3], off nt
	s_mov_b32 s4, 0x60000
	v_add_co_u32_e32 v14, vcc, s4, v12
	s_waitcnt lgkmcnt(1)
	v_cvt_pk_bf16_f32 v0, v4, v5
	v_cvt_pk_bf16_f32 v1, v6, v7
	s_waitcnt lgkmcnt(0)
	v_cvt_pk_bf16_f32 v2, v8, v9
	v_cvt_pk_bf16_f32 v3, v10, v11
	ds_read_b128 v[4:7], v16 offset:59136
	ds_read_b128 v[8:11], v16 offset:59152
	v_addc_co_u32_e32 v15, vcc, 0, v13, vcc
	global_store_dwordx4 v[14:15], v[0:3], off nt
	s_waitcnt lgkmcnt(1)
	s_nop 0
	v_cvt_pk_bf16_f32 v0, v4, v5
	v_add_co_u32_e32 v4, vcc, 0x70000, v12
	v_cvt_pk_bf16_f32 v1, v6, v7
	s_waitcnt lgkmcnt(0)
	v_cvt_pk_bf16_f32 v2, v8, v9
	v_cvt_pk_bf16_f32 v3, v10, v11
	v_addc_co_u32_e32 v5, vcc, 0, v13, vcc
	global_store_dwordx4 v[4:5], v[0:3], off nt
	s_barrier
	s_and_saveexec_b64 s[4:5], s[36:37]
	s_cbranch_execz .LBB0_93
	v_readlane_b32 s6, v253, 62
	s_nop 1
	v_mov_b32_e32 v0, s6
	s_waitcnt vmcnt(0)
	v_add_u32_e32 v128, s26, v128
	ds_write_b32 v0, v128
	s_branch .LBB0_93

.LBB0_114:
	s_mov_b64 s[10:11], exec
	v_mbcnt_lo_u32_b32 v0, s10, 0
	v_mbcnt_hi_u32_b32 v0, s11, v0
	v_cmp_eq_u32_e32 vcc, 0, v0
	s_and_saveexec_b64 s[8:9], vcc
	s_cbranch_execz .LBB0_116
	s_bcnt1_i32_b64 s10, s[10:11]
	v_mov_b32_e32 v1, s10
	global_atomic_add v137, v209, v1, s[4:5] sc0
.LBB0_116:
	s_or_b64 exec, exec, s[8:9]
	v_readlane_b32 s18, v254, 14
	s_movk_i32 s19, 0x48
	s_or_b64 exec, exec, s[0:1]
	s_cmp_lt_i32 s16, s12
	s_mov_b64 s[0:1], -1
	s_cbranch_scc1 .LBB0_113

.LBB0_125:
	s_barrier
	s_and_saveexec_b64 s[0:1], s[36:37]
	s_cbranch_execz .LBB0_110
	v_readlane_b32 s8, v253, 62
	s_nop 1
	v_mov_b32_e32 v0, s8
	s_waitcnt vmcnt(0)
	v_add_u32_e32 v137, s26, v137
	ds_write_b32 v0, v137
	s_branch .LBB0_110

.LBB0_132:
	v_mov_b32_e32 v144, 0
	s_and_saveexec_b64 s[4:5], s[36:37]
	s_cbranch_execz .LBB0_136
	s_mov_b64 s[8:9], exec
	v_mbcnt_lo_u32_b32 v0, s8, 0
	v_mbcnt_hi_u32_b32 v0, s9, v0
	v_cmp_eq_u32_e32 vcc, 0, v0
	s_and_saveexec_b64 s[6:7], vcc
	s_cbranch_execz .LBB0_135
	s_bcnt1_i32_b64 s8, s[8:9]
	v_mov_b32_e32 v1, s8
	global_atomic_add v144, v209, v1, s[0:1] sc0
.LBB0_135:
	s_or_b64 exec, exec, s[6:7]
.LBB0_136:
	s_or_b64 exec, exec, s[4:5]
	s_ashr_i32 s4, s13, 3
	s_and_b32 s6, s13, 7
	v_readlane_b32 s2, v254, 0
	s_ashr_i32 s5, s4, 31
	s_lshl_b32 s14, s6, 7
	s_lshl_b32 s8, s6, 9
	v_readlane_b32 s3, v254, 1
	s_add_u32 s17, s11, s8
	s_mov_b32 s9, s3
	v_writelane_b32 v254, s2, 0
	s_mul_i32 s7, s4, 0x180000
	s_addc_u32 s18, s12, 0
	s_lshl_b32 s8, s6, 8
	v_mov_b32_e32 v104, 0
	v_writelane_b32 v254, s3, 1
	v_readlane_b32 s2, v252, 3
	v_mov_b32_e32 v207, 0xb9c68948
	v_mov_b32_e32 v206, 0x7f800000
	s_mul_hi_i32 s13, s4, 0x60000
	s_mul_i32 s15, s4, 0x60000
	s_mul_hi_i32 s16, s4, 0x180000
	s_or_b32 s19, s7, s8
	s_lshl_b32 s8, s6, 17
	s_mov_b64 s[6:7], 0
	v_mov_b32_e32 v105, v104
	v_mov_b32_e32 v120, v104
	v_mov_b32_e32 v121, v104
	v_mov_b32_e32 v124, v104
	v_mov_b32_e32 v125, v104
	v_mov_b32_e32 v126, v104
	v_mov_b32_e32 v127, v104
	v_mov_b32_e32 v110, v104
	v_mov_b32_e32 v111, v104
	v_mov_b32_e32 v114, v104
	v_mov_b32_e32 v115, v104
	v_mov_b32_e32 v118, v104
	v_mov_b32_e32 v119, v104
	v_mov_b32_e32 v122, v104
	v_mov_b32_e32 v123, v104
	v_mov_b32_e32 v100, v104
	v_mov_b32_e32 v101, v104
	v_mov_b32_e32 v106, v104
	v_mov_b32_e32 v107, v104
	v_mov_b32_e32 v112, v104
	v_mov_b32_e32 v113, v104
	v_mov_b32_e32 v116, v104
	v_mov_b32_e32 v117, v104
	v_mov_b32_e32 v92, v104
	v_mov_b32_e32 v93, v104
	v_mov_b32_e32 v96, v104
	v_mov_b32_e32 v97, v104
	v_mov_b32_e32 v102, v104
	v_mov_b32_e32 v103, v104
	v_mov_b32_e32 v108, v104
	v_mov_b32_e32 v109, v104
	v_mov_b32_e32 v84, v104
	v_mov_b32_e32 v85, v104
	v_mov_b32_e32 v88, v104
	v_mov_b32_e32 v89, v104
	v_mov_b32_e32 v94, v104
	v_mov_b32_e32 v95, v104
	v_mov_b32_e32 v98, v104
	v_mov_b32_e32 v99, v104
	v_mov_b32_e32 v78, v104
	v_mov_b32_e32 v79, v104
	v_mov_b32_e32 v82, v104
	v_mov_b32_e32 v83, v104
	v_mov_b32_e32 v86, v104
	v_mov_b32_e32 v87, v104
	v_mov_b32_e32 v90, v104
	v_mov_b32_e32 v91, v104
	v_mov_b32_e32 v70, v104
	v_mov_b32_e32 v71, v104
	v_mov_b32_e32 v74, v104
	v_mov_b32_e32 v75, v104
	v_mov_b32_e32 v76, v104
	v_mov_b32_e32 v77, v104
	v_mov_b32_e32 v80, v104
	v_mov_b32_e32 v81, v104
	v_mov_b32_e32 v64, v104
	v_mov_b32_e32 v65, v104
	v_mov_b32_e32 v66, v104
	v_mov_b32_e32 v67, v104
	v_mov_b32_e32 v68, v104
	v_mov_b32_e32 v69, v104
	v_mov_b32_e32 v72, v104
	v_mov_b32_e32 v73, v104
	s_movk_i32 s38, 0xc00
	s_movk_i32 s39, 0x3000
	v_readlane_b32 s3, v252, 4
.LBB0_137:
	v_mov_b32_e32 v148, v211
	s_nop 0
	v_ashrrev_i32_e32 v146, 3, v148
	v_mad_i64_i32 v[0:1], s[20:21], v146, s38, 0
	v_lshlrev_b32_e32 v2, 4, v148
	v_and_b32_e32 v145, 0x70, v2
	s_add_u32 s20, s2, s15
	v_ashrrev_i32_e32 v147, 31, v146
	v_or_b32_e32 v0, v0, v145
	s_addc_u32 s21, s3, s13
	v_lshl_add_u64 v[12:13], s[20:21], 0, v[0:1]
	v_lshlrev_b64 v[0:1], 10, v[146:147]
	s_add_u32 s20, s2, s8
	v_or_b32_e32 v0, v0, v145
	s_addc_u32 s21, s3, s9
	v_lshl_add_u64 v[28:29], s[20:21], 0, v[0:1]
	s_mov_b32 s20, 0x28600000
	v_add_co_u32_e32 v128, vcc, s20, v12
	s_mov_b32 s20, 0x28618000
	s_nop 0
	v_addc_co_u32_e32 v129, vcc, 0, v13, vcc
	v_add_co_u32_e32 v130, vcc, s20, v12
	s_mov_b32 s20, 0x28630000
	s_nop 0
	v_addc_co_u32_e32 v131, vcc, 0, v13, vcc
	v_add_co_u32_e32 v132, vcc, s20, v12
	s_mov_b32 s20, 0x28648000
	s_nop 0
	v_addc_co_u32_e32 v133, vcc, 0, v13, vcc
	v_add_co_u32_e32 v134, vcc, s20, v12
	s_mov_b32 s20, 0x33c00000
	s_nop 0
	v_addc_co_u32_e32 v135, vcc, 0, v13, vcc
	global_load_dwordx4 v[0:3], v[128:129], off
	global_load_dwordx4 v[4:7], v[130:131], off
	v_add_co_u32_e32 v136, vcc, s20, v28
	s_mov_b32 s20, 0x33c08000
	s_nop 0
	v_addc_co_u32_e32 v137, vcc, 0, v29, vcc
	global_load_dwordx4 v[8:11], v[132:133], off
	global_load_dwordx4 v[12:15], v[134:135], off
	v_add_co_u32_e32 v138, vcc, s20, v28
	s_mov_b32 s20, 0x33c10000
	s_nop 0
	v_addc_co_u32_e32 v139, vcc, 0, v29, vcc
	global_load_dwordx4 v[16:19], v[136:137], off
	global_load_dwordx4 v[20:23], v[138:139], off
	v_add_co_u32_e32 v140, vcc, s20, v28
	s_mov_b32 s20, 0x33c18000
	s_nop 0
	v_addc_co_u32_e32 v141, vcc, 0, v29, vcc
	global_load_dwordx4 v[24:27], v[140:141], off
	v_add_co_u32_e32 v142, vcc, s20, v28
	v_mul_u32_u24_e32 v146, 0xa0, v146
	s_nop 0
	v_addc_co_u32_e32 v143, vcc, 0, v29, vcc
	global_load_dwordx4 v[28:31], v[142:143], off
	global_load_dwordx4 v[56:59], v[128:129], off offset:128
	global_load_dwordx4 v[60:63], v[130:131], off offset:128
	global_load_dwordx4 v[44:47], v[132:133], off offset:128
	global_load_dwordx4 v[48:51], v[134:135], off offset:128
	global_load_dwordx4 v[52:55], v[136:137], off offset:128
	global_load_dwordx4 v[32:35], v[138:139], off offset:128
	global_load_dwordx4 v[36:39], v[140:141], off offset:128
	global_load_dwordx4 v[40:43], v[142:143], off offset:128
	v_add3_u32 v145, 0, v146, v145
	s_barrier
	s_add_u32 s20, s17, s6
	s_addc_u32 s21, s18, s7
	s_waitcnt vmcnt(15)
	ds_write_b128 v145, v[0:3]
	s_waitcnt vmcnt(14)
	ds_write_b128 v145, v[4:7] offset:5120
	s_waitcnt vmcnt(13)
	ds_write_b128 v145, v[8:11] offset:10240
	s_waitcnt vmcnt(12)
	ds_write_b128 v145, v[12:15] offset:15360
	s_waitcnt vmcnt(11)
	ds_write_b128 v145, v[16:19] offset:20480
	s_waitcnt vmcnt(10)
	ds_write_b128 v145, v[20:23] offset:25600
	s_waitcnt vmcnt(9)
	ds_write_b128 v145, v[24:27] offset:30720
	s_waitcnt vmcnt(8)
	ds_write_b128 v145, v[28:31] offset:35840
	v_and_b32_e32 v0, 15, v148
	v_lshrrev_b32_e32 v1, 1, v148
	v_and_or_b32 v0, v1, s43, v0
	v_mul_u32_u24_e32 v0, 0xa0, v0
	v_and_b32_e32 v1, 48, v148
	v_add3_u32 v146, 0, v0, v1
	v_and_b32_e32 v0, 0x4f, v148
	v_mul_u32_u24_e32 v0, 0x50, v0
	v_lshlrev_b32_e32 v0, 1, v0
	s_waitcnt lgkmcnt(0)
	s_barrier
	v_add3_u32 v147, 0, v0, v1
	v_add_u32_e32 v147, 0x5000, v147
	global_load_dwordx4 v[0:3], v[128:129], off offset:256
	global_load_dwordx4 v[4:7], v[130:131], off offset:256
	global_load_dwordx4 v[8:11], v[132:133], off offset:256
	global_load_dwordx4 v[12:15], v[134:135], off offset:256
	global_load_dwordx4 v[16:19], v[136:137], off offset:256
	global_load_dwordx4 v[20:23], v[138:139], off offset:256
	global_load_dwordx4 v[24:27], v[140:141], off offset:256
	global_load_dwordx4 v[28:31], v[142:143], off offset:256
	ds_read_b128 v[150:153], v146
	ds_read_b128 v[154:157], v146 offset:2560
	ds_read_b128 v[158:161], v146 offset:5120
	ds_read_b128 v[162:165], v146 offset:7680
	ds_read_b128 v[166:169], v147
	ds_read_b128 v[170:173], v147 offset:2560
	ds_read_b128 v[174:177], v147 offset:5120
	ds_read_b128 v[178:181], v147 offset:7680
	v_add_u32_e32 v148, 0xf000, v145
	s_waitcnt lgkmcnt(3)
	v_mfma_f32_16x16x32_bf16 v[182:185], v[150:153], v[166:169], 0
	s_waitcnt lgkmcnt(2)
	v_mfma_f32_16x16x32_bf16 v[186:189], v[150:153], v[170:173], 0
	s_waitcnt lgkmcnt(1)
	v_mfma_f32_16x16x32_bf16 v[190:193], v[150:153], v[174:177], 0
	s_waitcnt lgkmcnt(0)
	v_mfma_f32_16x16x32_bf16 v[150:153], v[150:153], v[178:181], 0
	v_mfma_f32_16x16x32_bf16 v[194:197], v[154:157], v[166:169], 0
	v_mfma_f32_16x16x32_bf16 v[198:201], v[154:157], v[170:173], 0
	v_mfma_f32_16x16x32_bf16 v[202:205], v[154:157], v[174:177], 0
	v_mfma_f32_16x16x32_bf16 v[154:157], v[154:157], v[178:181], 0
	v_mfma_f32_16x16x32_bf16 v[212:215], v[158:161], v[166:169], 0
	v_mfma_f32_16x16x32_bf16 v[224:227], v[158:161], v[170:173], 0
	v_mfma_f32_16x16x32_bf16 v[228:231], v[158:161], v[174:177], 0
	v_mfma_f32_16x16x32_bf16 v[158:161], v[158:161], v[178:181], 0
	v_mfma_f32_16x16x32_bf16 v[166:169], v[162:165], v[166:169], 0
	v_mfma_f32_16x16x32_bf16 v[170:173], v[162:165], v[170:173], 0
	v_mfma_f32_16x16x32_bf16 v[174:177], v[162:165], v[174:177], 0
	v_mfma_f32_16x16x32_bf16 v[162:165], v[162:165], v[178:181], 0
	ds_read_b128 v[178:181], v146 offset:64
	ds_read_b128 v[232:235], v146 offset:2624
	ds_read_b128 v[236:239], v146 offset:5184
	ds_read_b128 v[240:243], v146 offset:7744
	ds_read_b128 v[244:247], v147 offset:64
	ds_read_b128 v[248:251], v147 offset:2624
	ds_read_b128 v[216:219], v147 offset:5184
	ds_read_b128 v[220:223], v147 offset:7744
	s_waitcnt vmcnt(15)
	ds_write_b128 v145, v[56:59] offset:40960
	s_waitcnt vmcnt(14)
	ds_write_b128 v145, v[60:63] offset:46080
	s_waitcnt vmcnt(13)
	ds_write_b128 v145, v[44:47] offset:51200
	s_waitcnt vmcnt(12)
	ds_write_b128 v145, v[48:51] offset:56320
	s_waitcnt vmcnt(11)
	ds_write_b128 v145, v[52:55] offset:61440
	s_waitcnt vmcnt(10)
	ds_write_b128 v148, v[32:35] offset:5120
	s_waitcnt vmcnt(9)
	ds_write_b128 v148, v[36:39] offset:10240
	s_waitcnt vmcnt(8)
	ds_write_b128 v148, v[40:43] offset:15360
	s_waitcnt lgkmcnt(0)
	s_barrier
	global_load_dwordx4 v[56:59], v[128:129], off offset:384
	global_load_dwordx4 v[60:63], v[130:131], off offset:384
	global_load_dwordx4 v[44:47], v[132:133], off offset:384
	global_load_dwordx4 v[48:51], v[134:135], off offset:384
	global_load_dwordx4 v[52:55], v[136:137], off offset:384
	global_load_dwordx4 v[32:35], v[138:139], off offset:384
	global_load_dwordx4 v[36:39], v[140:141], off offset:384
	global_load_dwordx4 v[40:43], v[142:143], off offset:384
	v_mfma_f32_16x16x32_bf16 v[182:185], v[178:181], v[244:247], v[182:185]
	v_mfma_f32_16x16x32_bf16 v[186:189], v[178:181], v[248:251], v[186:189]
	v_mfma_f32_16x16x32_bf16 v[190:193], v[178:181], v[216:219], v[190:193]
	v_mfma_f32_16x16x32_bf16 v[150:153], v[178:181], v[220:223], v[150:153]
	v_mfma_f32_16x16x32_bf16 v[178:181], v[232:235], v[244:247], v[194:197]
	v_mfma_f32_16x16x32_bf16 v[194:197], v[232:235], v[248:251], v[198:201]
	v_mfma_f32_16x16x32_bf16 v[198:201], v[232:235], v[216:219], v[202:205]
	v_mfma_f32_16x16x32_bf16 v[154:157], v[232:235], v[220:223], v[154:157]
	v_mfma_f32_16x16x32_bf16 v[202:205], v[236:239], v[244:247], v[212:215]
	v_mfma_f32_16x16x32_bf16 v[212:215], v[236:239], v[248:251], v[224:227]
	v_mfma_f32_16x16x32_bf16 v[224:227], v[236:239], v[216:219], v[228:231]
	v_mfma_f32_16x16x32_bf16 v[158:161], v[236:239], v[220:223], v[158:161]
	v_mfma_f32_16x16x32_bf16 v[166:169], v[240:243], v[244:247], v[166:169]
	v_mfma_f32_16x16x32_bf16 v[170:173], v[240:243], v[248:251], v[170:173]
	v_mfma_f32_16x16x32_bf16 v[174:177], v[240:243], v[216:219], v[174:177]
	v_mfma_f32_16x16x32_bf16 v[162:165], v[240:243], v[220:223], v[162:165]
	ds_read_b128 v[216:219], v146 offset:40960
	ds_read_b128 v[220:223], v146 offset:43520
	ds_read_b128 v[228:231], v146 offset:46080
	ds_read_b128 v[232:235], v146 offset:48640
	ds_read_b128 v[236:239], v147 offset:40960
	ds_read_b128 v[240:243], v147 offset:43520
	ds_read_b128 v[244:247], v147 offset:46080
	ds_read_b128 v[248:251], v147 offset:48640
	s_waitcnt lgkmcnt(3)
	v_mfma_f32_16x16x32_bf16 v[182:185], v[216:219], v[236:239], v[182:185]
	s_waitcnt lgkmcnt(2)
	v_mfma_f32_16x16x32_bf16 v[186:189], v[216:219], v[240:243], v[186:189]
	s_waitcnt lgkmcnt(1)
	v_mfma_f32_16x16x32_bf16 v[190:193], v[216:219], v[244:247], v[190:193]
	s_waitcnt lgkmcnt(0)
	v_mfma_f32_16x16x32_bf16 v[150:153], v[216:219], v[248:251], v[150:153]
	v_mfma_f32_16x16x32_bf16 v[178:181], v[220:223], v[236:239], v[178:181]
	v_mfma_f32_16x16x32_bf16 v[194:197], v[220:223], v[240:243], v[194:197]
	v_mfma_f32_16x16x32_bf16 v[198:201], v[220:223], v[244:247], v[198:201]
	v_mfma_f32_16x16x32_bf16 v[154:157], v[220:223], v[248:251], v[154:157]
	v_mfma_f32_16x16x32_bf16 v[202:205], v[228:231], v[236:239], v[202:205]
	v_mfma_f32_16x16x32_bf16 v[212:215], v[228:231], v[240:243], v[212:215]
	v_mfma_f32_16x16x32_bf16 v[216:219], v[228:231], v[244:247], v[224:227]
	v_mfma_f32_16x16x32_bf16 v[158:161], v[228:231], v[248:251], v[158:161]
	v_mfma_f32_16x16x32_bf16 v[166:169], v[232:235], v[236:239], v[166:169]
	v_mfma_f32_16x16x32_bf16 v[170:173], v[232:235], v[240:243], v[170:173]
	v_mfma_f32_16x16x32_bf16 v[174:177], v[232:235], v[244:247], v[174:177]
	v_mfma_f32_16x16x32_bf16 v[162:165], v[232:235], v[248:251], v[162:165]
	ds_read_b128 v[220:223], v146 offset:41024
	ds_read_b128 v[224:227], v146 offset:43584
	ds_read_b128 v[228:231], v146 offset:46144
	ds_read_b128 v[232:235], v146 offset:48704
	ds_read_b128 v[236:239], v147 offset:41024
	ds_read_b128 v[240:243], v147 offset:43584
	ds_read_b128 v[244:247], v147 offset:46144
	ds_read_b128 v[248:251], v147 offset:48704
	s_waitcnt vmcnt(15)
	ds_write_b128 v145, v[0:3]
	s_waitcnt vmcnt(14)
	ds_write_b128 v145, v[4:7] offset:5120
	s_waitcnt vmcnt(13)
	ds_write_b128 v145, v[8:11] offset:10240
	s_waitcnt vmcnt(12)
	ds_write_b128 v145, v[12:15] offset:15360
	s_waitcnt vmcnt(11)
	ds_write_b128 v145, v[16:19] offset:20480
	s_waitcnt vmcnt(10)
	ds_write_b128 v145, v[20:23] offset:25600
	s_waitcnt vmcnt(9)
	ds_write_b128 v145, v[24:27] offset:30720
	s_waitcnt vmcnt(8)
	ds_write_b128 v145, v[28:31] offset:35840
	s_waitcnt lgkmcnt(0)
	s_barrier
	global_load_dwordx4 v[0:3], v[128:129], off offset:512
	global_load_dwordx4 v[4:7], v[130:131], off offset:512
	global_load_dwordx4 v[8:11], v[132:133], off offset:512
	global_load_dwordx4 v[12:15], v[134:135], off offset:512
	global_load_dwordx4 v[16:19], v[136:137], off offset:512
	global_load_dwordx4 v[20:23], v[138:139], off offset:512
	global_load_dwordx4 v[24:27], v[140:141], off offset:512
	global_load_dwordx4 v[28:31], v[142:143], off offset:512
	v_mfma_f32_16x16x32_bf16 v[182:185], v[220:223], v[236:239], v[182:185]
	v_mfma_f32_16x16x32_bf16 v[186:189], v[220:223], v[240:243], v[186:189]
	v_mfma_f32_16x16x32_bf16 v[190:193], v[220:223], v[244:247], v[190:193]
	v_mfma_f32_16x16x32_bf16 v[150:153], v[220:223], v[248:251], v[150:153]
	v_mfma_f32_16x16x32_bf16 v[178:181], v[224:227], v[236:239], v[178:181]
	v_mfma_f32_16x16x32_bf16 v[194:197], v[224:227], v[240:243], v[194:197]
	v_mfma_f32_16x16x32_bf16 v[198:201], v[224:227], v[244:247], v[198:201]
	v_mfma_f32_16x16x32_bf16 v[154:157], v[224:227], v[248:251], v[154:157]
	v_mfma_f32_16x16x32_bf16 v[202:205], v[228:231], v[236:239], v[202:205]
	v_mfma_f32_16x16x32_bf16 v[212:215], v[228:231], v[240:243], v[212:215]
	v_mfma_f32_16x16x32_bf16 v[216:219], v[228:231], v[244:247], v[216:219]
	v_mfma_f32_16x16x32_bf16 v[158:161], v[228:231], v[248:251], v[158:161]
	v_mfma_f32_16x16x32_bf16 v[166:169], v[232:235], v[236:239], v[166:169]
	v_mfma_f32_16x16x32_bf16 v[170:173], v[232:235], v[240:243], v[170:173]
	v_mfma_f32_16x16x32_bf16 v[174:177], v[232:235], v[244:247], v[174:177]
	v_mfma_f32_16x16x32_bf16 v[162:165], v[232:235], v[248:251], v[162:165]
	ds_read_b128 v[220:223], v146
	ds_read_b128 v[224:227], v146 offset:2560
	ds_read_b128 v[228:231], v146 offset:5120
	ds_read_b128 v[232:235], v146 offset:7680
	ds_read_b128 v[236:239], v147
	ds_read_b128 v[240:243], v147 offset:2560
	ds_read_b128 v[244:247], v147 offset:5120
	ds_read_b128 v[248:251], v147 offset:7680
	s_waitcnt lgkmcnt(3)
	v_mfma_f32_16x16x32_bf16 v[182:185], v[220:223], v[236:239], v[182:185]
	s_waitcnt lgkmcnt(2)
	v_mfma_f32_16x16x32_bf16 v[186:189], v[220:223], v[240:243], v[186:189]
	s_waitcnt lgkmcnt(1)
	v_mfma_f32_16x16x32_bf16 v[190:193], v[220:223], v[244:247], v[190:193]
	s_waitcnt lgkmcnt(0)
	v_mfma_f32_16x16x32_bf16 v[150:153], v[220:223], v[248:251], v[150:153]
	v_mfma_f32_16x16x32_bf16 v[178:181], v[224:227], v[236:239], v[178:181]
	v_mfma_f32_16x16x32_bf16 v[194:197], v[224:227], v[240:243], v[194:197]
	v_mfma_f32_16x16x32_bf16 v[198:201], v[224:227], v[244:247], v[198:201]
	v_mfma_f32_16x16x32_bf16 v[154:157], v[224:227], v[248:251], v[154:157]
	v_mfma_f32_16x16x32_bf16 v[202:205], v[228:231], v[236:239], v[202:205]
	v_mfma_f32_16x16x32_bf16 v[212:215], v[228:231], v[240:243], v[212:215]
	v_mfma_f32_16x16x32_bf16 v[216:219], v[228:231], v[244:247], v[216:219]
	v_mfma_f32_16x16x32_bf16 v[158:161], v[228:231], v[248:251], v[158:161]
	v_mfma_f32_16x16x32_bf16 v[166:169], v[232:235], v[236:239], v[166:169]
	v_mfma_f32_16x16x32_bf16 v[170:173], v[232:235], v[240:243], v[170:173]
	v_mfma_f32_16x16x32_bf16 v[174:177], v[232:235], v[244:247], v[174:177]
	v_mfma_f32_16x16x32_bf16 v[162:165], v[232:235], v[248:251], v[162:165]
	ds_read_b128 v[220:223], v146 offset:64
	ds_read_b128 v[224:227], v146 offset:2624
	ds_read_b128 v[228:231], v146 offset:5184
	ds_read_b128 v[232:235], v146 offset:7744
	ds_read_b128 v[236:239], v147 offset:64
	ds_read_b128 v[240:243], v147 offset:2624
	ds_read_b128 v[244:247], v147 offset:5184
	ds_read_b128 v[248:251], v147 offset:7744
	s_waitcnt vmcnt(15)
	ds_write_b128 v145, v[56:59] offset:40960
	s_waitcnt vmcnt(14)
	ds_write_b128 v145, v[60:63] offset:46080
	s_waitcnt vmcnt(13)
	ds_write_b128 v145, v[44:47] offset:51200
	s_waitcnt vmcnt(12)
	ds_write_b128 v145, v[48:51] offset:56320
	s_waitcnt vmcnt(11)
	ds_write_b128 v145, v[52:55] offset:61440
	s_waitcnt vmcnt(10)
	ds_write_b128 v148, v[32:35] offset:5120
	s_waitcnt vmcnt(9)
	ds_write_b128 v148, v[36:39] offset:10240
	s_waitcnt vmcnt(8)
	ds_write_b128 v148, v[40:43] offset:15360
	s_waitcnt lgkmcnt(0)
	s_barrier
	global_load_dwordx4 v[56:59], v[128:129], off offset:640
	global_load_dwordx4 v[60:63], v[130:131], off offset:640
	global_load_dwordx4 v[44:47], v[132:133], off offset:640
	global_load_dwordx4 v[48:51], v[134:135], off offset:640
	global_load_dwordx4 v[52:55], v[136:137], off offset:640
	global_load_dwordx4 v[32:35], v[138:139], off offset:640
	global_load_dwordx4 v[36:39], v[140:141], off offset:640
	global_load_dwordx4 v[40:43], v[142:143], off offset:640
	v_mfma_f32_16x16x32_bf16 v[182:185], v[220:223], v[236:239], v[182:185]
	v_mfma_f32_16x16x32_bf16 v[186:189], v[220:223], v[240:243], v[186:189]
	v_mfma_f32_16x16x32_bf16 v[190:193], v[220:223], v[244:247], v[190:193]
	v_mfma_f32_16x16x32_bf16 v[150:153], v[220:223], v[248:251], v[150:153]
	v_mfma_f32_16x16x32_bf16 v[178:181], v[224:227], v[236:239], v[178:181]
	v_mfma_f32_16x16x32_bf16 v[194:197], v[224:227], v[240:243], v[194:197]
	v_mfma_f32_16x16x32_bf16 v[198:201], v[224:227], v[244:247], v[198:201]
	v_mfma_f32_16x16x32_bf16 v[154:157], v[224:227], v[248:251], v[154:157]
	v_mfma_f32_16x16x32_bf16 v[202:205], v[228:231], v[236:239], v[202:205]
	v_mfma_f32_16x16x32_bf16 v[212:215], v[228:231], v[240:243], v[212:215]
	v_mfma_f32_16x16x32_bf16 v[216:219], v[228:231], v[244:247], v[216:219]
	v_mfma_f32_16x16x32_bf16 v[158:161], v[228:231], v[248:251], v[158:161]
	v_mfma_f32_16x16x32_bf16 v[166:169], v[232:235], v[236:239], v[166:169]
	v_mfma_f32_16x16x32_bf16 v[170:173], v[232:235], v[240:243], v[170:173]
	v_mfma_f32_16x16x32_bf16 v[174:177], v[232:235], v[244:247], v[174:177]
	v_mfma_f32_16x16x32_bf16 v[162:165], v[232:235], v[248:251], v[162:165]
	ds_read_b128 v[220:223], v146 offset:40960
	ds_read_b128 v[224:227], v146 offset:43520
	ds_read_b128 v[228:231], v146 offset:46080
	ds_read_b128 v[232:235], v146 offset:48640
	ds_read_b128 v[236:239], v147 offset:40960
	ds_read_b128 v[240:243], v147 offset:43520
	ds_read_b128 v[244:247], v147 offset:46080
	ds_read_b128 v[248:251], v147 offset:48640
	s_waitcnt lgkmcnt(3)
	v_mfma_f32_16x16x32_bf16 v[182:185], v[220:223], v[236:239], v[182:185]
	s_waitcnt lgkmcnt(2)
	v_mfma_f32_16x16x32_bf16 v[186:189], v[220:223], v[240:243], v[186:189]
	s_waitcnt lgkmcnt(1)
	v_mfma_f32_16x16x32_bf16 v[190:193], v[220:223], v[244:247], v[190:193]
	s_waitcnt lgkmcnt(0)
	v_mfma_f32_16x16x32_bf16 v[150:153], v[220:223], v[248:251], v[150:153]
	v_mfma_f32_16x16x32_bf16 v[178:181], v[224:227], v[236:239], v[178:181]
	v_mfma_f32_16x16x32_bf16 v[194:197], v[224:227], v[240:243], v[194:197]
	v_mfma_f32_16x16x32_bf16 v[198:201], v[224:227], v[244:247], v[198:201]
	v_mfma_f32_16x16x32_bf16 v[154:157], v[224:227], v[248:251], v[154:157]
	v_mfma_f32_16x16x32_bf16 v[202:205], v[228:231], v[236:239], v[202:205]
	v_mfma_f32_16x16x32_bf16 v[212:215], v[228:231], v[240:243], v[212:215]
	v_mfma_f32_16x16x32_bf16 v[216:219], v[228:231], v[244:247], v[216:219]
	v_mfma_f32_16x16x32_bf16 v[158:161], v[228:231], v[248:251], v[158:161]
	v_mfma_f32_16x16x32_bf16 v[166:169], v[232:235], v[236:239], v[166:169]
	v_mfma_f32_16x16x32_bf16 v[170:173], v[232:235], v[240:243], v[170:173]
	v_mfma_f32_16x16x32_bf16 v[174:177], v[232:235], v[244:247], v[174:177]
	v_mfma_f32_16x16x32_bf16 v[162:165], v[232:235], v[248:251], v[162:165]
	ds_read_b128 v[220:223], v146 offset:41024
	ds_read_b128 v[224:227], v146 offset:43584
	ds_read_b128 v[228:231], v146 offset:46144
	ds_read_b128 v[232:235], v146 offset:48704
	ds_read_b128 v[236:239], v147 offset:41024
	ds_read_b128 v[240:243], v147 offset:43584
	ds_read_b128 v[244:247], v147 offset:46144
	ds_read_b128 v[248:251], v147 offset:48704
	s_waitcnt vmcnt(15)
	ds_write_b128 v145, v[0:3]
	s_waitcnt vmcnt(14)
	ds_write_b128 v145, v[4:7] offset:5120
	s_waitcnt vmcnt(13)
	ds_write_b128 v145, v[8:11] offset:10240
	s_waitcnt vmcnt(12)
	ds_write_b128 v145, v[12:15] offset:15360
	s_waitcnt vmcnt(11)
	ds_write_b128 v145, v[16:19] offset:20480
	s_waitcnt vmcnt(10)
	ds_write_b128 v145, v[20:23] offset:25600
	s_waitcnt vmcnt(9)
	ds_write_b128 v145, v[24:27] offset:30720
	s_waitcnt vmcnt(8)
	ds_write_b128 v145, v[28:31] offset:35840
	s_waitcnt lgkmcnt(0)
	s_barrier
	global_load_dwordx4 v[0:3], v[128:129], off offset:768
	global_load_dwordx4 v[4:7], v[130:131], off offset:768
	global_load_dwordx4 v[8:11], v[132:133], off offset:768
	global_load_dwordx4 v[12:15], v[134:135], off offset:768
	global_load_dwordx4 v[16:19], v[136:137], off offset:768
	global_load_dwordx4 v[20:23], v[138:139], off offset:768
	global_load_dwordx4 v[24:27], v[140:141], off offset:768
	global_load_dwordx4 v[28:31], v[142:143], off offset:768
	v_mfma_f32_16x16x32_bf16 v[182:185], v[220:223], v[236:239], v[182:185]
	v_mfma_f32_16x16x32_bf16 v[186:189], v[220:223], v[240:243], v[186:189]
	v_mfma_f32_16x16x32_bf16 v[190:193], v[220:223], v[244:247], v[190:193]
	v_mfma_f32_16x16x32_bf16 v[150:153], v[220:223], v[248:251], v[150:153]
	v_mfma_f32_16x16x32_bf16 v[178:181], v[224:227], v[236:239], v[178:181]
	v_mfma_f32_16x16x32_bf16 v[194:197], v[224:227], v[240:243], v[194:197]
	v_mfma_f32_16x16x32_bf16 v[198:201], v[224:227], v[244:247], v[198:201]
	v_mfma_f32_16x16x32_bf16 v[154:157], v[224:227], v[248:251], v[154:157]
	v_mfma_f32_16x16x32_bf16 v[202:205], v[228:231], v[236:239], v[202:205]
	v_mfma_f32_16x16x32_bf16 v[212:215], v[228:231], v[240:243], v[212:215]
	v_mfma_f32_16x16x32_bf16 v[216:219], v[228:231], v[244:247], v[216:219]
	v_mfma_f32_16x16x32_bf16 v[158:161], v[228:231], v[248:251], v[158:161]
	v_mfma_f32_16x16x32_bf16 v[166:169], v[232:235], v[236:239], v[166:169]
	v_mfma_f32_16x16x32_bf16 v[170:173], v[232:235], v[240:243], v[170:173]
	v_mfma_f32_16x16x32_bf16 v[174:177], v[232:235], v[244:247], v[174:177]
	v_mfma_f32_16x16x32_bf16 v[162:165], v[232:235], v[248:251], v[162:165]
	ds_read_b128 v[220:223], v146
	ds_read_b128 v[224:227], v146 offset:2560
	ds_read_b128 v[228:231], v146 offset:5120
	ds_read_b128 v[232:235], v146 offset:7680
	ds_read_b128 v[236:239], v147
	ds_read_b128 v[240:243], v147 offset:2560
	ds_read_b128 v[244:247], v147 offset:5120
	ds_read_b128 v[248:251], v147 offset:7680
	s_waitcnt lgkmcnt(3)
	v_mfma_f32_16x16x32_bf16 v[182:185], v[220:223], v[236:239], v[182:185]
	s_waitcnt lgkmcnt(2)
	v_mfma_f32_16x16x32_bf16 v[186:189], v[220:223], v[240:243], v[186:189]
	s_waitcnt lgkmcnt(1)
	v_mfma_f32_16x16x32_bf16 v[190:193], v[220:223], v[244:247], v[190:193]
	s_waitcnt lgkmcnt(0)
	v_mfma_f32_16x16x32_bf16 v[150:153], v[220:223], v[248:251], v[150:153]
	v_mfma_f32_16x16x32_bf16 v[178:181], v[224:227], v[236:239], v[178:181]
	v_mfma_f32_16x16x32_bf16 v[194:197], v[224:227], v[240:243], v[194:197]
	v_mfma_f32_16x16x32_bf16 v[198:201], v[224:227], v[244:247], v[198:201]
	v_mfma_f32_16x16x32_bf16 v[154:157], v[224:227], v[248:251], v[154:157]
	v_mfma_f32_16x16x32_bf16 v[202:205], v[228:231], v[236:239], v[202:205]
	v_mfma_f32_16x16x32_bf16 v[212:215], v[228:231], v[240:243], v[212:215]
	v_mfma_f32_16x16x32_bf16 v[216:219], v[228:231], v[244:247], v[216:219]
	v_mfma_f32_16x16x32_bf16 v[158:161], v[228:231], v[248:251], v[158:161]
	v_mfma_f32_16x16x32_bf16 v[166:169], v[232:235], v[236:239], v[166:169]
	v_mfma_f32_16x16x32_bf16 v[170:173], v[232:235], v[240:243], v[170:173]
	v_mfma_f32_16x16x32_bf16 v[174:177], v[232:235], v[244:247], v[174:177]
	v_mfma_f32_16x16x32_bf16 v[162:165], v[232:235], v[248:251], v[162:165]
	ds_read_b128 v[220:223], v146 offset:64
	ds_read_b128 v[224:227], v146 offset:2624
	ds_read_b128 v[228:231], v146 offset:5184
	ds_read_b128 v[232:235], v146 offset:7744
	ds_read_b128 v[236:239], v147 offset:64
	ds_read_b128 v[240:243], v147 offset:2624
	ds_read_b128 v[244:247], v147 offset:5184
	ds_read_b128 v[248:251], v147 offset:7744
	s_waitcnt vmcnt(15)
	ds_write_b128 v145, v[56:59] offset:40960
	s_waitcnt vmcnt(14)
	ds_write_b128 v145, v[60:63] offset:46080
	s_waitcnt vmcnt(13)
	ds_write_b128 v145, v[44:47] offset:51200
	s_waitcnt vmcnt(12)
	ds_write_b128 v145, v[48:51] offset:56320
	s_waitcnt vmcnt(11)
	ds_write_b128 v145, v[52:55] offset:61440
	s_waitcnt vmcnt(10)
	ds_write_b128 v148, v[32:35] offset:5120
	s_waitcnt vmcnt(9)
	ds_write_b128 v148, v[36:39] offset:10240
	s_waitcnt vmcnt(8)
	ds_write_b128 v148, v[40:43] offset:15360
	s_waitcnt lgkmcnt(0)
	s_barrier
	global_load_dwordx4 v[56:59], v[128:129], off offset:896
	global_load_dwordx4 v[60:63], v[130:131], off offset:896
	global_load_dwordx4 v[44:47], v[132:133], off offset:896
	global_load_dwordx4 v[48:51], v[134:135], off offset:896
	global_load_dwordx4 v[52:55], v[136:137], off offset:896
	global_load_dwordx4 v[32:35], v[138:139], off offset:896
	global_load_dwordx4 v[36:39], v[140:141], off offset:896
	global_load_dwordx4 v[40:43], v[142:143], off offset:896
	v_mfma_f32_16x16x32_bf16 v[182:185], v[220:223], v[236:239], v[182:185]
	v_mfma_f32_16x16x32_bf16 v[186:189], v[220:223], v[240:243], v[186:189]
	v_mfma_f32_16x16x32_bf16 v[190:193], v[220:223], v[244:247], v[190:193]
	v_mfma_f32_16x16x32_bf16 v[150:153], v[220:223], v[248:251], v[150:153]
	v_mfma_f32_16x16x32_bf16 v[178:181], v[224:227], v[236:239], v[178:181]
	v_mfma_f32_16x16x32_bf16 v[194:197], v[224:227], v[240:243], v[194:197]
	v_mfma_f32_16x16x32_bf16 v[198:201], v[224:227], v[244:247], v[198:201]
	v_mfma_f32_16x16x32_bf16 v[154:157], v[224:227], v[248:251], v[154:157]
	v_mfma_f32_16x16x32_bf16 v[202:205], v[228:231], v[236:239], v[202:205]
	v_mfma_f32_16x16x32_bf16 v[212:215], v[228:231], v[240:243], v[212:215]
	v_mfma_f32_16x16x32_bf16 v[216:219], v[228:231], v[244:247], v[216:219]
	v_mfma_f32_16x16x32_bf16 v[158:161], v[228:231], v[248:251], v[158:161]
	v_mfma_f32_16x16x32_bf16 v[166:169], v[232:235], v[236:239], v[166:169]
	v_mfma_f32_16x16x32_bf16 v[170:173], v[232:235], v[240:243], v[170:173]
	v_mfma_f32_16x16x32_bf16 v[174:177], v[232:235], v[244:247], v[174:177]
	v_mfma_f32_16x16x32_bf16 v[162:165], v[232:235], v[248:251], v[162:165]
	ds_read_b128 v[128:131], v146 offset:40960
	ds_read_b128 v[132:135], v146 offset:43520
	ds_read_b128 v[136:139], v146 offset:46080
	ds_read_b128 v[140:143], v146 offset:48640
	ds_read_b128 v[220:223], v147 offset:40960
	ds_read_b128 v[224:227], v147 offset:43520
	ds_read_b128 v[228:231], v147 offset:46080
	ds_read_b128 v[232:235], v147 offset:48640
	s_waitcnt lgkmcnt(3)
	v_mfma_f32_16x16x32_bf16 v[182:185], v[128:131], v[220:223], v[182:185]
	s_waitcnt lgkmcnt(2)
	v_mfma_f32_16x16x32_bf16 v[186:189], v[128:131], v[224:227], v[186:189]
	s_waitcnt lgkmcnt(1)
	v_mfma_f32_16x16x32_bf16 v[190:193], v[128:131], v[228:231], v[190:193]
	s_waitcnt lgkmcnt(0)
	v_mfma_f32_16x16x32_bf16 v[128:131], v[128:131], v[232:235], v[150:153]
	v_mfma_f32_16x16x32_bf16 v[150:153], v[132:135], v[220:223], v[178:181]
	v_mfma_f32_16x16x32_bf16 v[178:181], v[132:135], v[224:227], v[194:197]
	v_mfma_f32_16x16x32_bf16 v[194:197], v[132:135], v[228:231], v[198:201]
	v_mfma_f32_16x16x32_bf16 v[132:135], v[132:135], v[232:235], v[154:157]
	v_mfma_f32_16x16x32_bf16 v[154:157], v[136:139], v[220:223], v[202:205]
	v_mfma_f32_16x16x32_bf16 v[198:201], v[136:139], v[224:227], v[212:215]
	v_mfma_f32_16x16x32_bf16 v[202:205], v[136:139], v[228:231], v[216:219]
	v_mfma_f32_16x16x32_bf16 v[136:139], v[136:139], v[232:235], v[158:161]
	v_mfma_f32_16x16x32_bf16 v[158:161], v[140:143], v[220:223], v[166:169]
	v_mfma_f32_16x16x32_bf16 v[166:169], v[140:143], v[224:227], v[170:173]
	v_mfma_f32_16x16x32_bf16 v[170:173], v[140:143], v[228:231], v[174:177]
	v_mfma_f32_16x16x32_bf16 v[140:143], v[140:143], v[232:235], v[162:165]
	s_nop 2
	ds_read_b128 v[162:165], v146 offset:41024
	ds_read_b128 v[174:177], v146 offset:43584
	ds_read_b128 v[212:215], v146 offset:46144
	ds_read_b128 v[216:219], v146 offset:48704
	ds_read_b128 v[220:223], v147 offset:41024
	ds_read_b128 v[224:227], v147 offset:43584
	ds_read_b128 v[228:231], v147 offset:46144
	ds_read_b128 v[232:235], v147 offset:48704
	s_waitcnt vmcnt(15)
	ds_write_b128 v145, v[0:3]
	s_waitcnt vmcnt(14)
	ds_write_b128 v145, v[4:7] offset:5120
	s_waitcnt vmcnt(13)
	ds_write_b128 v145, v[8:11] offset:10240
	s_waitcnt vmcnt(12)
	ds_write_b128 v145, v[12:15] offset:15360
	s_waitcnt vmcnt(11)
	ds_write_b128 v145, v[16:19] offset:20480
	s_waitcnt vmcnt(10)
	ds_write_b128 v145, v[20:23] offset:25600
	s_waitcnt vmcnt(9)
	ds_write_b128 v145, v[24:27] offset:30720
	s_waitcnt vmcnt(8)
	ds_write_b128 v145, v[28:31] offset:35840
	s_waitcnt lgkmcnt(0)
	s_barrier
	ds_read_b128 v[0:3], v146
	ds_read_b128 v[4:7], v146 offset:2560
	ds_read_b128 v[8:11], v146 offset:5120
	ds_read_b128 v[12:15], v146 offset:7680
	ds_read_b128 v[16:19], v147
	ds_read_b128 v[20:23], v147 offset:2560
	ds_read_b128 v[24:27], v147 offset:5120
	ds_read_b128 v[28:31], v147 offset:7680
	v_mfma_f32_16x16x32_bf16 v[182:185], v[162:165], v[220:223], v[182:185]
	v_mfma_f32_16x16x32_bf16 v[186:189], v[162:165], v[224:227], v[186:189]
	v_mfma_f32_16x16x32_bf16 v[190:193], v[162:165], v[228:231], v[190:193]
	v_mfma_f32_16x16x32_bf16 v[128:131], v[162:165], v[232:235], v[128:131]
	v_mfma_f32_16x16x32_bf16 v[150:153], v[174:177], v[220:223], v[150:153]
	v_mfma_f32_16x16x32_bf16 v[162:165], v[174:177], v[224:227], v[178:181]
	v_mfma_f32_16x16x32_bf16 v[178:181], v[174:177], v[228:231], v[194:197]
	v_mfma_f32_16x16x32_bf16 v[132:135], v[174:177], v[232:235], v[132:135]
	v_mfma_f32_16x16x32_bf16 v[154:157], v[212:215], v[220:223], v[154:157]
	v_mfma_f32_16x16x32_bf16 v[174:177], v[212:215], v[224:227], v[198:201]
	v_mfma_f32_16x16x32_bf16 v[194:197], v[212:215], v[228:231], v[202:205]
	v_mfma_f32_16x16x32_bf16 v[136:139], v[212:215], v[232:235], v[136:139]
	v_mfma_f32_16x16x32_bf16 v[158:161], v[216:219], v[220:223], v[158:161]
	v_mfma_f32_16x16x32_bf16 v[166:169], v[216:219], v[224:227], v[166:169]
	v_mfma_f32_16x16x32_bf16 v[170:173], v[216:219], v[228:231], v[170:173]
	v_mfma_f32_16x16x32_bf16 v[140:143], v[216:219], v[232:235], v[140:143]
	s_waitcnt lgkmcnt(3)
	v_mfma_f32_16x16x32_bf16 v[182:185], v[0:3], v[16:19], v[182:185]
	s_waitcnt lgkmcnt(2)
	v_mfma_f32_16x16x32_bf16 v[186:189], v[0:3], v[20:23], v[186:189]
	s_waitcnt lgkmcnt(1)
	v_mfma_f32_16x16x32_bf16 v[190:193], v[0:3], v[24:27], v[190:193]
	s_waitcnt lgkmcnt(0)
	v_mfma_f32_16x16x32_bf16 v[0:3], v[0:3], v[28:31], v[128:131]
	v_mfma_f32_16x16x32_bf16 v[128:131], v[4:7], v[16:19], v[150:153]
	v_mfma_f32_16x16x32_bf16 v[150:153], v[4:7], v[20:23], v[162:165]
	v_mfma_f32_16x16x32_bf16 v[162:165], v[4:7], v[24:27], v[178:181]
	v_mfma_f32_16x16x32_bf16 v[4:7], v[4:7], v[28:31], v[132:135]
	v_mfma_f32_16x16x32_bf16 v[132:135], v[8:11], v[16:19], v[154:157]
	v_mfma_f32_16x16x32_bf16 v[154:157], v[8:11], v[20:23], v[174:177]
	v_mfma_f32_16x16x32_bf16 v[174:177], v[8:11], v[24:27], v[194:197]
	v_mfma_f32_16x16x32_bf16 v[8:11], v[8:11], v[28:31], v[136:139]
	v_mfma_f32_16x16x32_bf16 v[16:19], v[12:15], v[16:19], v[158:161]
	v_mfma_f32_16x16x32_bf16 v[20:23], v[12:15], v[20:23], v[166:169]
	v_mfma_f32_16x16x32_bf16 v[24:27], v[12:15], v[24:27], v[170:173]
	v_mfma_f32_16x16x32_bf16 v[12:15], v[12:15], v[28:31], v[140:143]
	ds_read_b128 v[28:31], v146 offset:64
	ds_read_b128 v[136:139], v146 offset:2624
	s_nop 0
	ds_read_b128 v[140:143], v146 offset:5184
	ds_read_b128 v[158:161], v146 offset:7744
	ds_read_b128 v[166:169], v147 offset:64
	ds_read_b128 v[170:173], v147 offset:2624
	ds_read_b128 v[178:181], v147 offset:5184
	ds_read_b128 v[194:197], v147 offset:7744
	s_waitcnt vmcnt(7)
	ds_write_b128 v145, v[56:59] offset:40960
	s_waitcnt vmcnt(6)
	ds_write_b128 v145, v[60:63] offset:46080
	s_waitcnt vmcnt(5)
	ds_write_b128 v145, v[44:47] offset:51200
	s_waitcnt vmcnt(4)
	ds_write_b128 v145, v[48:51] offset:56320
	s_waitcnt vmcnt(3)
	ds_write_b128 v145, v[52:55] offset:61440
	s_waitcnt vmcnt(2)
	ds_write_b128 v148, v[32:35] offset:5120
	s_waitcnt vmcnt(1)
	ds_write_b128 v148, v[36:39] offset:10240
	s_waitcnt vmcnt(0)
	ds_write_b128 v148, v[40:43] offset:15360
	s_waitcnt lgkmcnt(0)
	s_barrier
	ds_read_b128 v[32:35], v146 offset:40960
	ds_read_b128 v[36:39], v146 offset:43520
	ds_read_b128 v[40:43], v146 offset:46080
	ds_read_b128 v[44:47], v146 offset:48640
	ds_read_b128 v[48:51], v147 offset:40960
	ds_read_b128 v[52:55], v147 offset:43520
	ds_read_b128 v[56:59], v147 offset:46080
	ds_read_b128 v[60:63], v147 offset:48640
	v_mfma_f32_16x16x32_bf16 v[182:185], v[28:31], v[166:169], v[182:185]
	v_mfma_f32_16x16x32_bf16 v[186:189], v[28:31], v[170:173], v[186:189]
	v_mfma_f32_16x16x32_bf16 v[190:193], v[28:31], v[178:181], v[190:193]
	v_mfma_f32_16x16x32_bf16 v[0:3], v[28:31], v[194:197], v[0:3]
	v_mfma_f32_16x16x32_bf16 v[28:31], v[136:139], v[166:169], v[128:131]
	v_mfma_f32_16x16x32_bf16 v[128:131], v[136:139], v[170:173], v[150:153]
	v_mfma_f32_16x16x32_bf16 v[150:153], v[136:139], v[178:181], v[162:165]
	v_mfma_f32_16x16x32_bf16 v[4:7], v[136:139], v[194:197], v[4:7]
	v_mfma_f32_16x16x32_bf16 v[132:135], v[140:143], v[166:169], v[132:135]
	v_mfma_f32_16x16x32_bf16 v[136:139], v[140:143], v[170:173], v[154:157]
	v_mfma_f32_16x16x32_bf16 v[154:157], v[140:143], v[178:181], v[174:177]
	v_mfma_f32_16x16x32_bf16 v[8:11], v[140:143], v[194:197], v[8:11]
	v_mfma_f32_16x16x32_bf16 v[16:19], v[158:161], v[166:169], v[16:19]
	v_mfma_f32_16x16x32_bf16 v[20:23], v[158:161], v[170:173], v[20:23]
	v_mfma_f32_16x16x32_bf16 v[24:27], v[158:161], v[178:181], v[24:27]
	v_mfma_f32_16x16x32_bf16 v[12:15], v[158:161], v[194:197], v[12:15]
	s_waitcnt lgkmcnt(3)
	v_mfma_f32_16x16x32_bf16 v[140:143], v[32:35], v[48:51], v[182:185]
	s_waitcnt lgkmcnt(2)
	v_mfma_f32_16x16x32_bf16 v[158:161], v[32:35], v[52:55], v[186:189]
	s_waitcnt lgkmcnt(1)
	v_mfma_f32_16x16x32_bf16 v[162:165], v[32:35], v[56:59], v[190:193]
	s_waitcnt lgkmcnt(0)
	v_mfma_f32_16x16x32_bf16 v[0:3], v[32:35], v[60:63], v[0:3]
	v_mfma_f32_16x16x32_bf16 v[28:31], v[36:39], v[48:51], v[28:31]
	v_mfma_f32_16x16x32_bf16 v[32:35], v[36:39], v[52:55], v[128:131]
	v_mfma_f32_16x16x32_bf16 v[128:131], v[36:39], v[56:59], v[150:153]
	v_mfma_f32_16x16x32_bf16 v[4:7], v[36:39], v[60:63], v[4:7]
	v_mfma_f32_16x16x32_bf16 v[36:39], v[40:43], v[48:51], v[132:135]
	v_mfma_f32_16x16x32_bf16 v[132:135], v[40:43], v[52:55], v[136:139]
	v_mfma_f32_16x16x32_bf16 v[136:139], v[40:43], v[56:59], v[154:157]
	v_mfma_f32_16x16x32_bf16 v[8:11], v[40:43], v[60:63], v[8:11]
	v_mfma_f32_16x16x32_bf16 v[16:19], v[44:47], v[48:51], v[16:19]
	v_mfma_f32_16x16x32_bf16 v[20:23], v[44:47], v[52:55], v[20:23]
	v_mfma_f32_16x16x32_bf16 v[24:27], v[44:47], v[56:59], v[24:27]
	v_mfma_f32_16x16x32_bf16 v[12:15], v[44:47], v[60:63], v[12:15]
	ds_read_b128 v[40:43], v146 offset:41024
	ds_read_b128 v[44:47], v146 offset:43584
	ds_read_b128 v[48:51], v146 offset:46144
	ds_read_b128 v[52:55], v146 offset:48704
	ds_read_b128 v[56:59], v147 offset:41024
	ds_read_b128 v[60:63], v147 offset:43584
	ds_read_b128 v[148:151], v147 offset:46144
	ds_read_b128 v[152:155], v147 offset:48704
	s_waitcnt lgkmcnt(0)
	s_barrier
	v_mfma_f32_16x16x32_bf16 v[140:143], v[40:43], v[56:59], v[140:143]
	v_mfma_f32_16x16x32_bf16 v[156:159], v[40:43], v[60:63], v[158:161]
	v_mfma_f32_16x16x32_bf16 v[160:163], v[40:43], v[148:151], v[162:165]
	v_mfma_f32_16x16x32_bf16 v[0:3], v[40:43], v[152:155], v[0:3]
	v_mfma_f32_16x16x32_bf16 v[28:31], v[44:47], v[56:59], v[28:31]
	v_mfma_f32_16x16x32_bf16 v[32:35], v[44:47], v[60:63], v[32:35]
	v_mfma_f32_16x16x32_bf16 v[40:43], v[44:47], v[148:151], v[128:131]
	v_mfma_f32_16x16x32_bf16 v[4:7], v[44:47], v[152:155], v[4:7]
	v_mfma_f32_16x16x32_bf16 v[36:39], v[48:51], v[56:59], v[36:39]
	v_mfma_f32_16x16x32_bf16 v[44:47], v[48:51], v[60:63], v[132:135]
	v_mfma_f32_16x16x32_bf16 v[128:131], v[48:51], v[148:151], v[136:139]
	v_mfma_f32_16x16x32_bf16 v[8:11], v[48:51], v[152:155], v[8:11]
	v_mov_b32_e32 v48, v211
	s_nop 0
	v_lshrrev_b32_e32 v50, 2, v48
	v_lshrrev_b32_e32 v49, 1, v48
	v_and_b32_e32 v50, 12, v50
	v_and_or_b32 v49, v49, s43, v50
	v_and_b32_e32 v48, 0x4f, v48
	v_lshlrev_b32_e32 v48, 2, v48
	v_mul_lo_u32 v49, v49, s22
	v_add3_u32 v48, 0, v48, v49
	v_mfma_f32_16x16x32_bf16 v[16:19], v[52:55], v[56:59], v[16:19]
	v_add_u32_e32 v49, 0x400, v48
	ds_write2_b32 v48, v140, v156 offset1:16
	ds_write2_b32 v48, v141, v157 offset0:132 offset1:148
	ds_write2_b32 v49, v142, v158 offset0:8 offset1:24
	ds_write2_b32 v49, v143, v159 offset0:140 offset1:156
	ds_write2_b32 v48, v160, v0 offset0:32 offset1:48
	ds_write2_b32 v48, v161, v1 offset0:164 offset1:180
	ds_write2_b32 v49, v162, v2 offset0:40 offset1:56
	ds_write2_b32 v49, v163, v3 offset0:172 offset1:188
	v_mfma_f32_16x16x32_bf16 v[20:23], v[52:55], v[60:63], v[20:23]
	v_add_u32_e32 v0, 0x2000, v48
	v_add_u32_e32 v1, 0x2400, v48
	ds_write2_b32 v0, v28, v32 offset0:64 offset1:80
	ds_write2_b32 v0, v29, v33 offset0:196 offset1:212
	v_mfma_f32_16x16x32_bf16 v[24:27], v[52:55], v[148:151], v[24:27]
	ds_write2_b32 v1, v30, v34 offset0:72 offset1:88
	ds_write2_b32 v1, v31, v35 offset0:204 offset1:220
	ds_write2_b32 v0, v40, v4 offset0:96 offset1:112
	ds_write2_b32 v0, v41, v5 offset0:228 offset1:244
	ds_write2_b32 v1, v42, v6 offset0:104 offset1:120
	ds_write2_b32 v1, v43, v7 offset0:236 offset1:252
	v_add_u32_e32 v0, 0x4000, v48
	v_add_u32_e32 v1, 0x4400, v48
	v_mfma_f32_16x16x32_bf16 v[12:15], v[52:55], v[152:155], v[12:15]
	v_add_u32_e32 v2, 0x4800, v48
	ds_write2_b32 v0, v36, v44 offset0:128 offset1:144
	ds_write2_b32 v1, v37, v45 offset0:4 offset1:20
	ds_write2_b32 v1, v38, v46 offset0:136 offset1:152
	ds_write2_b32 v2, v39, v47 offset0:12 offset1:28
	ds_write2_b32 v0, v128, v8 offset0:160 offset1:176
	ds_write2_b32 v1, v129, v9 offset0:36 offset1:52
	ds_write2_b32 v1, v130, v10 offset0:168 offset1:184
	ds_write2_b32 v2, v131, v11 offset0:44 offset1:60
	v_add_u32_e32 v0, 0x6000, v48
	v_add_u32_e32 v1, 0x6400, v48
	v_add_u32_e32 v2, 0x6800, v48
	ds_write2_b32 v0, v16, v20 offset0:192 offset1:208
	ds_write2_b32 v1, v17, v21 offset0:68 offset1:84
	ds_write2_b32 v1, v18, v22 offset0:200 offset1:216
	ds_write2_b32 v2, v19, v23 offset0:76 offset1:92
	ds_write2_b32 v0, v24, v12 offset0:224 offset1:240
	ds_write2_b32 v1, v25, v13 offset0:100 offset1:116
	ds_write2_b32 v1, v26, v14 offset0:232 offset1:248
	ds_write2_b32 v2, v27, v15 offset0:108 offset1:124
	v_mov_b32_e32 v0, v211
	s_waitcnt lgkmcnt(0)
	s_barrier
	s_nop 0
	v_ashrrev_i32_e32 v8, 4, v0
	v_lshlrev_b32_e32 v1, 5, v0
	v_and_b32_e32 v11, 15, v0
	v_and_b32_e32 v9, 0x1e0, v1
	v_lshlrev_b32_e32 v4, 5, v11
	v_mul_lo_u32 v10, v8, s22
	global_load_dwordx4 v[0:3], v4, s[20:21] offset:16
	s_nop 0
	global_load_dwordx4 v[4:7], v4, s[20:21]
	v_add3_u32 v10, 0, v9, v10
	v_mad_i64_i32 v[8:9], s[20:21], v8, s39, 0
	s_add_u32 s20, s2, s19
	v_lshl_or_b32 v8, v11, 4, v8
	s_addc_u32 s21, s3, s16
	v_lshl_add_u64 v[8:9], s[20:21], 0, v[8:9]
	s_mov_b32 s20, 0xcc01000
	v_add_co_u32_e32 v12, vcc, s20, v8
	s_add_u32 s6, s6, 0x1000
	s_nop 0
	v_addc_co_u32_e32 v13, vcc, 0, v9, vcc
	global_load_dwordx4 v[12:15], v[12:13], off offset:2048
	s_mov_b32 s20, 0xcc31000
	v_add_co_u32_e32 v32, vcc, s20, v8
	s_nop 1
	v_addc_co_u32_e32 v33, vcc, 0, v9, vcc
	global_load_dwordx4 v[32:35], v[32:33], off offset:2048
	s_mov_b32 s20, 0xcc61000
	v_add_co_u32_e32 v36, vcc, s20, v8
	s_nop 1
	v_addc_co_u32_e32 v37, vcc, 0, v9, vcc
	global_load_dwordx4 v[36:39], v[36:37], off offset:2048
	s_mov_b32 s20, 0xcc91000
	v_add_co_u32_e32 v40, vcc, s20, v8
	s_nop 1
	v_addc_co_u32_e32 v41, vcc, 0, v9, vcc
	global_load_dwordx4 v[40:43], v[40:41], off offset:2048
	s_mov_b32 s20, 0xccc1000
	v_add_co_u32_e32 v44, vcc, s20, v8
	s_nop 1
	v_addc_co_u32_e32 v45, vcc, 0, v9, vcc
	global_load_dwordx4 v[44:47], v[44:45], off offset:2048
	s_mov_b32 s20, 0xccf1000
	v_add_co_u32_e32 v48, vcc, s20, v8
	s_nop 1
	v_addc_co_u32_e32 v49, vcc, 0, v9, vcc
	global_load_dwordx4 v[48:51], v[48:49], off offset:2048
	s_mov_b32 s20, 0xcd21000
	v_add_co_u32_e32 v52, vcc, s20, v8
	s_nop 1
	v_addc_co_u32_e32 v53, vcc, 0, v9, vcc
	global_load_dwordx4 v[52:55], v[52:53], off offset:2048
	s_mov_b32 s20, 0xcd51000
	v_add_co_u32_e32 v56, vcc, s20, v8
	s_nop 1
	v_addc_co_u32_e32 v57, vcc, 0, v9, vcc
	global_load_dwordx4 v[56:59], v[56:57], off offset:2048
	s_addc_u32 s7, s7, 0
	s_add_u32 s19, s19, 0x800
	s_addc_u32 s16, s16, 0
	s_add_u32 s15, s15, 0x400
	s_addc_u32 s13, s13, 0
	s_add_u32 s8, s8, 0x100000
	s_addc_u32 s9, s9, 0
	s_cmpk_eq_i32 s6, 0x3000
	s_waitcnt vmcnt(7)
	v_lshlrev_b32_e32 v11, 16, v12
	v_add_f32_e32 v11, v4, v11
	v_and_b32_e32 v12, 0xffff0000, v12
	v_mul_f32_e32 v11, 0xbfb8aa3b, v11
	v_exp_f32_e32 v20, v11
	v_add_f32_e32 v11, v5, v12
	v_mul_f32_e32 v11, 0xbfb8aa3b, v11
	v_exp_f32_e32 v21, v11
	v_lshlrev_b32_e32 v22, 16, v13
	v_and_b32_e32 v23, 0xffff0000, v13
	v_lshlrev_b32_e32 v24, 16, v14
	v_and_b32_e32 v25, 0xffff0000, v14
	v_lshlrev_b32_e32 v26, 16, v15
	v_and_b32_e32 v27, 0xffff0000, v15
	ds_read_b128 v[12:15], v10
	ds_read_b128 v[16:19], v10 offset:16
	v_pk_add_f32 v[20:21], v[20:21], 1.0 op_sel_hi:[1,0]
	s_waitcnt lgkmcnt(1)
	v_div_scale_f32 v11, s[20:21], v21, v21, v13
	v_rcp_f32_e32 v28, v11
	s_nop 0
	v_fma_f32 v29, -v11, v28, 1.0
	v_fmac_f32_e32 v28, v29, v28
	v_div_scale_f32 v29, vcc, v13, v21, v13
	v_mul_f32_e32 v30, v29, v28
	v_fma_f32 v31, -v11, v30, v29
	v_fmac_f32_e32 v30, v31, v28
	v_fma_f32 v11, -v11, v30, v29
	v_div_fmas_f32 v11, v11, v28, v30
	v_div_fixup_f32 v13, v11, v21, v13
	v_div_scale_f32 v11, s[20:21], v20, v20, v12
	v_rcp_f32_e32 v21, v11
	s_nop 0
	v_fma_f32 v28, -v11, v21, 1.0
	v_fmac_f32_e32 v21, v28, v21
	v_div_scale_f32 v28, vcc, v12, v20, v12
	v_mul_f32_e32 v29, v28, v21
	v_fma_f32 v30, -v11, v29, v28
	v_fmac_f32_e32 v29, v30, v21
	v_fma_f32 v11, -v11, v29, v28
	v_div_fmas_f32 v11, v11, v21, v29
	v_div_fixup_f32 v12, v11, v20, v12
	v_add_f32_e32 v11, v6, v22
	v_mul_f32_e32 v11, 0xbfb8aa3b, v11
	v_pk_add_f32 v[126:127], v[126:127], v[12:13]
	v_exp_f32_e32 v12, v11
	v_add_f32_e32 v11, v7, v23
	v_mul_f32_e32 v11, 0xbfb8aa3b, v11
	v_exp_f32_e32 v13, v11
	s_nop 0
	v_pk_add_f32 v[12:13], v[12:13], 1.0 op_sel_hi:[1,0]
	s_nop 0
	v_div_scale_f32 v11, s[20:21], v13, v13, v15
	v_rcp_f32_e32 v20, v11
	s_nop 0
	v_fma_f32 v21, -v11, v20, 1.0
	v_fmac_f32_e32 v20, v21, v20
	v_div_scale_f32 v21, vcc, v15, v13, v15
	v_mul_f32_e32 v22, v21, v20
	v_fma_f32 v23, -v11, v22, v21
	v_fmac_f32_e32 v22, v23, v20
	v_fma_f32 v11, -v11, v22, v21
	v_div_fmas_f32 v11, v11, v20, v22
	v_div_fixup_f32 v13, v11, v13, v15
	v_div_scale_f32 v11, s[20:21], v12, v12, v14
	v_rcp_f32_e32 v15, v11
	s_nop 0
	v_fma_f32 v20, -v11, v15, 1.0
	v_fmac_f32_e32 v15, v20, v15
	v_div_scale_f32 v20, vcc, v14, v12, v14
	v_mul_f32_e32 v21, v20, v15
	v_fma_f32 v22, -v11, v21, v20
	v_fmac_f32_e32 v21, v22, v15
	v_fma_f32 v11, -v11, v21, v20
	v_div_fmas_f32 v11, v11, v15, v21
	v_div_fixup_f32 v12, v11, v12, v14
	v_add_f32_e32 v11, v0, v24
	v_mul_f32_e32 v11, 0xbfb8aa3b, v11
	v_pk_add_f32 v[124:125], v[124:125], v[12:13]
	v_exp_f32_e32 v12, v11
	v_add_f32_e32 v11, v1, v25
	v_mul_f32_e32 v11, 0xbfb8aa3b, v11
	v_exp_f32_e32 v13, v11
	s_nop 0
	v_pk_add_f32 v[12:13], v[12:13], 1.0 op_sel_hi:[1,0]
	s_waitcnt lgkmcnt(0)
	v_div_scale_f32 v11, s[20:21], v13, v13, v17
	v_rcp_f32_e32 v14, v11
	s_nop 0
	v_fma_f32 v15, -v11, v14, 1.0
	v_fmac_f32_e32 v14, v15, v14
	v_div_scale_f32 v15, vcc, v17, v13, v17
	v_mul_f32_e32 v20, v15, v14
	v_fma_f32 v21, -v11, v20, v15
	v_fmac_f32_e32 v20, v21, v14
	v_fma_f32 v11, -v11, v20, v15
	v_div_fmas_f32 v11, v11, v14, v20
	v_div_fixup_f32 v13, v11, v13, v17
	v_div_scale_f32 v11, s[20:21], v12, v12, v16
	v_rcp_f32_e32 v14, v11
	s_nop 0
	v_fma_f32 v15, -v11, v14, 1.0
	v_fmac_f32_e32 v14, v15, v14
	v_div_scale_f32 v15, vcc, v16, v12, v16
	v_mul_f32_e32 v17, v15, v14
	v_fma_f32 v20, -v11, v17, v15
	v_fmac_f32_e32 v17, v20, v14
	v_fma_f32 v11, -v11, v17, v15
	v_div_fmas_f32 v11, v11, v14, v17
	v_div_fixup_f32 v12, v11, v12, v16
	v_add_f32_e32 v11, v2, v26
	v_mul_f32_e32 v11, 0xbfb8aa3b, v11
	v_pk_add_f32 v[120:121], v[120:121], v[12:13]
	v_exp_f32_e32 v12, v11
	v_add_f32_e32 v11, v3, v27
	v_mul_f32_e32 v11, 0xbfb8aa3b, v11
	v_exp_f32_e32 v13, v11
	s_nop 0
	v_pk_add_f32 v[12:13], v[12:13], 1.0 op_sel_hi:[1,0]
	s_nop 0
	v_div_scale_f32 v11, s[20:21], v13, v13, v19
	v_rcp_f32_e32 v14, v11
	s_nop 0
	v_fma_f32 v15, -v11, v14, 1.0
	v_fmac_f32_e32 v14, v15, v14
	v_div_scale_f32 v15, vcc, v19, v13, v19
	v_mul_f32_e32 v16, v15, v14
	v_fma_f32 v17, -v11, v16, v15
	v_fmac_f32_e32 v16, v17, v14
	v_fma_f32 v11, -v11, v16, v15
	v_div_fmas_f32 v11, v11, v14, v16
	v_div_fixup_f32 v13, v11, v13, v19
	v_div_scale_f32 v11, s[20:21], v12, v12, v18
	v_rcp_f32_e32 v14, v11
	s_mov_b32 s20, 0xcc31000
	v_fma_f32 v15, -v11, v14, 1.0
	v_fmac_f32_e32 v14, v15, v14
	v_div_scale_f32 v15, vcc, v18, v12, v18
	v_mul_f32_e32 v16, v15, v14
	v_fma_f32 v17, -v11, v16, v15
	v_fmac_f32_e32 v16, v17, v14
	v_fma_f32 v11, -v11, v16, v15
	v_div_fmas_f32 v11, v11, v14, v16
	v_div_fixup_f32 v12, v11, v12, v18
	v_pk_add_f32 v[104:105], v[104:105], v[12:13]
	s_waitcnt vmcnt(6)
	v_mov_b32_e32 v12, v32
	v_mov_b32_e32 v13, v33
	v_mov_b32_e32 v14, v34
	v_mov_b32_e32 v15, v35
	v_lshlrev_b32_e32 v11, 16, v12
	v_add_f32_e32 v11, v4, v11
	v_and_b32_e32 v12, 0xffff0000, v12
	v_mul_f32_e32 v11, 0xbfb8aa3b, v11
	v_exp_f32_e32 v16, v11
	v_add_f32_e32 v11, v5, v12
	v_mul_f32_e32 v11, 0xbfb8aa3b, v11
	v_lshlrev_b32_e32 v18, 16, v13
	v_and_b32_e32 v19, 0xffff0000, v13
	v_lshlrev_b32_e32 v20, 16, v14
	v_and_b32_e32 v21, 0xffff0000, v14
	v_lshlrev_b32_e32 v22, 16, v15
	v_and_b32_e32 v23, 0xffff0000, v15
	v_exp_f32_e32 v17, v11
	ds_read_b128 v[12:15], v10 offset:8448
	v_pk_add_f32 v[16:17], v[16:17], 1.0 op_sel_hi:[1,0]
	s_waitcnt lgkmcnt(0)
	v_div_scale_f32 v11, s[20:21], v17, v17, v13
	v_rcp_f32_e32 v24, v11
	s_nop 0
	v_fma_f32 v25, -v11, v24, 1.0
	v_fmac_f32_e32 v24, v25, v24
	v_div_scale_f32 v25, vcc, v13, v17, v13
	v_mul_f32_e32 v26, v25, v24
	v_fma_f32 v27, -v11, v26, v25
	v_fmac_f32_e32 v26, v27, v24
	v_fma_f32 v11, -v11, v26, v25
	v_div_fmas_f32 v11, v11, v24, v26
	v_div_fixup_f32 v13, v11, v17, v13
	v_div_scale_f32 v11, s[20:21], v16, v16, v12
	v_rcp_f32_e32 v17, v11
	s_nop 0
	v_fma_f32 v24, -v11, v17, 1.0
	v_fmac_f32_e32 v17, v24, v17
	v_div_scale_f32 v24, vcc, v12, v16, v12
	v_mul_f32_e32 v25, v24, v17
	v_fma_f32 v26, -v11, v25, v24
	v_fmac_f32_e32 v25, v26, v17
	v_fma_f32 v11, -v11, v25, v24
	v_div_fmas_f32 v11, v11, v17, v25
	v_div_fixup_f32 v12, v11, v16, v12
	v_add_f32_e32 v11, v6, v18
	v_mul_f32_e32 v11, 0xbfb8aa3b, v11
	v_pk_add_f32 v[122:123], v[122:123], v[12:13]
	v_exp_f32_e32 v12, v11
	v_add_f32_e32 v11, v7, v19
	v_mul_f32_e32 v11, 0xbfb8aa3b, v11
	v_exp_f32_e32 v13, v11
	s_nop 0
	v_pk_add_f32 v[12:13], v[12:13], 1.0 op_sel_hi:[1,0]
	s_nop 0
	v_div_scale_f32 v11, s[20:21], v13, v13, v15
	v_rcp_f32_e32 v16, v11
	s_nop 0
	v_fma_f32 v17, -v11, v16, 1.0
	v_fmac_f32_e32 v16, v17, v16
	v_div_scale_f32 v17, vcc, v15, v13, v15
	v_mul_f32_e32 v18, v17, v16
	v_fma_f32 v19, -v11, v18, v17
	v_fmac_f32_e32 v18, v19, v16
	v_fma_f32 v11, -v11, v18, v17
	v_div_fmas_f32 v11, v11, v16, v18
	v_div_fixup_f32 v13, v11, v13, v15
	v_div_scale_f32 v11, s[20:21], v12, v12, v14
	v_rcp_f32_e32 v15, v11
	s_nop 0
	v_fma_f32 v16, -v11, v15, 1.0
	v_fmac_f32_e32 v15, v16, v15
	v_div_scale_f32 v16, vcc, v14, v12, v14
	v_mul_f32_e32 v17, v16, v15
	v_fma_f32 v18, -v11, v17, v16
	v_fmac_f32_e32 v17, v18, v15
	v_fma_f32 v11, -v11, v17, v16
	v_div_fmas_f32 v11, v11, v15, v17
	v_div_fixup_f32 v12, v11, v12, v14
	v_add_f32_e32 v11, v0, v20
	v_mul_f32_e32 v11, 0xbfb8aa3b, v11
	v_exp_f32_e32 v16, v11
	v_add_f32_e32 v11, v1, v21
	v_mul_f32_e32 v11, 0xbfb8aa3b, v11
	v_pk_add_f32 v[118:119], v[118:119], v[12:13]
	v_exp_f32_e32 v17, v11
	ds_read_b128 v[12:15], v10 offset:8464
	v_pk_add_f32 v[16:17], v[16:17], 1.0 op_sel_hi:[1,0]
	s_waitcnt lgkmcnt(0)
	v_div_scale_f32 v11, s[20:21], v17, v17, v13
	v_rcp_f32_e32 v18, v11
	s_nop 0
	v_fma_f32 v19, -v11, v18, 1.0
	v_fmac_f32_e32 v18, v19, v18
	v_div_scale_f32 v19, vcc, v13, v17, v13
	v_mul_f32_e32 v20, v19, v18
	v_fma_f32 v21, -v11, v20, v19
	v_fmac_f32_e32 v20, v21, v18
	v_fma_f32 v11, -v11, v20, v19
	v_div_fmas_f32 v11, v11, v18, v20
	v_div_fixup_f32 v13, v11, v17, v13
	v_div_scale_f32 v11, s[20:21], v16, v16, v12
	v_rcp_f32_e32 v17, v11
	s_nop 0
	v_fma_f32 v18, -v11, v17, 1.0
	v_fmac_f32_e32 v17, v18, v17
	v_div_scale_f32 v18, vcc, v12, v16, v12
	v_mul_f32_e32 v19, v18, v17
	v_fma_f32 v20, -v11, v19, v18
	v_fmac_f32_e32 v19, v20, v17
	v_fma_f32 v11, -v11, v19, v18
	v_div_fmas_f32 v11, v11, v17, v19
	v_div_fixup_f32 v12, v11, v16, v12
	v_add_f32_e32 v11, v2, v22
	v_mul_f32_e32 v11, 0xbfb8aa3b, v11
	v_pk_add_f32 v[114:115], v[114:115], v[12:13]
	v_exp_f32_e32 v12, v11
	v_add_f32_e32 v11, v3, v23
	v_mul_f32_e32 v11, 0xbfb8aa3b, v11
	v_exp_f32_e32 v13, v11
	s_nop 0
	v_pk_add_f32 v[12:13], v[12:13], 1.0 op_sel_hi:[1,0]
	s_nop 0
	v_div_scale_f32 v11, s[20:21], v13, v13, v15
	v_rcp_f32_e32 v16, v11
	s_nop 0
	v_fma_f32 v17, -v11, v16, 1.0
	v_fmac_f32_e32 v16, v17, v16
	v_div_scale_f32 v17, vcc, v15, v13, v15
	v_mul_f32_e32 v18, v17, v16
	v_fma_f32 v19, -v11, v18, v17
	v_fmac_f32_e32 v18, v19, v16
	v_fma_f32 v11, -v11, v18, v17
	v_div_fmas_f32 v11, v11, v16, v18
	v_div_fixup_f32 v13, v11, v13, v15
	v_div_scale_f32 v11, s[20:21], v12, v12, v14
	v_rcp_f32_e32 v15, v11
	s_mov_b32 s20, 0xcc61000
	v_fma_f32 v16, -v11, v15, 1.0
	v_fmac_f32_e32 v15, v16, v15
	v_div_scale_f32 v16, vcc, v14, v12, v14
	v_mul_f32_e32 v17, v16, v15
	v_fma_f32 v18, -v11, v17, v16
	v_fmac_f32_e32 v17, v18, v15
	v_fma_f32 v11, -v11, v17, v16
	v_div_fmas_f32 v11, v11, v15, v17
	v_div_fixup_f32 v12, v11, v12, v14
	v_pk_add_f32 v[110:111], v[110:111], v[12:13]
	s_waitcnt vmcnt(5)
	v_mov_b32_e32 v12, v36
	v_mov_b32_e32 v13, v37
	v_mov_b32_e32 v14, v38
	v_mov_b32_e32 v15, v39
	v_lshlrev_b32_e32 v11, 16, v12
	v_add_f32_e32 v11, v4, v11
	v_and_b32_e32 v12, 0xffff0000, v12
	v_mul_f32_e32 v11, 0xbfb8aa3b, v11
	v_exp_f32_e32 v16, v11
	v_add_f32_e32 v11, v5, v12
	v_mul_f32_e32 v11, 0xbfb8aa3b, v11
	v_lshlrev_b32_e32 v18, 16, v13
	v_and_b32_e32 v19, 0xffff0000, v13
	v_lshlrev_b32_e32 v20, 16, v14
	v_and_b32_e32 v21, 0xffff0000, v14
	v_lshlrev_b32_e32 v22, 16, v15
	v_and_b32_e32 v23, 0xffff0000, v15
	v_exp_f32_e32 v17, v11
	ds_read_b128 v[12:15], v10 offset:16896
	v_pk_add_f32 v[16:17], v[16:17], 1.0 op_sel_hi:[1,0]
	s_waitcnt lgkmcnt(0)
	v_div_scale_f32 v11, s[20:21], v17, v17, v13
	v_rcp_f32_e32 v24, v11
	s_nop 0
	v_fma_f32 v25, -v11, v24, 1.0
	v_fmac_f32_e32 v24, v25, v24
	v_div_scale_f32 v25, vcc, v13, v17, v13
	v_mul_f32_e32 v26, v25, v24
	v_fma_f32 v27, -v11, v26, v25
	v_fmac_f32_e32 v26, v27, v24
	v_fma_f32 v11, -v11, v26, v25
	v_div_fmas_f32 v11, v11, v24, v26
	v_div_fixup_f32 v13, v11, v17, v13
	v_div_scale_f32 v11, s[20:21], v16, v16, v12
	v_rcp_f32_e32 v17, v11
	s_nop 0
	v_fma_f32 v24, -v11, v17, 1.0
	v_fmac_f32_e32 v17, v24, v17
	v_div_scale_f32 v24, vcc, v12, v16, v12
	v_mul_f32_e32 v25, v24, v17
	v_fma_f32 v26, -v11, v25, v24
	v_fmac_f32_e32 v25, v26, v17
	v_fma_f32 v11, -v11, v25, v24
	v_div_fmas_f32 v11, v11, v17, v25
	v_div_fixup_f32 v12, v11, v16, v12
	v_add_f32_e32 v11, v6, v18
	v_mul_f32_e32 v11, 0xbfb8aa3b, v11
	v_pk_add_f32 v[116:117], v[116:117], v[12:13]
	v_exp_f32_e32 v12, v11
	v_add_f32_e32 v11, v7, v19
	v_mul_f32_e32 v11, 0xbfb8aa3b, v11
	v_exp_f32_e32 v13, v11
	s_nop 0
	v_pk_add_f32 v[12:13], v[12:13], 1.0 op_sel_hi:[1,0]
	s_nop 0
	v_div_scale_f32 v11, s[20:21], v13, v13, v15
	v_rcp_f32_e32 v16, v11
	s_nop 0
	v_fma_f32 v17, -v11, v16, 1.0
	v_fmac_f32_e32 v16, v17, v16
	v_div_scale_f32 v17, vcc, v15, v13, v15
	v_mul_f32_e32 v18, v17, v16
	v_fma_f32 v19, -v11, v18, v17
	v_fmac_f32_e32 v18, v19, v16
	v_fma_f32 v11, -v11, v18, v17
	v_div_fmas_f32 v11, v11, v16, v18
	v_div_fixup_f32 v13, v11, v13, v15
	v_div_scale_f32 v11, s[20:21], v12, v12, v14
	v_rcp_f32_e32 v15, v11
	s_nop 0
	v_fma_f32 v16, -v11, v15, 1.0
	v_fmac_f32_e32 v15, v16, v15
	v_div_scale_f32 v16, vcc, v14, v12, v14
	v_mul_f32_e32 v17, v16, v15
	v_fma_f32 v18, -v11, v17, v16
	v_fmac_f32_e32 v17, v18, v15
	v_fma_f32 v11, -v11, v17, v16
	v_div_fmas_f32 v11, v11, v15, v17
	v_div_fixup_f32 v12, v11, v12, v14
	v_add_f32_e32 v11, v0, v20
	v_mul_f32_e32 v11, 0xbfb8aa3b, v11
	v_exp_f32_e32 v16, v11
	v_add_f32_e32 v11, v1, v21
	v_mul_f32_e32 v11, 0xbfb8aa3b, v11
	v_pk_add_f32 v[112:113], v[112:113], v[12:13]
	v_exp_f32_e32 v17, v11
	ds_read_b128 v[12:15], v10 offset:16912
	v_pk_add_f32 v[16:17], v[16:17], 1.0 op_sel_hi:[1,0]
	s_waitcnt lgkmcnt(0)
	v_div_scale_f32 v11, s[20:21], v17, v17, v13
	v_rcp_f32_e32 v18, v11
	s_nop 0
	v_fma_f32 v19, -v11, v18, 1.0
	v_fmac_f32_e32 v18, v19, v18
	v_div_scale_f32 v19, vcc, v13, v17, v13
	v_mul_f32_e32 v20, v19, v18
	v_fma_f32 v21, -v11, v20, v19
	v_fmac_f32_e32 v20, v21, v18
	v_fma_f32 v11, -v11, v20, v19
	v_div_fmas_f32 v11, v11, v18, v20
	v_div_fixup_f32 v13, v11, v17, v13
	v_div_scale_f32 v11, s[20:21], v16, v16, v12
	v_rcp_f32_e32 v17, v11
	s_nop 0
	v_fma_f32 v18, -v11, v17, 1.0
	v_fmac_f32_e32 v17, v18, v17
	v_div_scale_f32 v18, vcc, v12, v16, v12
	v_mul_f32_e32 v19, v18, v17
	v_fma_f32 v20, -v11, v19, v18
	v_fmac_f32_e32 v19, v20, v17
	v_fma_f32 v11, -v11, v19, v18
	v_div_fmas_f32 v11, v11, v17, v19
	v_div_fixup_f32 v12, v11, v16, v12
	v_add_f32_e32 v11, v2, v22
	v_mul_f32_e32 v11, 0xbfb8aa3b, v11
	v_pk_add_f32 v[106:107], v[106:107], v[12:13]
	v_exp_f32_e32 v12, v11
	v_add_f32_e32 v11, v3, v23
	v_mul_f32_e32 v11, 0xbfb8aa3b, v11
	v_exp_f32_e32 v13, v11
	s_nop 0
	v_pk_add_f32 v[12:13], v[12:13], 1.0 op_sel_hi:[1,0]
	s_nop 0
	v_div_scale_f32 v11, s[20:21], v13, v13, v15
	v_rcp_f32_e32 v16, v11
	s_nop 0
	v_fma_f32 v17, -v11, v16, 1.0
	v_fmac_f32_e32 v16, v17, v16
	v_div_scale_f32 v17, vcc, v15, v13, v15
	v_mul_f32_e32 v18, v17, v16
	v_fma_f32 v19, -v11, v18, v17
	v_fmac_f32_e32 v18, v19, v16
	v_fma_f32 v11, -v11, v18, v17
	v_div_fmas_f32 v11, v11, v16, v18
	v_div_fixup_f32 v13, v11, v13, v15
	v_div_scale_f32 v11, s[20:21], v12, v12, v14
	v_rcp_f32_e32 v15, v11
	s_mov_b32 s20, 0xcc91000
	v_fma_f32 v16, -v11, v15, 1.0
	v_fmac_f32_e32 v15, v16, v15
	v_div_scale_f32 v16, vcc, v14, v12, v14
	v_mul_f32_e32 v17, v16, v15
	v_fma_f32 v18, -v11, v17, v16
	v_fmac_f32_e32 v17, v18, v15
	v_fma_f32 v11, -v11, v17, v16
	v_div_fmas_f32 v11, v11, v15, v17
	v_div_fixup_f32 v12, v11, v12, v14
	v_pk_add_f32 v[100:101], v[100:101], v[12:13]
	s_waitcnt vmcnt(4)
	v_mov_b32_e32 v12, v40
	v_mov_b32_e32 v13, v41
	v_mov_b32_e32 v14, v42
	v_mov_b32_e32 v15, v43
	v_lshlrev_b32_e32 v11, 16, v12
	v_add_f32_e32 v11, v4, v11
	v_and_b32_e32 v12, 0xffff0000, v12
	v_mul_f32_e32 v11, 0xbfb8aa3b, v11
	v_exp_f32_e32 v16, v11
	v_add_f32_e32 v11, v5, v12
	v_mul_f32_e32 v11, 0xbfb8aa3b, v11
	v_lshlrev_b32_e32 v18, 16, v13
	v_and_b32_e32 v19, 0xffff0000, v13
	v_lshlrev_b32_e32 v20, 16, v14
	v_and_b32_e32 v21, 0xffff0000, v14
	v_lshlrev_b32_e32 v22, 16, v15
	v_and_b32_e32 v23, 0xffff0000, v15
	v_exp_f32_e32 v17, v11
	ds_read_b128 v[12:15], v10 offset:25344
	v_pk_add_f32 v[16:17], v[16:17], 1.0 op_sel_hi:[1,0]
	s_waitcnt lgkmcnt(0)
	v_div_scale_f32 v11, s[20:21], v17, v17, v13
	v_rcp_f32_e32 v24, v11
	s_nop 0
	v_fma_f32 v25, -v11, v24, 1.0
	v_fmac_f32_e32 v24, v25, v24
	v_div_scale_f32 v25, vcc, v13, v17, v13
	v_mul_f32_e32 v26, v25, v24
	v_fma_f32 v27, -v11, v26, v25
	v_fmac_f32_e32 v26, v27, v24
	v_fma_f32 v11, -v11, v26, v25
	v_div_fmas_f32 v11, v11, v24, v26
	v_div_fixup_f32 v13, v11, v17, v13
	v_div_scale_f32 v11, s[20:21], v16, v16, v12
	v_rcp_f32_e32 v17, v11
	s_nop 0
	v_fma_f32 v24, -v11, v17, 1.0
	v_fmac_f32_e32 v17, v24, v17
	v_div_scale_f32 v24, vcc, v12, v16, v12
	v_mul_f32_e32 v25, v24, v17
	v_fma_f32 v26, -v11, v25, v24
	v_fmac_f32_e32 v25, v26, v17
	v_fma_f32 v11, -v11, v25, v24
	v_div_fmas_f32 v11, v11, v17, v25
	v_div_fixup_f32 v12, v11, v16, v12
	v_add_f32_e32 v11, v6, v18
	v_mul_f32_e32 v11, 0xbfb8aa3b, v11
	v_pk_add_f32 v[108:109], v[108:109], v[12:13]
	v_exp_f32_e32 v12, v11
	v_add_f32_e32 v11, v7, v19
	v_mul_f32_e32 v11, 0xbfb8aa3b, v11
	v_exp_f32_e32 v13, v11
	s_nop 0
	v_pk_add_f32 v[12:13], v[12:13], 1.0 op_sel_hi:[1,0]
	s_nop 0
	v_div_scale_f32 v11, s[20:21], v13, v13, v15
	v_rcp_f32_e32 v16, v11
	s_nop 0
	v_fma_f32 v17, -v11, v16, 1.0
	v_fmac_f32_e32 v16, v17, v16
	v_div_scale_f32 v17, vcc, v15, v13, v15
	v_mul_f32_e32 v18, v17, v16
	v_fma_f32 v19, -v11, v18, v17
	v_fmac_f32_e32 v18, v19, v16
	v_fma_f32 v11, -v11, v18, v17
	v_div_fmas_f32 v11, v11, v16, v18
	v_div_fixup_f32 v13, v11, v13, v15
	v_div_scale_f32 v11, s[20:21], v12, v12, v14
	v_rcp_f32_e32 v15, v11
	s_nop 0
	v_fma_f32 v16, -v11, v15, 1.0
	v_fmac_f32_e32 v15, v16, v15
	v_div_scale_f32 v16, vcc, v14, v12, v14
	v_mul_f32_e32 v17, v16, v15
	v_fma_f32 v18, -v11, v17, v16
	v_fmac_f32_e32 v17, v18, v15
	v_fma_f32 v11, -v11, v17, v16
	v_div_fmas_f32 v11, v11, v15, v17
	v_div_fixup_f32 v12, v11, v12, v14
	v_add_f32_e32 v11, v0, v20
	v_mul_f32_e32 v11, 0xbfb8aa3b, v11
	v_exp_f32_e32 v16, v11
	v_add_f32_e32 v11, v1, v21
	v_mul_f32_e32 v11, 0xbfb8aa3b, v11
	v_pk_add_f32 v[102:103], v[102:103], v[12:13]
	v_exp_f32_e32 v17, v11
	ds_read_b128 v[12:15], v10 offset:25360
	v_pk_add_f32 v[16:17], v[16:17], 1.0 op_sel_hi:[1,0]
	s_waitcnt lgkmcnt(0)
	v_div_scale_f32 v11, s[20:21], v17, v17, v13
	v_rcp_f32_e32 v18, v11
	s_nop 0
	v_fma_f32 v19, -v11, v18, 1.0
	v_fmac_f32_e32 v18, v19, v18
	v_div_scale_f32 v19, vcc, v13, v17, v13
	v_mul_f32_e32 v20, v19, v18
	v_fma_f32 v21, -v11, v20, v19
	v_fmac_f32_e32 v20, v21, v18
	v_fma_f32 v11, -v11, v20, v19
	v_div_fmas_f32 v11, v11, v18, v20
	v_div_fixup_f32 v13, v11, v17, v13
	v_div_scale_f32 v11, s[20:21], v16, v16, v12
	v_rcp_f32_e32 v17, v11
	s_nop 0
	v_fma_f32 v18, -v11, v17, 1.0
	v_fmac_f32_e32 v17, v18, v17
	v_div_scale_f32 v18, vcc, v12, v16, v12
	v_mul_f32_e32 v19, v18, v17
	v_fma_f32 v20, -v11, v19, v18
	v_fmac_f32_e32 v19, v20, v17
	v_fma_f32 v11, -v11, v19, v18
	v_div_fmas_f32 v11, v11, v17, v19
	v_div_fixup_f32 v12, v11, v16, v12
	v_add_f32_e32 v11, v2, v22
	v_mul_f32_e32 v11, 0xbfb8aa3b, v11
	v_pk_add_f32 v[96:97], v[96:97], v[12:13]
	v_exp_f32_e32 v12, v11
	v_add_f32_e32 v11, v3, v23
	v_mul_f32_e32 v11, 0xbfb8aa3b, v11
	v_exp_f32_e32 v13, v11
	s_nop 0
	v_pk_add_f32 v[12:13], v[12:13], 1.0 op_sel_hi:[1,0]
	s_nop 0
	v_div_scale_f32 v11, s[20:21], v13, v13, v15
	v_rcp_f32_e32 v16, v11
	s_nop 0
	v_fma_f32 v17, -v11, v16, 1.0
	v_fmac_f32_e32 v16, v17, v16
	v_div_scale_f32 v17, vcc, v15, v13, v15
	v_mul_f32_e32 v18, v17, v16
	v_fma_f32 v19, -v11, v18, v17
	v_fmac_f32_e32 v18, v19, v16
	v_fma_f32 v11, -v11, v18, v17
	v_div_fmas_f32 v11, v11, v16, v18
	v_div_fixup_f32 v13, v11, v13, v15
	v_div_scale_f32 v11, s[20:21], v12, v12, v14
	v_rcp_f32_e32 v15, v11
	s_mov_b32 s20, 0xccc1000
	v_fma_f32 v16, -v11, v15, 1.0
	v_fmac_f32_e32 v15, v16, v15
	v_div_scale_f32 v16, vcc, v14, v12, v14
	v_mul_f32_e32 v17, v16, v15
	v_fma_f32 v18, -v11, v17, v16
	v_fmac_f32_e32 v17, v18, v15
	v_fma_f32 v11, -v11, v17, v16
	v_div_fmas_f32 v11, v11, v15, v17
	v_div_fixup_f32 v12, v11, v12, v14
	v_pk_add_f32 v[92:93], v[92:93], v[12:13]
	s_waitcnt vmcnt(3)
	v_mov_b32_e32 v12, v44
	v_mov_b32_e32 v13, v45
	v_mov_b32_e32 v14, v46
	v_mov_b32_e32 v15, v47
	v_lshlrev_b32_e32 v11, 16, v12
	v_add_f32_e32 v11, v4, v11
	v_and_b32_e32 v12, 0xffff0000, v12
	v_mul_f32_e32 v11, 0xbfb8aa3b, v11
	v_exp_f32_e32 v16, v11
	v_add_f32_e32 v11, v5, v12
	v_mul_f32_e32 v11, 0xbfb8aa3b, v11
	v_lshlrev_b32_e32 v18, 16, v13
	v_and_b32_e32 v19, 0xffff0000, v13
	v_lshlrev_b32_e32 v20, 16, v14
	v_and_b32_e32 v21, 0xffff0000, v14
	v_lshlrev_b32_e32 v22, 16, v15
	v_and_b32_e32 v23, 0xffff0000, v15
	v_exp_f32_e32 v17, v11
	ds_read_b128 v[12:15], v10 offset:33792
	v_pk_add_f32 v[16:17], v[16:17], 1.0 op_sel_hi:[1,0]
	s_waitcnt lgkmcnt(0)
	v_div_scale_f32 v11, s[20:21], v17, v17, v13
	v_rcp_f32_e32 v24, v11
	s_nop 0
	v_fma_f32 v25, -v11, v24, 1.0
	v_fmac_f32_e32 v24, v25, v24
	v_div_scale_f32 v25, vcc, v13, v17, v13
	v_mul_f32_e32 v26, v25, v24
	v_fma_f32 v27, -v11, v26, v25
	v_fmac_f32_e32 v26, v27, v24
	v_fma_f32 v11, -v11, v26, v25
	v_div_fmas_f32 v11, v11, v24, v26
	v_div_fixup_f32 v13, v11, v17, v13
	v_div_scale_f32 v11, s[20:21], v16, v16, v12
	v_rcp_f32_e32 v17, v11
	s_nop 0
	v_fma_f32 v24, -v11, v17, 1.0
	v_fmac_f32_e32 v17, v24, v17
	v_div_scale_f32 v24, vcc, v12, v16, v12
	v_mul_f32_e32 v25, v24, v17
	v_fma_f32 v26, -v11, v25, v24
	v_fmac_f32_e32 v25, v26, v17
	v_fma_f32 v11, -v11, v25, v24
	v_div_fmas_f32 v11, v11, v17, v25
	v_div_fixup_f32 v12, v11, v16, v12
	v_add_f32_e32 v11, v6, v18
	v_mul_f32_e32 v11, 0xbfb8aa3b, v11
	v_pk_add_f32 v[98:99], v[98:99], v[12:13]
	v_exp_f32_e32 v12, v11
	v_add_f32_e32 v11, v7, v19
	v_mul_f32_e32 v11, 0xbfb8aa3b, v11
	v_exp_f32_e32 v13, v11
	s_nop 0
	v_pk_add_f32 v[12:13], v[12:13], 1.0 op_sel_hi:[1,0]
	s_nop 0
	v_div_scale_f32 v11, s[20:21], v13, v13, v15
	v_rcp_f32_e32 v16, v11
	s_nop 0
	v_fma_f32 v17, -v11, v16, 1.0
	v_fmac_f32_e32 v16, v17, v16
	v_div_scale_f32 v17, vcc, v15, v13, v15
	v_mul_f32_e32 v18, v17, v16
	v_fma_f32 v19, -v11, v18, v17
	v_fmac_f32_e32 v18, v19, v16
	v_fma_f32 v11, -v11, v18, v17
	v_div_fmas_f32 v11, v11, v16, v18
	v_div_fixup_f32 v13, v11, v13, v15
	v_div_scale_f32 v11, s[20:21], v12, v12, v14
	v_rcp_f32_e32 v15, v11
	s_nop 0
	v_fma_f32 v16, -v11, v15, 1.0
	v_fmac_f32_e32 v15, v16, v15
	v_div_scale_f32 v16, vcc, v14, v12, v14
	v_mul_f32_e32 v17, v16, v15
	v_fma_f32 v18, -v11, v17, v16
	v_fmac_f32_e32 v17, v18, v15
	v_fma_f32 v11, -v11, v17, v16
	v_div_fmas_f32 v11, v11, v15, v17
	v_div_fixup_f32 v12, v11, v12, v14
	v_add_f32_e32 v11, v0, v20
	v_mul_f32_e32 v11, 0xbfb8aa3b, v11
	v_exp_f32_e32 v16, v11
	v_add_f32_e32 v11, v1, v21
	v_mul_f32_e32 v11, 0xbfb8aa3b, v11
	v_pk_add_f32 v[94:95], v[94:95], v[12:13]
	v_exp_f32_e32 v17, v11
	ds_read_b128 v[12:15], v10 offset:33808
	v_pk_add_f32 v[16:17], v[16:17], 1.0 op_sel_hi:[1,0]
	s_waitcnt lgkmcnt(0)
	v_div_scale_f32 v11, s[20:21], v17, v17, v13
	v_rcp_f32_e32 v18, v11
	s_nop 0
	v_fma_f32 v19, -v11, v18, 1.0
	v_fmac_f32_e32 v18, v19, v18
	v_div_scale_f32 v19, vcc, v13, v17, v13
	v_mul_f32_e32 v20, v19, v18
	v_fma_f32 v21, -v11, v20, v19
	v_fmac_f32_e32 v20, v21, v18
	v_fma_f32 v11, -v11, v20, v19
	v_div_fmas_f32 v11, v11, v18, v20
	v_div_fixup_f32 v13, v11, v17, v13
	v_div_scale_f32 v11, s[20:21], v16, v16, v12
	v_rcp_f32_e32 v17, v11
	s_nop 0
	v_fma_f32 v18, -v11, v17, 1.0
	v_fmac_f32_e32 v17, v18, v17
	v_div_scale_f32 v18, vcc, v12, v16, v12
	v_mul_f32_e32 v19, v18, v17
	v_fma_f32 v20, -v11, v19, v18
	v_fmac_f32_e32 v19, v20, v17
	v_fma_f32 v11, -v11, v19, v18
	v_div_fmas_f32 v11, v11, v17, v19
	v_div_fixup_f32 v12, v11, v16, v12
	v_add_f32_e32 v11, v2, v22
	v_mul_f32_e32 v11, 0xbfb8aa3b, v11
	v_pk_add_f32 v[88:89], v[88:89], v[12:13]
	v_exp_f32_e32 v12, v11
	v_add_f32_e32 v11, v3, v23
	v_mul_f32_e32 v11, 0xbfb8aa3b, v11
	v_exp_f32_e32 v13, v11
	s_nop 0
	v_pk_add_f32 v[12:13], v[12:13], 1.0 op_sel_hi:[1,0]
	s_nop 0
	v_div_scale_f32 v11, s[20:21], v13, v13, v15
	v_rcp_f32_e32 v16, v11
	s_nop 0
	v_fma_f32 v17, -v11, v16, 1.0
	v_fmac_f32_e32 v16, v17, v16
	v_div_scale_f32 v17, vcc, v15, v13, v15
	v_mul_f32_e32 v18, v17, v16
	v_fma_f32 v19, -v11, v18, v17
	v_fmac_f32_e32 v18, v19, v16
	v_fma_f32 v11, -v11, v18, v17
	v_div_fmas_f32 v11, v11, v16, v18
	v_div_fixup_f32 v13, v11, v13, v15
	v_div_scale_f32 v11, s[20:21], v12, v12, v14
	v_rcp_f32_e32 v15, v11
	s_mov_b32 s20, 0xccf1000
	v_fma_f32 v16, -v11, v15, 1.0
	v_fmac_f32_e32 v15, v16, v15
	v_div_scale_f32 v16, vcc, v14, v12, v14
	v_mul_f32_e32 v17, v16, v15
	v_fma_f32 v18, -v11, v17, v16
	v_fmac_f32_e32 v17, v18, v15
	v_fma_f32 v11, -v11, v17, v16
	v_div_fmas_f32 v11, v11, v15, v17
	v_div_fixup_f32 v12, v11, v12, v14
	v_pk_add_f32 v[84:85], v[84:85], v[12:13]
	s_waitcnt vmcnt(2)
	v_mov_b32_e32 v12, v48
	v_mov_b32_e32 v13, v49
	v_mov_b32_e32 v14, v50
	v_mov_b32_e32 v15, v51
	v_lshlrev_b32_e32 v11, 16, v12
	v_add_f32_e32 v11, v4, v11
	v_and_b32_e32 v12, 0xffff0000, v12
	v_mul_f32_e32 v11, 0xbfb8aa3b, v11
	v_exp_f32_e32 v16, v11
	v_add_f32_e32 v11, v5, v12
	v_mul_f32_e32 v11, 0xbfb8aa3b, v11
	v_lshlrev_b32_e32 v18, 16, v13
	v_and_b32_e32 v19, 0xffff0000, v13
	v_lshlrev_b32_e32 v20, 16, v14
	v_and_b32_e32 v21, 0xffff0000, v14
	v_lshlrev_b32_e32 v22, 16, v15
	v_and_b32_e32 v23, 0xffff0000, v15
	v_exp_f32_e32 v17, v11
	ds_read_b128 v[12:15], v10 offset:42240
	v_pk_add_f32 v[16:17], v[16:17], 1.0 op_sel_hi:[1,0]
	s_waitcnt lgkmcnt(0)
	v_div_scale_f32 v11, s[20:21], v17, v17, v13
	v_rcp_f32_e32 v24, v11
	s_nop 0
	v_fma_f32 v25, -v11, v24, 1.0
	v_fmac_f32_e32 v24, v25, v24
	v_div_scale_f32 v25, vcc, v13, v17, v13
	v_mul_f32_e32 v26, v25, v24
	v_fma_f32 v27, -v11, v26, v25
	v_fmac_f32_e32 v26, v27, v24
	v_fma_f32 v11, -v11, v26, v25
	v_div_fmas_f32 v11, v11, v24, v26
	v_div_fixup_f32 v13, v11, v17, v13
	v_div_scale_f32 v11, s[20:21], v16, v16, v12
	v_rcp_f32_e32 v17, v11
	s_nop 0
	v_fma_f32 v24, -v11, v17, 1.0
	v_fmac_f32_e32 v17, v24, v17
	v_div_scale_f32 v24, vcc, v12, v16, v12
	v_mul_f32_e32 v25, v24, v17
	v_fma_f32 v26, -v11, v25, v24
	v_fmac_f32_e32 v25, v26, v17
	v_fma_f32 v11, -v11, v25, v24
	v_div_fmas_f32 v11, v11, v17, v25
	v_div_fixup_f32 v12, v11, v16, v12
	v_add_f32_e32 v11, v6, v18
	v_mul_f32_e32 v11, 0xbfb8aa3b, v11
	v_pk_add_f32 v[90:91], v[90:91], v[12:13]
	v_exp_f32_e32 v12, v11
	v_add_f32_e32 v11, v7, v19
	v_mul_f32_e32 v11, 0xbfb8aa3b, v11
	v_exp_f32_e32 v13, v11
	s_nop 0
	v_pk_add_f32 v[12:13], v[12:13], 1.0 op_sel_hi:[1,0]
	s_nop 0
	v_div_scale_f32 v11, s[20:21], v13, v13, v15
	v_rcp_f32_e32 v16, v11
	s_nop 0
	v_fma_f32 v17, -v11, v16, 1.0
	v_fmac_f32_e32 v16, v17, v16
	v_div_scale_f32 v17, vcc, v15, v13, v15
	v_mul_f32_e32 v18, v17, v16
	v_fma_f32 v19, -v11, v18, v17
	v_fmac_f32_e32 v18, v19, v16
	v_fma_f32 v11, -v11, v18, v17
	v_div_fmas_f32 v11, v11, v16, v18
	v_div_fixup_f32 v13, v11, v13, v15
	v_div_scale_f32 v11, s[20:21], v12, v12, v14
	v_rcp_f32_e32 v15, v11
	s_nop 0
	v_fma_f32 v16, -v11, v15, 1.0
	v_fmac_f32_e32 v15, v16, v15
	v_div_scale_f32 v16, vcc, v14, v12, v14
	v_mul_f32_e32 v17, v16, v15
	v_fma_f32 v18, -v11, v17, v16
	v_fmac_f32_e32 v17, v18, v15
	v_fma_f32 v11, -v11, v17, v16
	v_div_fmas_f32 v11, v11, v15, v17
	v_div_fixup_f32 v12, v11, v12, v14
	v_add_f32_e32 v11, v0, v20
	v_mul_f32_e32 v11, 0xbfb8aa3b, v11
	v_exp_f32_e32 v16, v11
	v_add_f32_e32 v11, v1, v21
	v_mul_f32_e32 v11, 0xbfb8aa3b, v11
	v_pk_add_f32 v[86:87], v[86:87], v[12:13]
	v_exp_f32_e32 v17, v11
	ds_read_b128 v[12:15], v10 offset:42256
	v_pk_add_f32 v[16:17], v[16:17], 1.0 op_sel_hi:[1,0]
	s_waitcnt lgkmcnt(0)
	v_div_scale_f32 v11, s[20:21], v17, v17, v13
	v_rcp_f32_e32 v18, v11
	s_nop 0
	v_fma_f32 v19, -v11, v18, 1.0
	v_fmac_f32_e32 v18, v19, v18
	v_div_scale_f32 v19, vcc, v13, v17, v13
	v_mul_f32_e32 v20, v19, v18
	v_fma_f32 v21, -v11, v20, v19
	v_fmac_f32_e32 v20, v21, v18
	v_fma_f32 v11, -v11, v20, v19
	v_div_fmas_f32 v11, v11, v18, v20
	v_div_fixup_f32 v13, v11, v17, v13
	v_div_scale_f32 v11, s[20:21], v16, v16, v12
	v_rcp_f32_e32 v17, v11
	s_nop 0
	v_fma_f32 v18, -v11, v17, 1.0
	v_fmac_f32_e32 v17, v18, v17
	v_div_scale_f32 v18, vcc, v12, v16, v12
	v_mul_f32_e32 v19, v18, v17
	v_fma_f32 v20, -v11, v19, v18
	v_fmac_f32_e32 v19, v20, v17
	v_fma_f32 v11, -v11, v19, v18
	v_div_fmas_f32 v11, v11, v17, v19
	v_div_fixup_f32 v12, v11, v16, v12
	v_add_f32_e32 v11, v2, v22
	v_mul_f32_e32 v11, 0xbfb8aa3b, v11
	v_pk_add_f32 v[82:83], v[82:83], v[12:13]
	v_exp_f32_e32 v12, v11
	v_add_f32_e32 v11, v3, v23
	v_mul_f32_e32 v11, 0xbfb8aa3b, v11
	v_exp_f32_e32 v13, v11
	s_nop 0
	v_pk_add_f32 v[12:13], v[12:13], 1.0 op_sel_hi:[1,0]
	s_nop 0
	v_div_scale_f32 v11, s[20:21], v13, v13, v15
	v_rcp_f32_e32 v16, v11
	s_nop 0
	v_fma_f32 v17, -v11, v16, 1.0
	v_fmac_f32_e32 v16, v17, v16
	v_div_scale_f32 v17, vcc, v15, v13, v15
	v_mul_f32_e32 v18, v17, v16
	v_fma_f32 v19, -v11, v18, v17
	v_fmac_f32_e32 v18, v19, v16
	v_fma_f32 v11, -v11, v18, v17
	v_div_fmas_f32 v11, v11, v16, v18
	v_div_fixup_f32 v13, v11, v13, v15
	v_div_scale_f32 v11, s[20:21], v12, v12, v14
	v_rcp_f32_e32 v15, v11
	s_mov_b32 s20, 0xcd21000
	v_fma_f32 v16, -v11, v15, 1.0
	v_fmac_f32_e32 v15, v16, v15
	v_div_scale_f32 v16, vcc, v14, v12, v14
	v_mul_f32_e32 v17, v16, v15
	v_fma_f32 v18, -v11, v17, v16
	v_fmac_f32_e32 v17, v18, v15
	v_fma_f32 v11, -v11, v17, v16
	v_div_fmas_f32 v11, v11, v15, v17
	v_div_fixup_f32 v12, v11, v12, v14
	v_pk_add_f32 v[78:79], v[78:79], v[12:13]
	s_waitcnt vmcnt(1)
	v_mov_b32_e32 v12, v52
	v_mov_b32_e32 v13, v53
	v_mov_b32_e32 v14, v54
	v_mov_b32_e32 v15, v55
	v_lshlrev_b32_e32 v11, 16, v12
	v_add_f32_e32 v11, v4, v11
	v_and_b32_e32 v12, 0xffff0000, v12
	v_mul_f32_e32 v11, 0xbfb8aa3b, v11
	v_exp_f32_e32 v16, v11
	v_add_f32_e32 v11, v5, v12
	v_mul_f32_e32 v11, 0xbfb8aa3b, v11
	v_lshlrev_b32_e32 v18, 16, v13
	v_and_b32_e32 v19, 0xffff0000, v13
	v_lshlrev_b32_e32 v20, 16, v14
	v_and_b32_e32 v21, 0xffff0000, v14
	v_lshlrev_b32_e32 v22, 16, v15
	v_and_b32_e32 v23, 0xffff0000, v15
	v_exp_f32_e32 v17, v11
	ds_read_b128 v[12:15], v10 offset:50688
	v_pk_add_f32 v[16:17], v[16:17], 1.0 op_sel_hi:[1,0]
	s_waitcnt lgkmcnt(0)
	v_div_scale_f32 v11, s[20:21], v17, v17, v13
	v_rcp_f32_e32 v24, v11
	s_nop 0
	v_fma_f32 v25, -v11, v24, 1.0
	v_fmac_f32_e32 v24, v25, v24
	v_div_scale_f32 v25, vcc, v13, v17, v13
	v_mul_f32_e32 v26, v25, v24
	v_fma_f32 v27, -v11, v26, v25
	v_fmac_f32_e32 v26, v27, v24
	v_fma_f32 v11, -v11, v26, v25
	v_div_fmas_f32 v11, v11, v24, v26
	v_div_fixup_f32 v13, v11, v17, v13
	v_div_scale_f32 v11, s[20:21], v16, v16, v12
	v_rcp_f32_e32 v17, v11
	s_nop 0
	v_fma_f32 v24, -v11, v17, 1.0
	v_fmac_f32_e32 v17, v24, v17
	v_div_scale_f32 v24, vcc, v12, v16, v12
	v_mul_f32_e32 v25, v24, v17
	v_fma_f32 v26, -v11, v25, v24
	v_fmac_f32_e32 v25, v26, v17
	v_fma_f32 v11, -v11, v25, v24
	v_div_fmas_f32 v11, v11, v17, v25
	v_div_fixup_f32 v12, v11, v16, v12
	v_add_f32_e32 v11, v6, v18
	v_mul_f32_e32 v11, 0xbfb8aa3b, v11
	v_pk_add_f32 v[80:81], v[80:81], v[12:13]
	v_exp_f32_e32 v12, v11
	v_add_f32_e32 v11, v7, v19
	v_mul_f32_e32 v11, 0xbfb8aa3b, v11
	v_exp_f32_e32 v13, v11
	s_nop 0
	v_pk_add_f32 v[12:13], v[12:13], 1.0 op_sel_hi:[1,0]
	s_nop 0
	v_div_scale_f32 v11, s[20:21], v13, v13, v15
	v_rcp_f32_e32 v16, v11
	s_nop 0
	v_fma_f32 v17, -v11, v16, 1.0
	v_fmac_f32_e32 v16, v17, v16
	v_div_scale_f32 v17, vcc, v15, v13, v15
	v_mul_f32_e32 v18, v17, v16
	v_fma_f32 v19, -v11, v18, v17
	v_fmac_f32_e32 v18, v19, v16
	v_fma_f32 v11, -v11, v18, v17
	v_div_fmas_f32 v11, v11, v16, v18
	v_div_fixup_f32 v13, v11, v13, v15
	v_div_scale_f32 v11, s[20:21], v12, v12, v14
	v_rcp_f32_e32 v15, v11
	s_nop 0
	v_fma_f32 v16, -v11, v15, 1.0
	v_fmac_f32_e32 v15, v16, v15
	v_div_scale_f32 v16, vcc, v14, v12, v14
	v_mul_f32_e32 v17, v16, v15
	v_fma_f32 v18, -v11, v17, v16
	v_fmac_f32_e32 v17, v18, v15
	v_fma_f32 v11, -v11, v17, v16
	v_div_fmas_f32 v11, v11, v15, v17
	v_div_fixup_f32 v12, v11, v12, v14
	v_add_f32_e32 v11, v0, v20
	v_mul_f32_e32 v11, 0xbfb8aa3b, v11
	v_exp_f32_e32 v16, v11
	v_add_f32_e32 v11, v1, v21
	v_mul_f32_e32 v11, 0xbfb8aa3b, v11
	v_pk_add_f32 v[76:77], v[76:77], v[12:13]
	v_exp_f32_e32 v17, v11
	ds_read_b128 v[12:15], v10 offset:50704
	v_pk_add_f32 v[16:17], v[16:17], 1.0 op_sel_hi:[1,0]
	s_waitcnt lgkmcnt(0)
	v_div_scale_f32 v11, s[20:21], v17, v17, v13
	v_rcp_f32_e32 v18, v11
	s_nop 0
	v_fma_f32 v19, -v11, v18, 1.0
	v_fmac_f32_e32 v18, v19, v18
	v_div_scale_f32 v19, vcc, v13, v17, v13
	v_mul_f32_e32 v20, v19, v18
	v_fma_f32 v21, -v11, v20, v19
	v_fmac_f32_e32 v20, v21, v18
	v_fma_f32 v11, -v11, v20, v19
	v_div_fmas_f32 v11, v11, v18, v20
	v_div_fixup_f32 v13, v11, v17, v13
	v_div_scale_f32 v11, s[20:21], v16, v16, v12
	v_rcp_f32_e32 v17, v11
	s_nop 0
	v_fma_f32 v18, -v11, v17, 1.0
	v_fmac_f32_e32 v17, v18, v17
	v_div_scale_f32 v18, vcc, v12, v16, v12
	v_mul_f32_e32 v19, v18, v17
	v_fma_f32 v20, -v11, v19, v18
	v_fmac_f32_e32 v19, v20, v17
	v_fma_f32 v11, -v11, v19, v18
	v_div_fmas_f32 v11, v11, v17, v19
	v_div_fixup_f32 v12, v11, v16, v12
	v_add_f32_e32 v11, v2, v22
	v_mul_f32_e32 v11, 0xbfb8aa3b, v11
	v_pk_add_f32 v[74:75], v[74:75], v[12:13]
	v_exp_f32_e32 v12, v11
	v_add_f32_e32 v11, v3, v23
	v_mul_f32_e32 v11, 0xbfb8aa3b, v11
	v_exp_f32_e32 v13, v11
	s_nop 0
	v_pk_add_f32 v[12:13], v[12:13], 1.0 op_sel_hi:[1,0]
	s_nop 0
	v_div_scale_f32 v11, s[20:21], v13, v13, v15
	v_rcp_f32_e32 v16, v11
	s_nop 0
	v_fma_f32 v17, -v11, v16, 1.0
	v_fmac_f32_e32 v16, v17, v16
	v_div_scale_f32 v17, vcc, v15, v13, v15
	v_mul_f32_e32 v18, v17, v16
	v_fma_f32 v19, -v11, v18, v17
	v_fmac_f32_e32 v18, v19, v16
	v_fma_f32 v11, -v11, v18, v17
	v_div_fmas_f32 v11, v11, v16, v18
	v_div_fixup_f32 v13, v11, v13, v15
	v_div_scale_f32 v11, s[20:21], v12, v12, v14
	v_rcp_f32_e32 v15, v11
	s_mov_b32 s20, 0xcd51000
	v_fma_f32 v16, -v11, v15, 1.0
	v_fmac_f32_e32 v15, v16, v15
	v_div_scale_f32 v16, vcc, v14, v12, v14
	v_mul_f32_e32 v17, v16, v15
	v_fma_f32 v18, -v11, v17, v16
	v_fmac_f32_e32 v17, v18, v15
	v_fma_f32 v11, -v11, v17, v16
	v_div_fmas_f32 v11, v11, v15, v17
	v_add_co_u32_e32 v8, vcc, s20, v8
	v_div_fixup_f32 v12, v11, v12, v14
	s_nop 0
	v_addc_co_u32_e32 v9, vcc, 0, v9, vcc
	v_pk_add_f32 v[70:71], v[70:71], v[12:13]
	s_waitcnt vmcnt(0)
	v_mov_b32_e32 v12, v56
	v_mov_b32_e32 v13, v57
	v_mov_b32_e32 v14, v58
	v_mov_b32_e32 v15, v59
	v_lshlrev_b32_e32 v11, 16, v12
	v_and_b32_e32 v12, 0xffff0000, v12
	v_add_f32_e32 v4, v4, v11
	v_add_f32_e32 v5, v5, v12
	v_mul_f32_e32 v4, 0xbfb8aa3b, v4
	v_mul_f32_e32 v5, 0xbfb8aa3b, v5
	v_lshlrev_b32_e32 v16, 16, v13
	v_and_b32_e32 v17, 0xffff0000, v13
	v_lshlrev_b32_e32 v18, 16, v14
	v_and_b32_e32 v19, 0xffff0000, v14
	v_lshlrev_b32_e32 v9, 16, v15
	v_and_b32_e32 v8, 0xffff0000, v15
	v_exp_f32_e32 v4, v4
	v_exp_f32_e32 v5, v5
	ds_read_b128 v[12:15], v10 offset:59136
	v_add_f32_e32 v0, v0, v18
	v_add_f32_e32 v1, v1, v19
	v_pk_add_f32 v[4:5], v[4:5], 1.0 op_sel_hi:[1,0]
	v_mul_f32_e32 v0, 0xbfb8aa3b, v0
	s_waitcnt lgkmcnt(0)
	v_div_scale_f32 v11, s[20:21], v5, v5, v13
	v_rcp_f32_e32 v20, v11
	v_mul_f32_e32 v1, 0xbfb8aa3b, v1
	v_exp_f32_e32 v0, v0
	v_exp_f32_e32 v1, v1
	v_fma_f32 v21, -v11, v20, 1.0
	v_fmac_f32_e32 v20, v21, v20
	v_div_scale_f32 v21, vcc, v13, v5, v13
	v_mul_f32_e32 v22, v21, v20
	v_fma_f32 v23, -v11, v22, v21
	v_fmac_f32_e32 v22, v23, v20
	v_fma_f32 v11, -v11, v22, v21
	v_div_fmas_f32 v11, v11, v20, v22
	v_div_fixup_f32 v5, v11, v5, v13
	v_div_scale_f32 v11, s[20:21], v4, v4, v12
	v_rcp_f32_e32 v13, v11
	v_pk_add_f32 v[0:1], v[0:1], 1.0 op_sel_hi:[1,0]
	v_fma_f32 v20, -v11, v13, 1.0
	v_fmac_f32_e32 v13, v20, v13
	v_div_scale_f32 v20, vcc, v12, v4, v12
	v_mul_f32_e32 v21, v20, v13
	v_fma_f32 v22, -v11, v21, v20
	v_fmac_f32_e32 v21, v22, v13
	v_fma_f32 v11, -v11, v21, v20
	v_div_fmas_f32 v11, v11, v13, v21
	v_div_fixup_f32 v4, v11, v4, v12
	v_pk_add_f32 v[72:73], v[72:73], v[4:5]
	v_add_f32_e32 v4, v6, v16
	v_add_f32_e32 v5, v7, v17
	v_mul_f32_e32 v4, 0xbfb8aa3b, v4
	v_mul_f32_e32 v5, 0xbfb8aa3b, v5
	v_exp_f32_e32 v4, v4
	v_exp_f32_e32 v5, v5
	s_nop 0
	v_pk_add_f32 v[4:5], v[4:5], 1.0 op_sel_hi:[1,0]
	s_nop 0
	v_div_scale_f32 v6, s[20:21], v5, v5, v15
	v_rcp_f32_e32 v7, v6
	s_nop 0
	v_fma_f32 v11, -v6, v7, 1.0
	v_fmac_f32_e32 v7, v11, v7
	v_div_scale_f32 v11, vcc, v15, v5, v15
	v_mul_f32_e32 v12, v11, v7
	v_fma_f32 v13, -v6, v12, v11
	v_fmac_f32_e32 v12, v13, v7
	v_fma_f32 v6, -v6, v12, v11
	v_div_fmas_f32 v6, v6, v7, v12
	v_div_fixup_f32 v5, v6, v5, v15
	v_div_scale_f32 v6, s[20:21], v4, v4, v14
	v_rcp_f32_e32 v7, v6
	s_nop 0
	v_fma_f32 v11, -v6, v7, 1.0
	v_fmac_f32_e32 v7, v11, v7
	v_div_scale_f32 v11, vcc, v14, v4, v14
	v_mul_f32_e32 v12, v11, v7
	v_fma_f32 v13, -v6, v12, v11
	v_fmac_f32_e32 v12, v13, v7
	v_fma_f32 v6, -v6, v12, v11
	v_div_fmas_f32 v6, v6, v7, v12
	v_div_fixup_f32 v4, v6, v4, v14
	v_pk_add_f32 v[68:69], v[68:69], v[4:5]
	ds_read_b128 v[4:7], v10 offset:59152
	s_waitcnt lgkmcnt(0)
	v_div_scale_f32 v10, s[20:21], v1, v1, v5
	v_rcp_f32_e32 v11, v10
	s_nop 0
	v_fma_f32 v12, -v10, v11, 1.0
	v_fmac_f32_e32 v11, v12, v11
	v_div_scale_f32 v12, vcc, v5, v1, v5
	v_mul_f32_e32 v13, v12, v11
	v_fma_f32 v14, -v10, v13, v12
	v_fmac_f32_e32 v13, v14, v11
	v_fma_f32 v10, -v10, v13, v12
	v_div_fmas_f32 v10, v10, v11, v13
	v_div_fixup_f32 v1, v10, v1, v5
	v_div_scale_f32 v5, s[20:21], v0, v0, v4
	v_rcp_f32_e32 v10, v5
	s_nop 0
	v_fma_f32 v11, -v5, v10, 1.0
	v_fmac_f32_e32 v10, v11, v10
	v_div_scale_f32 v11, vcc, v4, v0, v4
	v_mul_f32_e32 v12, v11, v10
	v_fma_f32 v13, -v5, v12, v11
	v_fmac_f32_e32 v12, v13, v10
	v_fma_f32 v5, -v5, v12, v11
	v_div_fmas_f32 v5, v5, v10, v12
	v_div_fixup_f32 v0, v5, v0, v4
	v_pk_add_f32 v[66:67], v[66:67], v[0:1]
	v_add_f32_e32 v0, v2, v9
	v_add_f32_e32 v1, v3, v8
	v_mul_f32_e32 v0, 0xbfb8aa3b, v0
	v_mul_f32_e32 v1, 0xbfb8aa3b, v1
	v_exp_f32_e32 v0, v0
	v_exp_f32_e32 v1, v1
	s_nop 0
	v_pk_add_f32 v[0:1], v[0:1], 1.0 op_sel_hi:[1,0]
	s_nop 0
	v_div_scale_f32 v2, s[20:21], v1, v1, v7
	v_rcp_f32_e32 v3, v2
	s_nop 0
	v_fma_f32 v4, -v2, v3, 1.0
	v_fmac_f32_e32 v3, v4, v3
	v_div_scale_f32 v4, vcc, v7, v1, v7
	v_mul_f32_e32 v5, v4, v3
	v_fma_f32 v8, -v2, v5, v4
	v_fmac_f32_e32 v5, v8, v3
	v_fma_f32 v2, -v2, v5, v4
	v_div_fmas_f32 v2, v2, v3, v5
	v_div_fixup_f32 v1, v2, v1, v7
	v_div_scale_f32 v2, s[20:21], v0, v0, v6
	v_rcp_f32_e32 v3, v2
	s_nop 0
	v_fma_f32 v4, -v2, v3, 1.0
	v_fmac_f32_e32 v3, v4, v3
	v_div_scale_f32 v4, vcc, v6, v0, v6
	v_mul_f32_e32 v5, v4, v3
	v_fma_f32 v7, -v2, v5, v4
	v_fmac_f32_e32 v5, v7, v3
	v_fma_f32 v2, -v2, v5, v4
	v_div_fmas_f32 v2, v2, v3, v5
	v_div_fixup_f32 v0, v2, v0, v6
	v_pk_add_f32 v[64:65], v[64:65], v[0:1]
	s_cbranch_scc0 .LBB0_137
	s_lshl_b64 s[4:5], s[4:5], 18
	v_readlane_b32 s6, v252, 21
	v_readlane_b32 s7, v252, 22
	s_add_u32 s4, s6, s4
	v_mov_b32_e32 v0, v211
	s_addc_u32 s5, s7, s5
	s_lshl_b32 s6, s14, 1
	s_add_u32 s4, s4, s6
	v_ashrrev_i32_e32 v4, 4, v0
	v_lshlrev_b32_e32 v0, 4, v0
	s_addc_u32 s5, s5, 0
	v_and_b32_e32 v208, 0xf0, v0
	v_ashrrev_i32_e32 v5, 31, v4
	v_lshl_add_u64 v[6:7], s[4:5], 0, v[208:209]
	v_lshlrev_b64 v[4:5], 11, v[4:5]
	v_lshl_add_u64 v[4:5], v[6:7], 0, v[4:5]
	s_mov_b32 s4, 0x8000
	v_cvt_pk_bf16_f32 v0, v126, v127
	v_cvt_pk_bf16_f32 v1, v124, v125
	v_cvt_pk_bf16_f32 v2, v120, v121
	v_cvt_pk_bf16_f32 v3, v104, v105
	v_add_co_u32_e32 v6, vcc, s4, v4
	global_store_dwordx4 v[4:5], v[0:3], off
	s_nop 0
	v_addc_co_u32_e32 v7, vcc, 0, v5, vcc
	v_cvt_pk_bf16_f32 v0, v122, v123
	v_cvt_pk_bf16_f32 v1, v118, v119
	v_cvt_pk_bf16_f32 v2, v114, v115
	v_cvt_pk_bf16_f32 v3, v110, v111
	s_mov_b32 s4, 0x10000
	global_store_dwordx4 v[6:7], v[0:3], off
	v_add_co_u32_e32 v6, vcc, s4, v4
	s_nop 0
	v_cvt_pk_bf16_f32 v0, v116, v117
	v_cvt_pk_bf16_f32 v1, v112, v113
	v_cvt_pk_bf16_f32 v2, v106, v107
	v_cvt_pk_bf16_f32 v3, v100, v101
	v_addc_co_u32_e32 v7, vcc, 0, v5, vcc
	s_mov_b32 s2, 0x18000
	global_store_dwordx4 v[6:7], v[0:3], off
	v_add_co_u32_e32 v6, vcc, s2, v4
	s_nop 0
	v_cvt_pk_bf16_f32 v0, v108, v109
	v_cvt_pk_bf16_f32 v1, v102, v103
	v_cvt_pk_bf16_f32 v2, v96, v97
	v_cvt_pk_bf16_f32 v3, v92, v93
	v_addc_co_u32_e32 v7, vcc, 0, v5, vcc
	s_mov_b32 s4, 0x20000
	global_store_dwordx4 v[6:7], v[0:3], off
	v_add_co_u32_e32 v6, vcc, s4, v4
	s_nop 0
	v_cvt_pk_bf16_f32 v0, v98, v99
	v_cvt_pk_bf16_f32 v1, v94, v95
	v_cvt_pk_bf16_f32 v2, v88, v89
	v_cvt_pk_bf16_f32 v3, v84, v85
	v_addc_co_u32_e32 v7, vcc, 0, v5, vcc
	s_mov_b32 s4, 0x28000
	global_store_dwordx4 v[6:7], v[0:3], off
	v_add_co_u32_e32 v6, vcc, s4, v4
	s_nop 0
	v_cvt_pk_bf16_f32 v0, v90, v91
	v_cvt_pk_bf16_f32 v1, v86, v87
	v_cvt_pk_bf16_f32 v2, v82, v83
	v_cvt_pk_bf16_f32 v3, v78, v79
	v_addc_co_u32_e32 v7, vcc, 0, v5, vcc
	s_mov_b32 s4, 0x30000
	global_store_dwordx4 v[6:7], v[0:3], off
	v_add_co_u32_e32 v6, vcc, s4, v4
	s_nop 0
	v_cvt_pk_bf16_f32 v0, v80, v81
	v_addc_co_u32_e32 v7, vcc, 0, v5, vcc
	v_cvt_pk_bf16_f32 v1, v76, v77
	v_cvt_pk_bf16_f32 v2, v74, v75
	v_cvt_pk_bf16_f32 v3, v70, v71
	v_add_co_u32_e32 v4, vcc, 0x38000, v4
	global_store_dwordx4 v[6:7], v[0:3], off
	s_nop 0
	v_addc_co_u32_e32 v5, vcc, 0, v5, vcc
	v_cvt_pk_bf16_f32 v0, v72, v73
	v_cvt_pk_bf16_f32 v1, v68, v69
	v_cvt_pk_bf16_f32 v2, v66, v67
	v_cvt_pk_bf16_f32 v3, v64, v65
	global_store_dwordx4 v[4:5], v[0:3], off
	s_barrier
	s_and_saveexec_b64 s[4:5], s[36:37]
	s_cbranch_execz .LBB0_131
	v_readlane_b32 s6, v253, 62
	s_nop 1
	v_mov_b32_e32 v0, s6
	s_waitcnt vmcnt(0)
	v_add_u32_e32 v144, s26, v144
	ds_write_b32 v0, v144
	s_branch .LBB0_131
